# GEMM K-loops: LDS-DMA loads use the SGPR-base (saddr) form so the loading half issues no VALU address adds; LDS read-address adds hoisted out of the loop
# baseline (speedup 1.0000x reference)
; #define PG8_STAGE(bufoff, gbase, voff) do { _Pragma("unroll") for (int _i = 0; _i < 2; ++_i) \
;         __builtin_amdgcn_global_load_lds((const unsigned*)((const char*)(gbase) + (voff)[_i]), (LAS unsigned*)(lds + (bufoff) + ldsw + _i * 8192), 16, 0, 0); } while (0)
; #define PG8_LDA(dst, b, h) do { _Pragma("unroll") for (int m = 0; m < 4; ++m) _Pragma("unroll") for (int k = 0; k < 2; ++k) dst[m][k] = *(const LAS bf16x8*)(lds + PG8_SA(b, h) + aoff + m * 2048 + k * 1024); } while (0)
; #define PG8_LDB(dst, b, h) do { _Pragma("unroll") for (int n = 0; n < 2; ++n) _Pragma("unroll") for (int k = 0; k < 2; ++k) dst[n][k] = *(const LAS bf16x8*)(lds + PG8_SB(b, h) + boff + n * 2048 + k * 1024); } while (0)
; #define PG8_SCHED __builtin_amdgcn_sched_barrier(0)
; __device__ __forceinline__ void gemm_phase(LAS unsigned char* lds, const Params& p, const bf16_t* gA, const bf16_t* gBt, const int gM, const int gN, const int gK, const int epi, const int perm, bf16_t* const Hp, const int goff, const float coef) {
;     ...
;         const char* nA = has_next ? (const char*)gA + (size_t)nxt.pm * tstep + (nxt.ks > 0 ? nxt.ks * ksl : 0) : cA; const char* nB = has_next ? (const char*)gBt + (size_t)nxt.pn * tstep + (nxt.ks > 0 ? nxt.ks * ksl : 0) : cB;
;         const int nt = cur.ks >= 0 ? ntf / 4 : ntf;
;         for (int t = 0; t < nt; t += 2) {
;             const bool last = (t == nt - 2);
;             const char* a1 = cA + (size_t)(t + 1) * kstep;
;             const char* a2 = last ? nA : cA + (size_t)(t + 2) * kstep; const char* b2 = last ? nB : cB + (size_t)(t + 2) * kstep;
;             const char* a3 = a2 + kstep; const char* b3 = b2 + kstep;
;             PG8_LDB(B0, 0, 0); PG8_LDB(B1, 0, 1); PG8_SCHED; PG8_LDA(At, 0, 0); PG8_STAGE(PG8_SA(1, 1), a1 + hstep, voffA);
;     ...
; #pragma unroll
;         for (int a = 0; a < 2; ++a)
; #pragma unroll
;             for (int b = 0; b < 2; ++b)
; #pragma unroll
;                 for (int m = 0; m < 4; ++m)
; #pragma unroll
;                     for (int n = 0; n < 2; ++n) acc[a][b][m][n] = (f32x4){0.f, 0.f, 0.f, 0.f};
;         cur = nxt; cA = nA; cB = nB; ++ui;
.LBB0_169:
	s_ashr_i32 s25, s24, 31
	s_lshl_b64 s[30:31], s[24:25], 20
	s_add_u32 s25, s3, s30
	s_addc_u32 s27, s10, s31
	s_lshl_b64 s[30:31], s[0:1], 10
	s_cmp_gt_i32 s0, 0
	s_cselect_b32 s52, s30, 0
	s_cselect_b32 s51, s31, 0
	s_add_u32 s30, s25, s52
	s_addc_u32 s31, s27, s51
	s_and_b64 s[34:35], s[28:29], exec
	s_cselect_b32 s25, s31, s45
	s_cselect_b32 s50, s30, s44
	s_ashr_i32 s27, s26, 31
	s_lshl_b64 s[34:35], s[26:27], 20
	s_add_u32 s27, s74, s34
	s_addc_u32 s35, s75, s35
	s_add_u32 s34, s27, s52
	s_addc_u32 s35, s35, s51
	s_and_b64 s[52:53], s[28:29], exec
	s_cselect_b32 s27, s35, s47
	s_cselect_b32 s51, s34, s46
	s_cmp_gt_i32 s49, -1
	s_cselect_b32 s52, 8, 32
	s_add_i32 s53, s52, -2
	s_add_u32 s44, s44, 0x80080
	s_addc_u32 s45, s45, 0
	s_add_u32 s54, s46, 0x100
	v_mov_b32_e32 v0, 0
	s_mov_b32 s48, 0
	s_addc_u32 s55, s47, 0
	v_mov_b32_e32 v1, v0
	v_mov_b32_e32 v2, v0
	v_mov_b32_e32 v3, v0
	v_mov_b32_e32 v4, v0
	v_mov_b32_e32 v5, v0
	v_mov_b32_e32 v6, v0
	v_mov_b32_e32 v7, v0
	v_mov_b32_e32 v16, v0
	v_mov_b32_e32 v17, v0
	v_mov_b32_e32 v18, v0
	v_mov_b32_e32 v19, v0
	v_mov_b32_e32 v20, v0
	v_mov_b32_e32 v21, v0
	v_mov_b32_e32 v22, v0
	v_mov_b32_e32 v23, v0
	v_mov_b32_e32 v32, v0
	v_mov_b32_e32 v33, v0
	v_mov_b32_e32 v34, v0
	v_mov_b32_e32 v35, v0
	v_mov_b32_e32 v36, v0
	v_mov_b32_e32 v37, v0
	v_mov_b32_e32 v38, v0
	v_mov_b32_e32 v39, v0
	v_mov_b32_e32 v48, v0
	v_mov_b32_e32 v49, v0
	v_mov_b32_e32 v50, v0
	v_mov_b32_e32 v51, v0
	v_mov_b32_e32 v52, v0
	v_mov_b32_e32 v53, v0
	v_mov_b32_e32 v54, v0
	v_mov_b32_e32 v55, v0
	v_mov_b32_e32 v8, v0
	v_mov_b32_e32 v9, v0
	v_mov_b32_e32 v10, v0
	v_mov_b32_e32 v11, v0
	v_mov_b32_e32 v12, v0
	v_mov_b32_e32 v13, v0
	v_mov_b32_e32 v14, v0
	v_mov_b32_e32 v15, v0
	v_mov_b32_e32 v24, v0
	v_mov_b32_e32 v25, v0
	v_mov_b32_e32 v26, v0
	v_mov_b32_e32 v27, v0
	v_mov_b32_e32 v28, v0
	v_mov_b32_e32 v29, v0
	v_mov_b32_e32 v30, v0
	v_mov_b32_e32 v31, v0
	v_mov_b32_e32 v40, v0
	v_mov_b32_e32 v41, v0
	v_mov_b32_e32 v42, v0
	v_mov_b32_e32 v43, v0
	v_mov_b32_e32 v44, v0
	v_mov_b32_e32 v45, v0
	v_mov_b32_e32 v46, v0
	v_mov_b32_e32 v47, v0
	v_mov_b32_e32 v56, v0
	v_mov_b32_e32 v57, v0
	v_mov_b32_e32 v58, v0
	v_mov_b32_e32 v59, v0
	v_mov_b32_e32 v60, v0
	v_mov_b32_e32 v61, v0
	v_mov_b32_e32 v62, v0
	v_mov_b32_e32 v63, v0
	v_mov_b32_e32 v64, v0
	v_mov_b32_e32 v65, v0
	v_mov_b32_e32 v66, v0
	v_mov_b32_e32 v67, v0
	v_mov_b32_e32 v68, v0
	v_mov_b32_e32 v69, v0
	v_mov_b32_e32 v70, v0
	v_mov_b32_e32 v71, v0
	v_mov_b32_e32 v80, v0
	v_mov_b32_e32 v81, v0
	v_mov_b32_e32 v82, v0
	v_mov_b32_e32 v83, v0
	v_mov_b32_e32 v84, v0
	v_mov_b32_e32 v85, v0
	v_mov_b32_e32 v86, v0
	v_mov_b32_e32 v87, v0
	v_mov_b32_e32 v96, v0
	v_mov_b32_e32 v97, v0
	v_mov_b32_e32 v98, v0
	v_mov_b32_e32 v99, v0
	v_mov_b32_e32 v100, v0
	v_mov_b32_e32 v101, v0
	v_mov_b32_e32 v102, v0
	v_mov_b32_e32 v103, v0
	v_mov_b32_e32 v112, v0
	v_mov_b32_e32 v113, v0
	v_mov_b32_e32 v114, v0
	v_mov_b32_e32 v115, v0
	v_mov_b32_e32 v116, v0
	v_mov_b32_e32 v117, v0
	v_mov_b32_e32 v118, v0
	v_mov_b32_e32 v119, v0
	v_mov_b32_e32 v72, v0
	v_mov_b32_e32 v73, v0
	v_mov_b32_e32 v74, v0
	v_mov_b32_e32 v75, v0
	v_mov_b32_e32 v76, v0
	v_mov_b32_e32 v77, v0
	v_mov_b32_e32 v78, v0
	v_mov_b32_e32 v79, v0
	v_mov_b32_e32 v88, v0
	v_mov_b32_e32 v89, v0
	v_mov_b32_e32 v90, v0
	v_mov_b32_e32 v91, v0
	v_mov_b32_e32 v92, v0
	v_mov_b32_e32 v93, v0
	v_mov_b32_e32 v94, v0
	v_mov_b32_e32 v95, v0
	v_mov_b32_e32 v104, v0
	v_mov_b32_e32 v105, v0
	v_mov_b32_e32 v106, v0
	v_mov_b32_e32 v107, v0
	v_mov_b32_e32 v108, v0
	v_mov_b32_e32 v109, v0
	v_mov_b32_e32 v110, v0
	v_mov_b32_e32 v111, v0
	v_mov_b32_e32 v120, v0
	v_mov_b32_e32 v121, v0
	v_mov_b32_e32 v122, v0
	v_mov_b32_e32 v123, v0
	v_mov_b32_e32 v124, v0
	v_mov_b32_e32 v125, v0
	v_mov_b32_e32 v126, v0
	v_mov_b32_e32 v127, v0
	v_add_u32_e32 v222, 0x18000, v146
	v_add_u32_e32 v223, 0x1c000, v146
.LBB0_170:
	ds_read_b128 v[158:161], v155
	ds_read_b128 v[162:165], v155 offset:1024
	ds_read_b128 v[166:169], v155 offset:2048
	ds_read_b128 v[170:173], v155 offset:3072
	ds_read_b128 v[174:177], v156
	ds_read_b128 v[178:181], v156 offset:1024
	ds_read_b128 v[182:185], v156 offset:2048
	ds_read_b128 v[186:189], v156 offset:3072
	s_add_i32 s56, s48, 2
	s_add_u32 s46, s44, 0xfff80080
	s_addc_u32 s47, s45, -1
	s_cmp_eq_u32 s53, s48
	s_cselect_b32 s48, s50, s46
	s_cselect_b32 s49, s25, s47
	s_cselect_b32 s47, s27, s55
	s_cselect_b32 s46, s51, s54
	s_add_i32 m0, s14, 0xc000
	ds_read_b128 v[190:193], v157
	ds_read_b128 v[194:197], v157 offset:1024
	ds_read_b128 v[198:201], v157 offset:2048
	ds_read_b128 v[202:205], v157 offset:3072
	ds_read_b128 v[206:209], v157 offset:4096
	ds_read_b128 v[210:213], v157 offset:5120
	ds_read_b128 v[214:217], v157 offset:6144
	ds_read_b128 v[218:221], v157 offset:7168
	global_load_lds_dwordx4 v136, s[44:45]
	s_add_i32 m0, s14, 0xe000
	s_nop 0
	global_load_lds_dwordx4 v138, s[44:45]
	s_waitcnt vmcnt(8)
	s_waitcnt lgkmcnt(0)
	s_barrier
; #define PG8_STAGE(bufoff, gbase, voff) do { _Pragma("unroll") for (int _i = 0; _i < 2; ++_i) \
;         __builtin_amdgcn_global_load_lds((const unsigned*)((const char*)(gbase) + (voff)[_i]), (LAS unsigned*)(lds + (bufoff) + ldsw + _i * 8192), 16, 0, 0); } while (0)
; #define PG8_LDA(dst, b, h) do { _Pragma("unroll") for (int m = 0; m < 4; ++m) _Pragma("unroll") for (int k = 0; k < 2; ++k) dst[m][k] = *(const LAS bf16x8*)(lds + PG8_SA(b, h) + aoff + m * 2048 + k * 1024); } while (0)
; #define PG8_MMA(ai, bj, At, Bt) do { __builtin_amdgcn_s_setprio(1); _Pragma("unroll") for (int m = 0; m < 4; ++m) _Pragma("unroll") for (int n = 0; n < 2; ++n) _Pragma("unroll") for (int k = 0; k < 2; ++k) \
;         acc[ai][bj][m][n] = __builtin_amdgcn_mfma_f32_16x16x32_bf16(Bt[n][k], At[m][k], acc[ai][bj][m][n], 0, 0, 0); __builtin_amdgcn_s_setprio(0); } while (0)
; #define PG8_WAIT_V(n) asm volatile("s_waitcnt vmcnt(" #n ")" ::: "memory")
; #define PG8_WAIT_L(n) asm volatile("s_waitcnt lgkmcnt(" #n ")" ::: "memory")
; #define PG8_BAR __builtin_amdgcn_s_barrier()
; #define PG8_SCHED __builtin_amdgcn_sched_barrier(0)
; __device__ __forceinline__ void gemm_phase(LAS unsigned char* lds, const Params& p, const bf16_t* gA, const bf16_t* gBt, const int gM, const int gN, const int gK, const int epi, const int perm, bf16_t* const Hp, const int goff, const float coef) {
;     ...
;             PG8_WAIT_V(8); PG8_WAIT_L(0); PG8_BAR; PG8_MMA(0, 0, At, B0); PG8_MMA(0, 1, At, B1); PG8_BAR; PG8_SCHED;
;             PG8_LDA(At, 0, 1); PG8_STAGE(PG8_SB(0, 0), b2, voffB); PG8_STAGE(PG8_SB(0, 1), b2 + hstep, voffB); PG8_STAGE(PG8_SA(0, 0), a2, voffA);
;             PG8_WAIT_V(8); PG8_WAIT_L(0); PG8_BAR; PG8_MMA(1, 0, At, B0); PG8_MMA(1, 1, At, B1); PG8_BAR; PG8_SCHED;
	s_setprio 1
	s_waitcnt lgkmcnt(0)
	v_mfma_f32_16x16x32_bf16 v[124:127], v[158:161], v[190:193], v[124:127]
	v_mfma_f32_16x16x32_bf16 v[120:123], v[166:169], v[190:193], v[120:123]
	v_mfma_f32_16x16x32_bf16 v[108:111], v[158:161], v[198:201], v[108:111]
	v_mfma_f32_16x16x32_bf16 v[104:107], v[166:169], v[198:201], v[104:107]
	v_mfma_f32_16x16x32_bf16 v[92:95], v[158:161], v[206:209], v[92:95]
	v_mfma_f32_16x16x32_bf16 v[88:91], v[166:169], v[206:209], v[88:91]
	v_mfma_f32_16x16x32_bf16 v[76:79], v[158:161], v[214:217], v[76:79]
	v_mfma_f32_16x16x32_bf16 v[72:75], v[166:169], v[214:217], v[72:75]
	v_mfma_f32_16x16x32_bf16 v[124:127], v[162:165], v[194:197], v[124:127]
	v_mfma_f32_16x16x32_bf16 v[120:123], v[170:173], v[194:197], v[120:123]
	v_mfma_f32_16x16x32_bf16 v[108:111], v[162:165], v[202:205], v[108:111]
	v_mfma_f32_16x16x32_bf16 v[104:107], v[170:173], v[202:205], v[104:107]
	v_mfma_f32_16x16x32_bf16 v[92:95], v[162:165], v[210:213], v[92:95]
	v_mfma_f32_16x16x32_bf16 v[88:91], v[170:173], v[210:213], v[88:91]
	v_mfma_f32_16x16x32_bf16 v[76:79], v[162:165], v[218:221], v[76:79]
	v_mfma_f32_16x16x32_bf16 v[72:75], v[170:173], v[218:221], v[72:75]
	s_setprio 0
	s_setprio 1
	v_mfma_f32_16x16x32_bf16 v[116:119], v[174:177], v[190:193], v[116:119]
	v_mfma_f32_16x16x32_bf16 v[112:115], v[182:185], v[190:193], v[112:115]
	v_mfma_f32_16x16x32_bf16 v[100:103], v[174:177], v[198:201], v[100:103]
	v_mfma_f32_16x16x32_bf16 v[96:99], v[182:185], v[198:201], v[96:99]
	v_mfma_f32_16x16x32_bf16 v[84:87], v[174:177], v[206:209], v[84:87]
	v_mfma_f32_16x16x32_bf16 v[80:83], v[182:185], v[206:209], v[80:83]
	v_mfma_f32_16x16x32_bf16 v[68:71], v[174:177], v[214:217], v[68:71]
	v_mfma_f32_16x16x32_bf16 v[64:67], v[182:185], v[214:217], v[64:67]
	v_mfma_f32_16x16x32_bf16 v[116:119], v[178:181], v[194:197], v[116:119]
	v_mfma_f32_16x16x32_bf16 v[112:115], v[186:189], v[194:197], v[112:115]
	v_mfma_f32_16x16x32_bf16 v[100:103], v[178:181], v[202:205], v[100:103]
	v_mfma_f32_16x16x32_bf16 v[96:99], v[186:189], v[202:205], v[96:99]
	v_mfma_f32_16x16x32_bf16 v[84:87], v[178:181], v[210:213], v[84:87]
	v_mfma_f32_16x16x32_bf16 v[80:83], v[186:189], v[210:213], v[80:83]
	v_mfma_f32_16x16x32_bf16 v[68:71], v[178:181], v[218:221], v[68:71]
	v_mfma_f32_16x16x32_bf16 v[64:67], v[186:189], v[218:221], v[64:67]
	s_setprio 0
	s_barrier
	s_add_i32 s57, s23, s11
	s_mov_b32 m0, s57
	ds_read_b128 v[190:193], v157 offset:16384
	ds_read_b128 v[194:197], v157 offset:17408
	ds_read_b128 v[198:201], v157 offset:18432
	ds_read_b128 v[202:205], v157 offset:19456
	ds_read_b128 v[206:209], v157 offset:20480
	ds_read_b128 v[210:213], v157 offset:21504
	ds_read_b128 v[214:217], v157 offset:22528
	ds_read_b128 v[218:221], v157 offset:23552
	global_load_lds_dwordx4 v130, s[46:47]
	s_add_i32 m0, s57, 0x2000
	s_add_u32 s58, s46, 0x80000
	s_addc_u32 s59, s47, 0
	s_add_i32 s57, s33, s11
	global_load_lds_dwordx4 v134, s[46:47]
	s_mov_b32 m0, s57
	s_nop 0
	global_load_lds_dwordx4 v130, s[58:59]
	s_add_i32 m0, s57, 0x2000
	s_nop 0
	global_load_lds_dwordx4 v134, s[58:59]
	s_mov_b32 m0, s14
	s_nop 0
	global_load_lds_dwordx4 v128, s[48:49]
	s_mov_b32 m0, s15
	s_nop 0
	global_load_lds_dwordx4 v132, s[48:49]
	s_waitcnt vmcnt(8)
	s_waitcnt lgkmcnt(0)
	s_barrier
	s_setprio 1
	s_waitcnt lgkmcnt(0)
	v_mfma_f32_16x16x32_bf16 v[60:63], v[158:161], v[190:193], v[60:63]
	v_mfma_f32_16x16x32_bf16 v[56:59], v[166:169], v[190:193], v[56:59]
	v_mfma_f32_16x16x32_bf16 v[44:47], v[158:161], v[198:201], v[44:47]
	v_mfma_f32_16x16x32_bf16 v[40:43], v[166:169], v[198:201], v[40:43]
	v_mfma_f32_16x16x32_bf16 v[28:31], v[158:161], v[206:209], v[28:31]
	v_mfma_f32_16x16x32_bf16 v[24:27], v[166:169], v[206:209], v[24:27]
	v_mfma_f32_16x16x32_bf16 v[12:15], v[158:161], v[214:217], v[12:15]
	v_mfma_f32_16x16x32_bf16 v[8:11], v[166:169], v[214:217], v[8:11]
	v_mfma_f32_16x16x32_bf16 v[60:63], v[162:165], v[194:197], v[60:63]
	v_mfma_f32_16x16x32_bf16 v[56:59], v[170:173], v[194:197], v[56:59]
	v_mfma_f32_16x16x32_bf16 v[44:47], v[162:165], v[202:205], v[44:47]
	v_mfma_f32_16x16x32_bf16 v[40:43], v[170:173], v[202:205], v[40:43]
	v_mfma_f32_16x16x32_bf16 v[28:31], v[162:165], v[210:213], v[28:31]
	v_mfma_f32_16x16x32_bf16 v[24:27], v[170:173], v[210:213], v[24:27]
	v_mfma_f32_16x16x32_bf16 v[12:15], v[162:165], v[218:221], v[12:15]
	v_mfma_f32_16x16x32_bf16 v[8:11], v[170:173], v[218:221], v[8:11]
	s_setprio 0
	s_setprio 1
	v_mfma_f32_16x16x32_bf16 v[52:55], v[174:177], v[190:193], v[52:55]
	v_mfma_f32_16x16x32_bf16 v[48:51], v[182:185], v[190:193], v[48:51]
	v_mfma_f32_16x16x32_bf16 v[36:39], v[174:177], v[198:201], v[36:39]
	v_mfma_f32_16x16x32_bf16 v[32:35], v[182:185], v[198:201], v[32:35]
	v_mfma_f32_16x16x32_bf16 v[20:23], v[174:177], v[206:209], v[20:23]
	v_mfma_f32_16x16x32_bf16 v[16:19], v[182:185], v[206:209], v[16:19]
	v_mfma_f32_16x16x32_bf16 v[4:7], v[174:177], v[214:217], v[4:7]
	v_mfma_f32_16x16x32_bf16 v[0:3], v[182:185], v[214:217], v[0:3]
	v_mfma_f32_16x16x32_bf16 v[52:55], v[178:181], v[194:197], v[52:55]
	v_mfma_f32_16x16x32_bf16 v[48:51], v[186:189], v[194:197], v[48:51]
	v_mfma_f32_16x16x32_bf16 v[36:39], v[178:181], v[202:205], v[36:39]
	v_mfma_f32_16x16x32_bf16 v[32:35], v[186:189], v[202:205], v[32:35]
	v_mfma_f32_16x16x32_bf16 v[20:23], v[178:181], v[210:213], v[20:23]
	v_mfma_f32_16x16x32_bf16 v[16:19], v[186:189], v[210:213], v[16:19]
	v_mfma_f32_16x16x32_bf16 v[4:7], v[178:181], v[218:221], v[4:7]
	v_mfma_f32_16x16x32_bf16 v[0:3], v[186:189], v[218:221], v[0:3]
	s_setprio 0
	s_barrier
; #define PG8_STAGE(bufoff, gbase, voff) do { _Pragma("unroll") for (int _i = 0; _i < 2; ++_i) \
;         __builtin_amdgcn_global_load_lds((const unsigned*)((const char*)(gbase) + (voff)[_i]), (LAS unsigned*)(lds + (bufoff) + ldsw + _i * 8192), 16, 0, 0); } while (0)
; #define PG8_LDA(dst, b, h) do { _Pragma("unroll") for (int m = 0; m < 4; ++m) _Pragma("unroll") for (int k = 0; k < 2; ++k) dst[m][k] = *(const LAS bf16x8*)(lds + PG8_SA(b, h) + aoff + m * 2048 + k * 1024); } while (0)
; #define PG8_LDB(dst, b, h) do { _Pragma("unroll") for (int n = 0; n < 2; ++n) _Pragma("unroll") for (int k = 0; k < 2; ++k) dst[n][k] = *(const LAS bf16x8*)(lds + PG8_SB(b, h) + boff + n * 2048 + k * 1024); } while (0)
; #define PG8_MMA(ai, bj, At, Bt) do { __builtin_amdgcn_s_setprio(1); _Pragma("unroll") for (int m = 0; m < 4; ++m) _Pragma("unroll") for (int n = 0; n < 2; ++n) _Pragma("unroll") for (int k = 0; k < 2; ++k) \
;         acc[ai][bj][m][n] = __builtin_amdgcn_mfma_f32_16x16x32_bf16(Bt[n][k], At[m][k], acc[ai][bj][m][n], 0, 0, 0); __builtin_amdgcn_s_setprio(0); } while (0)
; #define PG8_WAIT_V(n) asm volatile("s_waitcnt vmcnt(" #n ")" ::: "memory")
; #define PG8_WAIT_L(n) asm volatile("s_waitcnt lgkmcnt(" #n ")" ::: "memory")
; #define PG8_BAR __builtin_amdgcn_s_barrier()
; #define PG8_SCHED __builtin_amdgcn_sched_barrier(0)
; __device__ __forceinline__ void gemm_phase(LAS unsigned char* lds, const Params& p, const bf16_t* gA, const bf16_t* gBt, const int gM, const int gN, const int gK, const int epi, const int perm, bf16_t* const Hp, const int goff, const float coef) {
;     ...
;             PG8_LDB(B0, 1, 0); PG8_LDB(B1, 1, 1); PG8_SCHED; PG8_LDA(At, 1, 0); PG8_STAGE(PG8_SA(0, 1), a2 + hstep, voffA);
;             PG8_WAIT_V(8); PG8_WAIT_L(0); PG8_BAR; PG8_MMA(0, 0, At, B0); PG8_MMA(0, 1, At, B1); PG8_BAR; PG8_SCHED;
;             PG8_LDA(At, 1, 1); PG8_STAGE(PG8_SB(1, 0), b3, voffB); PG8_STAGE(PG8_SB(1, 1), b3 + hstep, voffB); PG8_STAGE(PG8_SA(1, 0), a3, voffA);
;             PG8_WAIT_V(8); PG8_WAIT_L(0); PG8_BAR; PG8_MMA(1, 0, At, B0); PG8_MMA(1, 1, At, B1); PG8_BAR; PG8_SCHED;
;         }
	s_add_i32 s57, 0, 0x18000
	s_add_i32 s58, 0, 0x1c000
	ds_read_b128 v[158:161], v222
	ds_read_b128 v[162:165], v222 offset:1024
	ds_read_b128 v[166:169], v222 offset:2048
	ds_read_b128 v[170:173], v222 offset:3072
	ds_read_b128 v[174:177], v223
	ds_read_b128 v[178:181], v223 offset:1024
	ds_read_b128 v[182:185], v223 offset:2048
	ds_read_b128 v[186:189], v223 offset:3072
	s_add_u32 s48, s48, 0x80000
	s_addc_u32 s49, s49, 0
	s_mov_b32 m0, s16
	ds_read_b128 v[190:193], v157 offset:32768
	ds_read_b128 v[194:197], v157 offset:33792
	ds_read_b128 v[198:201], v157 offset:34816
	ds_read_b128 v[202:205], v157 offset:35840
	ds_read_b128 v[206:209], v157 offset:36864
	ds_read_b128 v[210:213], v157 offset:37888
	ds_read_b128 v[214:217], v157 offset:38912
	ds_read_b128 v[218:221], v157 offset:39936
	global_load_lds_dwordx4 v128, s[48:49]
	s_mov_b32 m0, s17
	s_nop 0
	global_load_lds_dwordx4 v132, s[48:49]
	s_waitcnt vmcnt(8)
	s_waitcnt lgkmcnt(0)
	s_barrier
	s_setprio 1
	s_waitcnt lgkmcnt(0)
	v_mfma_f32_16x16x32_bf16 v[124:127], v[158:161], v[190:193], v[124:127]
	v_mfma_f32_16x16x32_bf16 v[120:123], v[166:169], v[190:193], v[120:123]
	v_mfma_f32_16x16x32_bf16 v[108:111], v[158:161], v[198:201], v[108:111]
	v_mfma_f32_16x16x32_bf16 v[104:107], v[166:169], v[198:201], v[104:107]
	v_mfma_f32_16x16x32_bf16 v[92:95], v[158:161], v[206:209], v[92:95]
	v_mfma_f32_16x16x32_bf16 v[88:91], v[166:169], v[206:209], v[88:91]
	v_mfma_f32_16x16x32_bf16 v[76:79], v[158:161], v[214:217], v[76:79]
	v_mfma_f32_16x16x32_bf16 v[72:75], v[166:169], v[214:217], v[72:75]
	v_mfma_f32_16x16x32_bf16 v[124:127], v[162:165], v[194:197], v[124:127]
	v_mfma_f32_16x16x32_bf16 v[120:123], v[170:173], v[194:197], v[120:123]
	v_mfma_f32_16x16x32_bf16 v[108:111], v[162:165], v[202:205], v[108:111]
	v_mfma_f32_16x16x32_bf16 v[104:107], v[170:173], v[202:205], v[104:107]
	v_mfma_f32_16x16x32_bf16 v[92:95], v[162:165], v[210:213], v[92:95]
	v_mfma_f32_16x16x32_bf16 v[88:91], v[170:173], v[210:213], v[88:91]
	v_mfma_f32_16x16x32_bf16 v[76:79], v[162:165], v[218:221], v[76:79]
	v_mfma_f32_16x16x32_bf16 v[72:75], v[170:173], v[218:221], v[72:75]
	s_setprio 0
	s_setprio 1
	v_mfma_f32_16x16x32_bf16 v[116:119], v[174:177], v[190:193], v[116:119]
	v_mfma_f32_16x16x32_bf16 v[112:115], v[182:185], v[190:193], v[112:115]
	v_mfma_f32_16x16x32_bf16 v[100:103], v[174:177], v[198:201], v[100:103]
	v_mfma_f32_16x16x32_bf16 v[96:99], v[182:185], v[198:201], v[96:99]
	v_mfma_f32_16x16x32_bf16 v[84:87], v[174:177], v[206:209], v[84:87]
	v_mfma_f32_16x16x32_bf16 v[80:83], v[182:185], v[206:209], v[80:83]
	v_mfma_f32_16x16x32_bf16 v[68:71], v[174:177], v[214:217], v[68:71]
	v_mfma_f32_16x16x32_bf16 v[64:67], v[182:185], v[214:217], v[64:67]
	v_mfma_f32_16x16x32_bf16 v[116:119], v[178:181], v[194:197], v[116:119]
	v_mfma_f32_16x16x32_bf16 v[112:115], v[186:189], v[194:197], v[112:115]
	v_mfma_f32_16x16x32_bf16 v[100:103], v[178:181], v[202:205], v[100:103]
	v_mfma_f32_16x16x32_bf16 v[96:99], v[186:189], v[202:205], v[96:99]
	v_mfma_f32_16x16x32_bf16 v[84:87], v[178:181], v[210:213], v[84:87]
	v_mfma_f32_16x16x32_bf16 v[80:83], v[186:189], v[210:213], v[80:83]
	v_mfma_f32_16x16x32_bf16 v[68:71], v[178:181], v[218:221], v[68:71]
	v_mfma_f32_16x16x32_bf16 v[64:67], v[186:189], v[218:221], v[64:67]
	s_setprio 0
	s_barrier
	s_mov_b64 s[98:99], s[48:49]
	s_add_i32 s48, s57, s11
	s_mov_b32 m0, s48
	ds_read_b128 v[190:193], v157 offset:49152
	ds_read_b128 v[194:197], v157 offset:50176
	ds_read_b128 v[198:201], v157 offset:51200
	ds_read_b128 v[202:205], v157 offset:52224
	ds_read_b128 v[206:209], v157 offset:53248
	ds_read_b128 v[210:213], v157 offset:54272
	ds_read_b128 v[214:217], v157 offset:55296
	ds_read_b128 v[218:221], v157 offset:56320
	s_add_u32 s100, s46, 0x80
	s_addc_u32 s101, s47, 0
	global_load_lds_dwordx4 v130, s[100:101]
	s_add_i32 m0, s48, 0x2000
	s_add_u32 s46, s46, 0x80080
	s_addc_u32 s47, s47, 0
	s_add_i32 s48, s58, s11
	global_load_lds_dwordx4 v134, s[100:101]
	s_mov_b32 m0, s48
	s_nop 0
	global_load_lds_dwordx4 v130, s[46:47]
	s_add_i32 m0, s48, 0x2000
	s_nop 0
	global_load_lds_dwordx4 v134, s[46:47]
	s_mov_b32 m0, s19
	s_nop 0
	s_add_u32 s100, s98, 0xfff80080
	s_addc_u32 s101, s99, -1
	global_load_lds_dwordx4 v128, s[100:101]
	s_mov_b32 m0, s20
	s_nop 0
	global_load_lds_dwordx4 v132, s[100:101]
	s_waitcnt vmcnt(8)
	s_waitcnt lgkmcnt(0)
	s_barrier
	s_setprio 1
	s_waitcnt lgkmcnt(0)
	v_mfma_f32_16x16x32_bf16 v[60:63], v[158:161], v[190:193], v[60:63]
	v_mfma_f32_16x16x32_bf16 v[56:59], v[166:169], v[190:193], v[56:59]
	v_mfma_f32_16x16x32_bf16 v[44:47], v[158:161], v[198:201], v[44:47]
	v_mfma_f32_16x16x32_bf16 v[40:43], v[166:169], v[198:201], v[40:43]
	v_mfma_f32_16x16x32_bf16 v[28:31], v[158:161], v[206:209], v[28:31]
	v_mfma_f32_16x16x32_bf16 v[24:27], v[166:169], v[206:209], v[24:27]
	v_mfma_f32_16x16x32_bf16 v[12:15], v[158:161], v[214:217], v[12:15]
	v_mfma_f32_16x16x32_bf16 v[8:11], v[166:169], v[214:217], v[8:11]
	v_mfma_f32_16x16x32_bf16 v[60:63], v[162:165], v[194:197], v[60:63]
	v_mfma_f32_16x16x32_bf16 v[56:59], v[170:173], v[194:197], v[56:59]
	v_mfma_f32_16x16x32_bf16 v[44:47], v[162:165], v[202:205], v[44:47]
	v_mfma_f32_16x16x32_bf16 v[40:43], v[170:173], v[202:205], v[40:43]
	v_mfma_f32_16x16x32_bf16 v[28:31], v[162:165], v[210:213], v[28:31]
	v_mfma_f32_16x16x32_bf16 v[24:27], v[170:173], v[210:213], v[24:27]
	v_mfma_f32_16x16x32_bf16 v[12:15], v[162:165], v[218:221], v[12:15]
	v_mfma_f32_16x16x32_bf16 v[8:11], v[170:173], v[218:221], v[8:11]
	s_setprio 0
	s_setprio 1
	v_mfma_f32_16x16x32_bf16 v[52:55], v[174:177], v[190:193], v[52:55]
	v_mfma_f32_16x16x32_bf16 v[48:51], v[182:185], v[190:193], v[48:51]
	v_mfma_f32_16x16x32_bf16 v[36:39], v[174:177], v[198:201], v[36:39]
	v_mfma_f32_16x16x32_bf16 v[32:35], v[182:185], v[198:201], v[32:35]
	v_mfma_f32_16x16x32_bf16 v[20:23], v[174:177], v[206:209], v[20:23]
	v_mfma_f32_16x16x32_bf16 v[16:19], v[182:185], v[206:209], v[16:19]
	v_mfma_f32_16x16x32_bf16 v[4:7], v[174:177], v[214:217], v[4:7]
	v_mfma_f32_16x16x32_bf16 v[0:3], v[182:185], v[214:217], v[0:3]
	v_mfma_f32_16x16x32_bf16 v[52:55], v[178:181], v[194:197], v[52:55]
	v_mfma_f32_16x16x32_bf16 v[48:51], v[186:189], v[194:197], v[48:51]
	v_mfma_f32_16x16x32_bf16 v[36:39], v[178:181], v[202:205], v[36:39]
	v_mfma_f32_16x16x32_bf16 v[32:35], v[186:189], v[202:205], v[32:35]
	v_mfma_f32_16x16x32_bf16 v[20:23], v[178:181], v[210:213], v[20:23]
	v_mfma_f32_16x16x32_bf16 v[16:19], v[186:189], v[210:213], v[16:19]
	v_mfma_f32_16x16x32_bf16 v[4:7], v[178:181], v[218:221], v[4:7]
	v_mfma_f32_16x16x32_bf16 v[0:3], v[186:189], v[218:221], v[0:3]
	s_setprio 0
	s_barrier
	s_add_u32 s44, s44, 0x100
	s_addc_u32 s45, s45, 0
	s_add_u32 s54, s54, 0x100
	s_addc_u32 s55, s55, 0
	s_cmp_ge_u32 s56, s52
	s_mov_b32 s48, s56
	s_cbranch_scc0 .LBB0_170
	s_and_b64 vcc, exec, s[12:13]
	s_cbranch_vccz .LBB0_173
	s_barrier

; #define PG8_STAGE(bufoff, gbase, voff) do { _Pragma("unroll") for (int _i = 0; _i < 2; ++_i) \
;         __builtin_amdgcn_global_load_lds((const unsigned*)((const char*)(gbase) + (voff)[_i]), (LAS unsigned*)(lds + (bufoff) + ldsw + _i * 8192), 16, 0, 0); } while (0)
; #define PG8_LDA(dst, b, h) do { _Pragma("unroll") for (int m = 0; m < 4; ++m) _Pragma("unroll") for (int k = 0; k < 2; ++k) dst[m][k] = *(const LAS bf16x8*)(lds + PG8_SA(b, h) + aoff + m * 2048 + k * 1024); } while (0)
; #define PG8_LDB(dst, b, h) do { _Pragma("unroll") for (int n = 0; n < 2; ++n) _Pragma("unroll") for (int k = 0; k < 2; ++k) dst[n][k] = *(const LAS bf16x8*)(lds + PG8_SB(b, h) + boff + n * 2048 + k * 1024); } while (0)
; #define PG8_WAIT_V(n) asm volatile("s_waitcnt vmcnt(" #n ")" ::: "memory")
; #define PG8_WAIT_L(n) asm volatile("s_waitcnt lgkmcnt(" #n ")" ::: "memory")
; #define PG8_BAR __builtin_amdgcn_s_barrier()
; __device__ __forceinline__ void gemm_phase(LAS unsigned char* lds, const Params& p, const bf16_t* gA, const bf16_t* gBt, const int gM, const int gN, const int gK, const int epi, const int perm, bf16_t* const Hp, const int goff, const float coef) {
;     ...
;         const char* nA = has_next ? (const char*)gA + (size_t)nxt.pm * tstep + (nxt.ks > 0 ? nxt.ks * ksl : 0) : cA; const char* nB = has_next ? (const char*)gBt + (size_t)nxt.pn * tstep + (nxt.ks > 0 ? nxt.ks * ksl : 0) : cB;
;         const int nt = cur.ks >= 0 ? ntf / 4 : ntf;
;         for (int t = 0; t < nt; t += 2) {
;             const bool last = (t == nt - 2);
;             const char* a1 = cA + (size_t)(t + 1) * kstep;
;             const char* a2 = last ? nA : cA + (size_t)(t + 2) * kstep; const char* b2 = last ? nB : cB + (size_t)(t + 2) * kstep;
;             const char* a3 = a2 + kstep; const char* b3 = b2 + kstep;
;             PG8_LDB(B0, 0, 0); PG8_LDB(B1, 0, 1); PG8_SCHED; PG8_LDA(At, 0, 0); PG8_STAGE(PG8_SA(1, 1), a1 + hstep, voffA);
;             PG8_WAIT_V(8); PG8_WAIT_L(0); PG8_BAR; PG8_MMA(0, 0, At, B0); PG8_MMA(0, 1, At, B1); PG8_BAR; PG8_SCHED;
;     ...
; #pragma unroll
;         for (int a = 0; a < 2; ++a)
; #pragma unroll
;             for (int b = 0; b < 2; ++b)
; #pragma unroll
;                 for (int m = 0; m < 4; ++m)
; #pragma unroll
;                     for (int n = 0; n < 2; ++n) acc[a][b][m][n] = (f32x4){0.f, 0.f, 0.f, 0.f};
;         cur = nxt; cA = nA; cB = nB; ++ui;
.LBB0_263:
	s_cmp_gt_i32 s6, -1
	s_cselect_b64 s[4:5], -1, 0
	s_and_b64 s[38:39], s[4:5], exec
	s_cselect_b32 s54, 22, 0x58
	s_add_i32 s55, s54, -2
	s_add_u32 s30, s30, 0x160080
	s_addc_u32 s31, s31, 0
	s_add_u32 s56, s34, 0x100
	v_mov_b32_e32 v0, 0
	s_addc_u32 s57, s35, 0
	s_mov_b32 s34, 0
	v_mov_b32_e32 v1, v0
	v_mov_b32_e32 v2, v0
	v_mov_b32_e32 v3, v0
	v_mov_b32_e32 v4, v0
	v_mov_b32_e32 v5, v0
	v_mov_b32_e32 v6, v0
	v_mov_b32_e32 v7, v0
	v_mov_b32_e32 v8, v0
	v_mov_b32_e32 v9, v0
	v_mov_b32_e32 v10, v0
	v_mov_b32_e32 v11, v0
	v_mov_b32_e32 v12, v0
	v_mov_b32_e32 v13, v0
	v_mov_b32_e32 v14, v0
	v_mov_b32_e32 v15, v0
	v_mov_b32_e32 v16, v0
	v_mov_b32_e32 v17, v0
	v_mov_b32_e32 v18, v0
	v_mov_b32_e32 v19, v0
	v_mov_b32_e32 v20, v0
	v_mov_b32_e32 v21, v0
	v_mov_b32_e32 v22, v0
	v_mov_b32_e32 v23, v0
	v_mov_b32_e32 v24, v0
	v_mov_b32_e32 v25, v0
	v_mov_b32_e32 v26, v0
	v_mov_b32_e32 v27, v0
	v_mov_b32_e32 v28, v0
	v_mov_b32_e32 v29, v0
	v_mov_b32_e32 v30, v0
	v_mov_b32_e32 v31, v0
	v_mov_b32_e32 v56, v0
	v_mov_b32_e32 v57, v0
	v_mov_b32_e32 v58, v0
	v_mov_b32_e32 v59, v0
	v_mov_b32_e32 v64, v0
	v_mov_b32_e32 v65, v0
	v_mov_b32_e32 v66, v0
	v_mov_b32_e32 v67, v0
	v_mov_b32_e32 v72, v0
	v_mov_b32_e32 v73, v0
	v_mov_b32_e32 v74, v0
	v_mov_b32_e32 v75, v0
	v_mov_b32_e32 v76, v0
	v_mov_b32_e32 v77, v0
	v_mov_b32_e32 v78, v0
	v_mov_b32_e32 v79, v0
	v_mov_b32_e32 v80, v0
	v_mov_b32_e32 v81, v0
	v_mov_b32_e32 v82, v0
	v_mov_b32_e32 v83, v0
	v_mov_b32_e32 v84, v0
	v_mov_b32_e32 v85, v0
	v_mov_b32_e32 v86, v0
	v_mov_b32_e32 v87, v0
	v_mov_b32_e32 v88, v0
	v_mov_b32_e32 v89, v0
	v_mov_b32_e32 v90, v0
	v_mov_b32_e32 v91, v0
	v_mov_b32_e32 v92, v0
	v_mov_b32_e32 v93, v0
	v_mov_b32_e32 v94, v0
	v_mov_b32_e32 v95, v0
	v_mov_b32_e32 v32, v0
	v_mov_b32_e32 v33, v0
	v_mov_b32_e32 v34, v0
	v_mov_b32_e32 v35, v0
	v_mov_b32_e32 v36, v0
	v_mov_b32_e32 v37, v0
	v_mov_b32_e32 v38, v0
	v_mov_b32_e32 v39, v0
	v_mov_b32_e32 v40, v0
	v_mov_b32_e32 v41, v0
	v_mov_b32_e32 v42, v0
	v_mov_b32_e32 v43, v0
	v_mov_b32_e32 v44, v0
	v_mov_b32_e32 v45, v0
	v_mov_b32_e32 v46, v0
	v_mov_b32_e32 v47, v0
	v_mov_b32_e32 v48, v0
	v_mov_b32_e32 v49, v0
	v_mov_b32_e32 v50, v0
	v_mov_b32_e32 v51, v0
	v_mov_b32_e32 v52, v0
	v_mov_b32_e32 v53, v0
	v_mov_b32_e32 v54, v0
	v_mov_b32_e32 v55, v0
	v_mov_b32_e32 v60, v0
	v_mov_b32_e32 v61, v0
	v_mov_b32_e32 v62, v0
	v_mov_b32_e32 v63, v0
	v_mov_b32_e32 v68, v0
	v_mov_b32_e32 v69, v0
	v_mov_b32_e32 v70, v0
	v_mov_b32_e32 v71, v0
	v_mov_b32_e32 v96, v0
	v_mov_b32_e32 v97, v0
	v_mov_b32_e32 v98, v0
	v_mov_b32_e32 v99, v0
	v_mov_b32_e32 v100, v0
	v_mov_b32_e32 v101, v0
	v_mov_b32_e32 v102, v0
	v_mov_b32_e32 v103, v0
	v_mov_b32_e32 v104, v0
	v_mov_b32_e32 v105, v0
	v_mov_b32_e32 v106, v0
	v_mov_b32_e32 v107, v0
	v_mov_b32_e32 v108, v0
	v_mov_b32_e32 v109, v0
	v_mov_b32_e32 v110, v0
	v_mov_b32_e32 v111, v0
	v_mov_b32_e32 v112, v0
	v_mov_b32_e32 v113, v0
	v_mov_b32_e32 v114, v0
	v_mov_b32_e32 v115, v0
	v_mov_b32_e32 v116, v0
	v_mov_b32_e32 v117, v0
	v_mov_b32_e32 v118, v0
	v_mov_b32_e32 v119, v0
	v_mov_b32_e32 v120, v0
	v_mov_b32_e32 v121, v0
	v_mov_b32_e32 v122, v0
	v_mov_b32_e32 v123, v0
	v_mov_b32_e32 v124, v0
	v_mov_b32_e32 v125, v0
	v_mov_b32_e32 v126, v0
	v_mov_b32_e32 v127, v0
	v_add_u32_e32 v222, 0x18000, v158
	v_add_u32_e32 v223, 0x1c000, v158
.LBB0_264:
	ds_read_b128 v[146:149], v167
	ds_read_b128 v[150:153], v167 offset:1024
	ds_read_b128 v[154:157], v167 offset:2048
	ds_read_b128 v[170:173], v167 offset:3072
	ds_read_b128 v[174:177], v168
	ds_read_b128 v[178:181], v168 offset:1024
	ds_read_b128 v[182:185], v168 offset:2048
	ds_read_b128 v[186:189], v168 offset:3072
	s_add_i32 s58, s34, 2
	s_add_u32 s35, s30, 0xffea0080
	s_addc_u32 s38, s31, -1
	s_cmp_eq_u32 s55, s34
	s_cselect_b32 s34, s28, s56
	s_cselect_b32 s39, s27, s38
	s_cselect_b32 s38, s26, s35
	s_cselect_b32 s35, s29, s57
	s_add_i32 m0, s17, 0xc000
	ds_read_b128 v[190:193], v169
	ds_read_b128 v[194:197], v169 offset:1024
	ds_read_b128 v[198:201], v169 offset:2048
	ds_read_b128 v[202:205], v169 offset:3072
	ds_read_b128 v[206:209], v169 offset:4096
	ds_read_b128 v[210:213], v169 offset:5120
	ds_read_b128 v[214:217], v169 offset:6144
	ds_read_b128 v[218:221], v169 offset:7168
	global_load_lds_dwordx4 v136, s[30:31]
	s_add_i32 m0, s17, 0xe000
	s_nop 0
	global_load_lds_dwordx4 v138, s[30:31]
	s_waitcnt vmcnt(8)
	s_waitcnt lgkmcnt(0)
	s_barrier
	s_setprio 1
	s_waitcnt lgkmcnt(0)
	v_mfma_f32_16x16x32_bf16 v[124:127], v[146:149], v[190:193], v[124:127]
	v_mfma_f32_16x16x32_bf16 v[120:123], v[154:157], v[190:193], v[120:123]
	v_mfma_f32_16x16x32_bf16 v[116:119], v[146:149], v[198:201], v[116:119]
	v_mfma_f32_16x16x32_bf16 v[112:115], v[154:157], v[198:201], v[112:115]
	v_mfma_f32_16x16x32_bf16 v[108:111], v[146:149], v[206:209], v[108:111]
	v_mfma_f32_16x16x32_bf16 v[104:107], v[154:157], v[206:209], v[104:107]
	v_mfma_f32_16x16x32_bf16 v[100:103], v[146:149], v[214:217], v[100:103]
	v_mfma_f32_16x16x32_bf16 v[96:99], v[154:157], v[214:217], v[96:99]
	v_mfma_f32_16x16x32_bf16 v[124:127], v[150:153], v[194:197], v[124:127]
	v_mfma_f32_16x16x32_bf16 v[120:123], v[170:173], v[194:197], v[120:123]
	v_mfma_f32_16x16x32_bf16 v[116:119], v[150:153], v[202:205], v[116:119]
	v_mfma_f32_16x16x32_bf16 v[112:115], v[170:173], v[202:205], v[112:115]
	v_mfma_f32_16x16x32_bf16 v[108:111], v[150:153], v[210:213], v[108:111]
	v_mfma_f32_16x16x32_bf16 v[104:107], v[170:173], v[210:213], v[104:107]
	v_mfma_f32_16x16x32_bf16 v[100:103], v[150:153], v[218:221], v[100:103]
	v_mfma_f32_16x16x32_bf16 v[96:99], v[170:173], v[218:221], v[96:99]
	s_setprio 0
	s_setprio 1
	v_mfma_f32_16x16x32_bf16 v[68:71], v[174:177], v[190:193], v[68:71]
	v_mfma_f32_16x16x32_bf16 v[60:63], v[182:185], v[190:193], v[60:63]
	v_mfma_f32_16x16x32_bf16 v[52:55], v[174:177], v[198:201], v[52:55]
	v_mfma_f32_16x16x32_bf16 v[48:51], v[182:185], v[198:201], v[48:51]
	v_mfma_f32_16x16x32_bf16 v[44:47], v[174:177], v[206:209], v[44:47]
	v_mfma_f32_16x16x32_bf16 v[40:43], v[182:185], v[206:209], v[40:43]
	v_mfma_f32_16x16x32_bf16 v[36:39], v[174:177], v[214:217], v[36:39]
	v_mfma_f32_16x16x32_bf16 v[32:35], v[182:185], v[214:217], v[32:35]
	v_mfma_f32_16x16x32_bf16 v[68:71], v[178:181], v[194:197], v[68:71]
	v_mfma_f32_16x16x32_bf16 v[60:63], v[186:189], v[194:197], v[60:63]
	v_mfma_f32_16x16x32_bf16 v[52:55], v[178:181], v[202:205], v[52:55]
	v_mfma_f32_16x16x32_bf16 v[48:51], v[186:189], v[202:205], v[48:51]
	v_mfma_f32_16x16x32_bf16 v[44:47], v[178:181], v[210:213], v[44:47]
	v_mfma_f32_16x16x32_bf16 v[40:43], v[186:189], v[210:213], v[40:43]
	v_mfma_f32_16x16x32_bf16 v[36:39], v[178:181], v[218:221], v[36:39]
	v_mfma_f32_16x16x32_bf16 v[32:35], v[186:189], v[218:221], v[32:35]
	s_setprio 0
	s_barrier
; #define PG8_STAGE(bufoff, gbase, voff) do { _Pragma("unroll") for (int _i = 0; _i < 2; ++_i) \
;         __builtin_amdgcn_global_load_lds((const unsigned*)((const char*)(gbase) + (voff)[_i]), (LAS unsigned*)(lds + (bufoff) + ldsw + _i * 8192), 16, 0, 0); } while (0)
; #define PG8_LDA(dst, b, h) do { _Pragma("unroll") for (int m = 0; m < 4; ++m) _Pragma("unroll") for (int k = 0; k < 2; ++k) dst[m][k] = *(const LAS bf16x8*)(lds + PG8_SA(b, h) + aoff + m * 2048 + k * 1024); } while (0)
; #define PG8_LDB(dst, b, h) do { _Pragma("unroll") for (int n = 0; n < 2; ++n) _Pragma("unroll") for (int k = 0; k < 2; ++k) dst[n][k] = *(const LAS bf16x8*)(lds + PG8_SB(b, h) + boff + n * 2048 + k * 1024); } while (0)
; #define PG8_MMA(ai, bj, At, Bt) do { __builtin_amdgcn_s_setprio(1); _Pragma("unroll") for (int m = 0; m < 4; ++m) _Pragma("unroll") for (int n = 0; n < 2; ++n) _Pragma("unroll") for (int k = 0; k < 2; ++k) \
;         acc[ai][bj][m][n] = __builtin_amdgcn_mfma_f32_16x16x32_bf16(Bt[n][k], At[m][k], acc[ai][bj][m][n], 0, 0, 0); __builtin_amdgcn_s_setprio(0); } while (0)
; #define PG8_WAIT_V(n) asm volatile("s_waitcnt vmcnt(" #n ")" ::: "memory")
; #define PG8_WAIT_L(n) asm volatile("s_waitcnt lgkmcnt(" #n ")" ::: "memory")
; #define PG8_BAR __builtin_amdgcn_s_barrier()
; #define PG8_SCHED __builtin_amdgcn_sched_barrier(0)
; __device__ __forceinline__ void gemm_phase(LAS unsigned char* lds, const Params& p, const bf16_t* gA, const bf16_t* gBt, const int gM, const int gN, const int gK, const int epi, const int perm, bf16_t* const Hp, const int goff, const float coef) {
;     ...
;             PG8_LDA(At, 0, 1); PG8_STAGE(PG8_SB(0, 0), b2, voffB); PG8_STAGE(PG8_SB(0, 1), b2 + hstep, voffB); PG8_STAGE(PG8_SA(0, 0), a2, voffA);
;             PG8_WAIT_V(8); PG8_WAIT_L(0); PG8_BAR; PG8_MMA(1, 0, At, B0); PG8_MMA(1, 1, At, B1); PG8_BAR; PG8_SCHED;
;             PG8_LDB(B0, 1, 0); PG8_LDB(B1, 1, 1); PG8_SCHED; PG8_LDA(At, 1, 0); PG8_STAGE(PG8_SA(0, 1), a2 + hstep, voffA);
;             PG8_WAIT_V(8); PG8_WAIT_L(0); PG8_BAR; PG8_MMA(0, 0, At, B0); PG8_MMA(0, 1, At, B1); PG8_BAR; PG8_SCHED;
	s_add_i32 s59, s46, s16
	s_mov_b32 m0, s59
	ds_read_b128 v[190:193], v169 offset:16384
	ds_read_b128 v[194:197], v169 offset:17408
	ds_read_b128 v[198:201], v169 offset:18432
	ds_read_b128 v[202:205], v169 offset:19456
	ds_read_b128 v[206:209], v169 offset:20480
	ds_read_b128 v[210:213], v169 offset:21504
	ds_read_b128 v[214:217], v169 offset:22528
	ds_read_b128 v[218:221], v169 offset:23552
	global_load_lds_dwordx4 v130, s[34:35]
	s_add_i32 m0, s59, 0x2000
	s_add_u32 s60, s34, 0x160000
	s_addc_u32 s61, s35, 0
	s_add_i32 s59, s47, s16
	global_load_lds_dwordx4 v134, s[34:35]
	s_mov_b32 m0, s59
	s_nop 0
	global_load_lds_dwordx4 v130, s[60:61]
	s_add_i32 m0, s59, 0x2000
	s_nop 0
	global_load_lds_dwordx4 v134, s[60:61]
	s_mov_b32 m0, s17
	s_nop 0
	global_load_lds_dwordx4 v128, s[38:39]
	s_mov_b32 m0, s18
	s_nop 0
	global_load_lds_dwordx4 v132, s[38:39]
	s_waitcnt vmcnt(8)
	s_waitcnt lgkmcnt(0)
	s_barrier
	s_setprio 1
	s_waitcnt lgkmcnt(0)
	v_mfma_f32_16x16x32_bf16 v[92:95], v[146:149], v[190:193], v[92:95]
	v_mfma_f32_16x16x32_bf16 v[88:91], v[154:157], v[190:193], v[88:91]
	v_mfma_f32_16x16x32_bf16 v[84:87], v[146:149], v[198:201], v[84:87]
	v_mfma_f32_16x16x32_bf16 v[80:83], v[154:157], v[198:201], v[80:83]
	v_mfma_f32_16x16x32_bf16 v[76:79], v[146:149], v[206:209], v[76:79]
	v_mfma_f32_16x16x32_bf16 v[72:75], v[154:157], v[206:209], v[72:75]
	v_mfma_f32_16x16x32_bf16 v[64:67], v[146:149], v[214:217], v[64:67]
	v_mfma_f32_16x16x32_bf16 v[56:59], v[154:157], v[214:217], v[56:59]
	v_mfma_f32_16x16x32_bf16 v[92:95], v[150:153], v[194:197], v[92:95]
	v_mfma_f32_16x16x32_bf16 v[88:91], v[170:173], v[194:197], v[88:91]
	v_mfma_f32_16x16x32_bf16 v[84:87], v[150:153], v[202:205], v[84:87]
	v_mfma_f32_16x16x32_bf16 v[80:83], v[170:173], v[202:205], v[80:83]
	v_mfma_f32_16x16x32_bf16 v[76:79], v[150:153], v[210:213], v[76:79]
	v_mfma_f32_16x16x32_bf16 v[72:75], v[170:173], v[210:213], v[72:75]
	v_mfma_f32_16x16x32_bf16 v[64:67], v[150:153], v[218:221], v[64:67]
	v_mfma_f32_16x16x32_bf16 v[56:59], v[170:173], v[218:221], v[56:59]
	s_setprio 0
	s_setprio 1
	v_mfma_f32_16x16x32_bf16 v[28:31], v[174:177], v[190:193], v[28:31]
	v_mfma_f32_16x16x32_bf16 v[24:27], v[182:185], v[190:193], v[24:27]
	v_mfma_f32_16x16x32_bf16 v[20:23], v[174:177], v[198:201], v[20:23]
	v_mfma_f32_16x16x32_bf16 v[16:19], v[182:185], v[198:201], v[16:19]
	v_mfma_f32_16x16x32_bf16 v[12:15], v[174:177], v[206:209], v[12:15]
	v_mfma_f32_16x16x32_bf16 v[8:11], v[182:185], v[206:209], v[8:11]
	v_mfma_f32_16x16x32_bf16 v[4:7], v[174:177], v[214:217], v[4:7]
	v_mfma_f32_16x16x32_bf16 v[0:3], v[182:185], v[214:217], v[0:3]
	v_mfma_f32_16x16x32_bf16 v[28:31], v[178:181], v[194:197], v[28:31]
	v_mfma_f32_16x16x32_bf16 v[24:27], v[186:189], v[194:197], v[24:27]
	v_mfma_f32_16x16x32_bf16 v[20:23], v[178:181], v[202:205], v[20:23]
	v_mfma_f32_16x16x32_bf16 v[16:19], v[186:189], v[202:205], v[16:19]
	v_mfma_f32_16x16x32_bf16 v[12:15], v[178:181], v[210:213], v[12:15]
	v_mfma_f32_16x16x32_bf16 v[8:11], v[186:189], v[210:213], v[8:11]
	v_mfma_f32_16x16x32_bf16 v[4:7], v[178:181], v[218:221], v[4:7]
	v_mfma_f32_16x16x32_bf16 v[0:3], v[186:189], v[218:221], v[0:3]
	s_setprio 0
	s_barrier
	s_add_i32 s59, 0, 0x18000
	s_add_i32 s60, 0, 0x1c000
	ds_read_b128 v[146:149], v222
	ds_read_b128 v[150:153], v222 offset:1024
	ds_read_b128 v[154:157], v222 offset:2048
	ds_read_b128 v[170:173], v222 offset:3072
	ds_read_b128 v[174:177], v223
	ds_read_b128 v[178:181], v223 offset:1024
	ds_read_b128 v[182:185], v223 offset:2048
	ds_read_b128 v[186:189], v223 offset:3072
	s_add_u32 s38, s38, 0x160000
	s_addc_u32 s39, s39, 0
	s_mov_b32 m0, s19
	ds_read_b128 v[190:193], v169 offset:32768
	ds_read_b128 v[194:197], v169 offset:33792
	ds_read_b128 v[198:201], v169 offset:34816
	ds_read_b128 v[202:205], v169 offset:35840
	ds_read_b128 v[206:209], v169 offset:36864
	ds_read_b128 v[210:213], v169 offset:37888
	ds_read_b128 v[214:217], v169 offset:38912
	ds_read_b128 v[218:221], v169 offset:39936
	global_load_lds_dwordx4 v128, s[38:39]
	s_mov_b32 m0, s20
	s_nop 0
	global_load_lds_dwordx4 v132, s[38:39]
	s_waitcnt vmcnt(8)
	s_waitcnt lgkmcnt(0)
	s_barrier
; #define PG8_STAGE(bufoff, gbase, voff) do { _Pragma("unroll") for (int _i = 0; _i < 2; ++_i) \
;         __builtin_amdgcn_global_load_lds((const unsigned*)((const char*)(gbase) + (voff)[_i]), (LAS unsigned*)(lds + (bufoff) + ldsw + _i * 8192), 16, 0, 0); } while (0)
; #define PG8_LDA(dst, b, h) do { _Pragma("unroll") for (int m = 0; m < 4; ++m) _Pragma("unroll") for (int k = 0; k < 2; ++k) dst[m][k] = *(const LAS bf16x8*)(lds + PG8_SA(b, h) + aoff + m * 2048 + k * 1024); } while (0)
; #define PG8_MMA(ai, bj, At, Bt) do { __builtin_amdgcn_s_setprio(1); _Pragma("unroll") for (int m = 0; m < 4; ++m) _Pragma("unroll") for (int n = 0; n < 2; ++n) _Pragma("unroll") for (int k = 0; k < 2; ++k) \
;         acc[ai][bj][m][n] = __builtin_amdgcn_mfma_f32_16x16x32_bf16(Bt[n][k], At[m][k], acc[ai][bj][m][n], 0, 0, 0); __builtin_amdgcn_s_setprio(0); } while (0)
; #define PG8_WAIT_V(n) asm volatile("s_waitcnt vmcnt(" #n ")" ::: "memory")
; #define PG8_WAIT_L(n) asm volatile("s_waitcnt lgkmcnt(" #n ")" ::: "memory")
; #define PG8_BAR __builtin_amdgcn_s_barrier()
; #define PG8_SCHED __builtin_amdgcn_sched_barrier(0)
; __device__ __forceinline__ void gemm_phase(LAS unsigned char* lds, const Params& p, const bf16_t* gA, const bf16_t* gBt, const int gM, const int gN, const int gK, const int epi, const int perm, bf16_t* const Hp, const int goff, const float coef) {
;     ...
;             PG8_WAIT_V(8); PG8_WAIT_L(0); PG8_BAR; PG8_MMA(0, 0, At, B0); PG8_MMA(0, 1, At, B1); PG8_BAR; PG8_SCHED;
;             PG8_LDA(At, 1, 1); PG8_STAGE(PG8_SB(1, 0), b3, voffB); PG8_STAGE(PG8_SB(1, 1), b3 + hstep, voffB); PG8_STAGE(PG8_SA(1, 0), a3, voffA);
;             PG8_WAIT_V(8); PG8_WAIT_L(0); PG8_BAR; PG8_MMA(1, 0, At, B0); PG8_MMA(1, 1, At, B1); PG8_BAR; PG8_SCHED;
;         }
	s_setprio 1
	s_waitcnt lgkmcnt(0)
	v_mfma_f32_16x16x32_bf16 v[124:127], v[146:149], v[190:193], v[124:127]
	v_mfma_f32_16x16x32_bf16 v[120:123], v[154:157], v[190:193], v[120:123]
	v_mfma_f32_16x16x32_bf16 v[116:119], v[146:149], v[198:201], v[116:119]
	v_mfma_f32_16x16x32_bf16 v[112:115], v[154:157], v[198:201], v[112:115]
	v_mfma_f32_16x16x32_bf16 v[108:111], v[146:149], v[206:209], v[108:111]
	v_mfma_f32_16x16x32_bf16 v[104:107], v[154:157], v[206:209], v[104:107]
	v_mfma_f32_16x16x32_bf16 v[100:103], v[146:149], v[214:217], v[100:103]
	v_mfma_f32_16x16x32_bf16 v[96:99], v[154:157], v[214:217], v[96:99]
	v_mfma_f32_16x16x32_bf16 v[124:127], v[150:153], v[194:197], v[124:127]
	v_mfma_f32_16x16x32_bf16 v[120:123], v[170:173], v[194:197], v[120:123]
	v_mfma_f32_16x16x32_bf16 v[116:119], v[150:153], v[202:205], v[116:119]
	v_mfma_f32_16x16x32_bf16 v[112:115], v[170:173], v[202:205], v[112:115]
	v_mfma_f32_16x16x32_bf16 v[108:111], v[150:153], v[210:213], v[108:111]
	v_mfma_f32_16x16x32_bf16 v[104:107], v[170:173], v[210:213], v[104:107]
	v_mfma_f32_16x16x32_bf16 v[100:103], v[150:153], v[218:221], v[100:103]
	v_mfma_f32_16x16x32_bf16 v[96:99], v[170:173], v[218:221], v[96:99]
	s_setprio 0
	s_setprio 1
	v_mfma_f32_16x16x32_bf16 v[68:71], v[174:177], v[190:193], v[68:71]
	v_mfma_f32_16x16x32_bf16 v[60:63], v[182:185], v[190:193], v[60:63]
	v_mfma_f32_16x16x32_bf16 v[52:55], v[174:177], v[198:201], v[52:55]
	v_mfma_f32_16x16x32_bf16 v[48:51], v[182:185], v[198:201], v[48:51]
	v_mfma_f32_16x16x32_bf16 v[44:47], v[174:177], v[206:209], v[44:47]
	v_mfma_f32_16x16x32_bf16 v[40:43], v[182:185], v[206:209], v[40:43]
	v_mfma_f32_16x16x32_bf16 v[36:39], v[174:177], v[214:217], v[36:39]
	v_mfma_f32_16x16x32_bf16 v[32:35], v[182:185], v[214:217], v[32:35]
	v_mfma_f32_16x16x32_bf16 v[68:71], v[178:181], v[194:197], v[68:71]
	v_mfma_f32_16x16x32_bf16 v[60:63], v[186:189], v[194:197], v[60:63]
	v_mfma_f32_16x16x32_bf16 v[52:55], v[178:181], v[202:205], v[52:55]
	v_mfma_f32_16x16x32_bf16 v[48:51], v[186:189], v[202:205], v[48:51]
	v_mfma_f32_16x16x32_bf16 v[44:47], v[178:181], v[210:213], v[44:47]
	v_mfma_f32_16x16x32_bf16 v[40:43], v[186:189], v[210:213], v[40:43]
	v_mfma_f32_16x16x32_bf16 v[36:39], v[178:181], v[218:221], v[36:39]
	v_mfma_f32_16x16x32_bf16 v[32:35], v[186:189], v[218:221], v[32:35]
	s_setprio 0
	s_barrier
	s_mov_b64 s[98:99], s[38:39]
	s_add_i32 s38, s59, s16
	s_mov_b32 m0, s38
	ds_read_b128 v[190:193], v169 offset:49152
	ds_read_b128 v[194:197], v169 offset:50176
	ds_read_b128 v[198:201], v169 offset:51200
	ds_read_b128 v[202:205], v169 offset:52224
	ds_read_b128 v[206:209], v169 offset:53248
	ds_read_b128 v[210:213], v169 offset:54272
	ds_read_b128 v[214:217], v169 offset:55296
	ds_read_b128 v[218:221], v169 offset:56320
	s_add_u32 s100, s34, 0x80
	s_addc_u32 s101, s35, 0
	global_load_lds_dwordx4 v130, s[100:101]
	s_add_i32 m0, s38, 0x2000
	s_add_u32 s34, s34, 0x160080
	s_addc_u32 s35, s35, 0
	s_add_i32 s38, s60, s16
	global_load_lds_dwordx4 v134, s[100:101]
	s_mov_b32 m0, s38
	s_nop 0
	global_load_lds_dwordx4 v130, s[34:35]
	s_add_i32 m0, s38, 0x2000
	s_nop 0
	global_load_lds_dwordx4 v134, s[34:35]
	s_mov_b32 m0, s23
	s_nop 0
	s_add_u32 s100, s98, 0xffea0080
	s_addc_u32 s101, s99, -1
	global_load_lds_dwordx4 v128, s[100:101]
	s_mov_b32 m0, s33
	s_nop 0
	global_load_lds_dwordx4 v132, s[100:101]
	s_waitcnt vmcnt(8)
	s_waitcnt lgkmcnt(0)
	s_barrier
	s_setprio 1
	s_waitcnt lgkmcnt(0)
	v_mfma_f32_16x16x32_bf16 v[92:95], v[146:149], v[190:193], v[92:95]
	v_mfma_f32_16x16x32_bf16 v[88:91], v[154:157], v[190:193], v[88:91]
	v_mfma_f32_16x16x32_bf16 v[84:87], v[146:149], v[198:201], v[84:87]
	v_mfma_f32_16x16x32_bf16 v[80:83], v[154:157], v[198:201], v[80:83]
	v_mfma_f32_16x16x32_bf16 v[76:79], v[146:149], v[206:209], v[76:79]
	v_mfma_f32_16x16x32_bf16 v[72:75], v[154:157], v[206:209], v[72:75]
	v_mfma_f32_16x16x32_bf16 v[64:67], v[146:149], v[214:217], v[64:67]
	v_mfma_f32_16x16x32_bf16 v[56:59], v[154:157], v[214:217], v[56:59]
	v_mfma_f32_16x16x32_bf16 v[92:95], v[150:153], v[194:197], v[92:95]
	v_mfma_f32_16x16x32_bf16 v[88:91], v[170:173], v[194:197], v[88:91]
	v_mfma_f32_16x16x32_bf16 v[84:87], v[150:153], v[202:205], v[84:87]
	v_mfma_f32_16x16x32_bf16 v[80:83], v[170:173], v[202:205], v[80:83]
	v_mfma_f32_16x16x32_bf16 v[76:79], v[150:153], v[210:213], v[76:79]
	v_mfma_f32_16x16x32_bf16 v[72:75], v[170:173], v[210:213], v[72:75]
	v_mfma_f32_16x16x32_bf16 v[64:67], v[150:153], v[218:221], v[64:67]
	v_mfma_f32_16x16x32_bf16 v[56:59], v[170:173], v[218:221], v[56:59]
	s_setprio 0
	s_setprio 1
	v_mfma_f32_16x16x32_bf16 v[28:31], v[174:177], v[190:193], v[28:31]
	v_mfma_f32_16x16x32_bf16 v[24:27], v[182:185], v[190:193], v[24:27]
	v_mfma_f32_16x16x32_bf16 v[20:23], v[174:177], v[198:201], v[20:23]
	v_mfma_f32_16x16x32_bf16 v[16:19], v[182:185], v[198:201], v[16:19]
	v_mfma_f32_16x16x32_bf16 v[12:15], v[174:177], v[206:209], v[12:15]
	v_mfma_f32_16x16x32_bf16 v[8:11], v[182:185], v[206:209], v[8:11]
	v_mfma_f32_16x16x32_bf16 v[4:7], v[174:177], v[214:217], v[4:7]
	v_mfma_f32_16x16x32_bf16 v[0:3], v[182:185], v[214:217], v[0:3]
	v_mfma_f32_16x16x32_bf16 v[28:31], v[178:181], v[194:197], v[28:31]
	v_mfma_f32_16x16x32_bf16 v[24:27], v[186:189], v[194:197], v[24:27]
	v_mfma_f32_16x16x32_bf16 v[20:23], v[178:181], v[202:205], v[20:23]
	v_mfma_f32_16x16x32_bf16 v[16:19], v[186:189], v[202:205], v[16:19]
	v_mfma_f32_16x16x32_bf16 v[12:15], v[178:181], v[210:213], v[12:15]
	v_mfma_f32_16x16x32_bf16 v[8:11], v[186:189], v[210:213], v[8:11]
	v_mfma_f32_16x16x32_bf16 v[4:7], v[178:181], v[218:221], v[4:7]
	v_mfma_f32_16x16x32_bf16 v[0:3], v[186:189], v[218:221], v[0:3]
	s_setprio 0
	s_barrier
	s_add_u32 s30, s30, 0x100
	s_addc_u32 s31, s31, 0
	s_add_u32 s56, s56, 0x100
	s_addc_u32 s57, s57, 0
	s_cmp_ge_u32 s58, s54
	s_mov_b64 s[98:99], s[34:35]
	s_mov_b32 s34, s58
	s_cbranch_scc0 .LBB0_264
	s_and_b64 vcc, exec, s[24:25]
	s_cbranch_vccz .LBB0_267
	s_barrier

; #define PG8_STAGE(bufoff, gbase, voff) do { _Pragma("unroll") for (int _i = 0; _i < 2; ++_i) \
;         __builtin_amdgcn_global_load_lds((const unsigned*)((const char*)(gbase) + (voff)[_i]), (LAS unsigned*)(lds + (bufoff) + ldsw + _i * 8192), 16, 0, 0); } while (0)
; #define PG8_LDA(dst, b, h) do { _Pragma("unroll") for (int m = 0; m < 4; ++m) _Pragma("unroll") for (int k = 0; k < 2; ++k) dst[m][k] = *(const LAS bf16x8*)(lds + PG8_SA(b, h) + aoff + m * 2048 + k * 1024); } while (0)
; #define PG8_LDB(dst, b, h) do { _Pragma("unroll") for (int n = 0; n < 2; ++n) _Pragma("unroll") for (int k = 0; k < 2; ++k) dst[n][k] = *(const LAS bf16x8*)(lds + PG8_SB(b, h) + boff + n * 2048 + k * 1024); } while (0)
; #define PG8_MMA(ai, bj, At, Bt) do { __builtin_amdgcn_s_setprio(1); _Pragma("unroll") for (int m = 0; m < 4; ++m) _Pragma("unroll") for (int n = 0; n < 2; ++n) _Pragma("unroll") for (int k = 0; k < 2; ++k) \
;         acc[ai][bj][m][n] = __builtin_amdgcn_mfma_f32_16x16x32_bf16(Bt[n][k], At[m][k], acc[ai][bj][m][n], 0, 0, 0); __builtin_amdgcn_s_setprio(0); } while (0)
; #define PG8_WAIT_V(n) asm volatile("s_waitcnt vmcnt(" #n ")" ::: "memory")
; #define PG8_BAR __builtin_amdgcn_s_barrier()
; __device__ __forceinline__ void gemm_phase(LAS unsigned char* lds, const Params& p, const bf16_t* gA, const bf16_t* gBt, const int gM, const int gN, const int gK, const int epi, const int perm, bf16_t* const Hp, const int goff, const float coef) {
;     ...
;         const bool has_next = S.next(ui + 1, nxt);
;         const char* nA = has_next ? (const char*)gA + (size_t)nxt.pm * tstep + (nxt.ks > 0 ? nxt.ks * ksl : 0) : cA; const char* nB = has_next ? (const char*)gBt + (size_t)nxt.pn * tstep + (nxt.ks > 0 ? nxt.ks * ksl : 0) : cB;
;         const int nt = cur.ks >= 0 ? ntf / 4 : ntf;
;         for (int t = 0; t < nt; t += 2) {
;             const bool last = (t == nt - 2);
;             const char* a1 = cA + (size_t)(t + 1) * kstep;
;             const char* a2 = last ? nA : cA + (size_t)(t + 2) * kstep; const char* b2 = last ? nB : cB + (size_t)(t + 2) * kstep;
;             const char* a3 = a2 + kstep; const char* b3 = b2 + kstep;
;             PG8_LDB(B0, 0, 0); PG8_LDB(B1, 0, 1); PG8_SCHED; PG8_LDA(At, 0, 0); PG8_STAGE(PG8_SA(1, 1), a1 + hstep, voffA);
;             PG8_WAIT_V(8); PG8_WAIT_L(0); PG8_BAR; PG8_MMA(0, 0, At, B0); PG8_MMA(0, 1, At, B1); PG8_BAR; PG8_SCHED;
.LBB0_435:
	s_ashr_i32 s35, s34, 31
	s_lshl_b64 s[14:15], s[34:35], 20
	s_add_u32 s16, s3, s14
	s_addc_u32 s17, s27, s15
	s_lshl_b64 s[14:15], s[6:7], 10
	s_cmp_gt_i32 s6, 0
	s_cselect_b32 s33, s14, 0
	s_cselect_b32 s23, s15, 0
	s_add_u32 s40, s16, s33
	s_addc_u32 s41, s17, s23
	s_and_b64 s[14:15], s[38:39], exec
	s_cselect_b32 s14, s41, s1
	s_cselect_b32 s15, s40, s0
	s_ashr_i32 s37, s36, 31
	s_lshl_b64 s[16:17], s[36:37], 20
	s_add_u32 s16, s29, s16
	s_addc_u32 s17, s31, s17
	s_add_u32 s42, s16, s33
	s_addc_u32 s43, s17, s23
	s_and_b64 s[16:17], s[38:39], exec
	s_cselect_b32 s16, s43, s5
	s_cselect_b32 s17, s42, s4
	s_cmp_gt_i32 s22, -1
	s_cselect_b32 s22, 8, 32
	s_add_i32 s23, s22, -2
	s_add_u32 s0, s0, 0x80080
	s_addc_u32 s1, s1, 0
	s_add_u32 s33, s4, 0x100
	v_mov_b32_e32 v0, 0
	s_mov_b32 s45, 0
	s_addc_u32 s35, s5, 0
	v_mov_b32_e32 v1, v0
	v_mov_b32_e32 v2, v0
	v_mov_b32_e32 v3, v0
	v_mov_b32_e32 v4, v0
	v_mov_b32_e32 v5, v0
	v_mov_b32_e32 v6, v0
	v_mov_b32_e32 v7, v0
	v_mov_b32_e32 v16, v0
	v_mov_b32_e32 v17, v0
	v_mov_b32_e32 v18, v0
	v_mov_b32_e32 v19, v0
	v_mov_b32_e32 v20, v0
	v_mov_b32_e32 v21, v0
	v_mov_b32_e32 v22, v0
	v_mov_b32_e32 v23, v0
	v_mov_b32_e32 v32, v0
	v_mov_b32_e32 v33, v0
	v_mov_b32_e32 v34, v0
	v_mov_b32_e32 v35, v0
	v_mov_b32_e32 v36, v0
	v_mov_b32_e32 v37, v0
	v_mov_b32_e32 v38, v0
	v_mov_b32_e32 v39, v0
	v_mov_b32_e32 v48, v0
	v_mov_b32_e32 v49, v0
	v_mov_b32_e32 v50, v0
	v_mov_b32_e32 v51, v0
	v_mov_b32_e32 v52, v0
	v_mov_b32_e32 v53, v0
	v_mov_b32_e32 v54, v0
	v_mov_b32_e32 v55, v0
	v_mov_b32_e32 v8, v0
	v_mov_b32_e32 v9, v0
	v_mov_b32_e32 v10, v0
	v_mov_b32_e32 v11, v0
	v_mov_b32_e32 v12, v0
	v_mov_b32_e32 v13, v0
	v_mov_b32_e32 v14, v0
	v_mov_b32_e32 v15, v0
	v_mov_b32_e32 v24, v0
	v_mov_b32_e32 v25, v0
	v_mov_b32_e32 v26, v0
	v_mov_b32_e32 v27, v0
	v_mov_b32_e32 v28, v0
	v_mov_b32_e32 v29, v0
	v_mov_b32_e32 v30, v0
	v_mov_b32_e32 v31, v0
	v_mov_b32_e32 v40, v0
	v_mov_b32_e32 v41, v0
	v_mov_b32_e32 v42, v0
	v_mov_b32_e32 v43, v0
	v_mov_b32_e32 v44, v0
	v_mov_b32_e32 v45, v0
	v_mov_b32_e32 v46, v0
	v_mov_b32_e32 v47, v0
	v_mov_b32_e32 v56, v0
	v_mov_b32_e32 v57, v0
	v_mov_b32_e32 v58, v0
	v_mov_b32_e32 v59, v0
	v_mov_b32_e32 v60, v0
	v_mov_b32_e32 v61, v0
	v_mov_b32_e32 v62, v0
	v_mov_b32_e32 v63, v0
	v_mov_b32_e32 v64, v0
	v_mov_b32_e32 v65, v0
	v_mov_b32_e32 v66, v0
	v_mov_b32_e32 v67, v0
	v_mov_b32_e32 v68, v0
	v_mov_b32_e32 v69, v0
	v_mov_b32_e32 v70, v0
	v_mov_b32_e32 v71, v0
	v_mov_b32_e32 v80, v0
	v_mov_b32_e32 v81, v0
	v_mov_b32_e32 v82, v0
	v_mov_b32_e32 v83, v0
	v_mov_b32_e32 v84, v0
	v_mov_b32_e32 v85, v0
	v_mov_b32_e32 v86, v0
	v_mov_b32_e32 v87, v0
	v_mov_b32_e32 v96, v0
	v_mov_b32_e32 v97, v0
	v_mov_b32_e32 v98, v0
	v_mov_b32_e32 v99, v0
	v_mov_b32_e32 v100, v0
	v_mov_b32_e32 v101, v0
	v_mov_b32_e32 v102, v0
	v_mov_b32_e32 v103, v0
	v_mov_b32_e32 v112, v0
	v_mov_b32_e32 v113, v0
	v_mov_b32_e32 v114, v0
	v_mov_b32_e32 v115, v0
	v_mov_b32_e32 v116, v0
	v_mov_b32_e32 v117, v0
	v_mov_b32_e32 v118, v0
	v_mov_b32_e32 v119, v0
	v_mov_b32_e32 v72, v0
	v_mov_b32_e32 v73, v0
	v_mov_b32_e32 v74, v0
	v_mov_b32_e32 v75, v0
	v_mov_b32_e32 v76, v0
	v_mov_b32_e32 v77, v0
	v_mov_b32_e32 v78, v0
	v_mov_b32_e32 v79, v0
	v_mov_b32_e32 v88, v0
	v_mov_b32_e32 v89, v0
	v_mov_b32_e32 v90, v0
	v_mov_b32_e32 v91, v0
	v_mov_b32_e32 v92, v0
	v_mov_b32_e32 v93, v0
	v_mov_b32_e32 v94, v0
	v_mov_b32_e32 v95, v0
	v_mov_b32_e32 v104, v0
	v_mov_b32_e32 v105, v0
	v_mov_b32_e32 v106, v0
	v_mov_b32_e32 v107, v0
	v_mov_b32_e32 v108, v0
	v_mov_b32_e32 v109, v0
	v_mov_b32_e32 v110, v0
	v_mov_b32_e32 v111, v0
	v_mov_b32_e32 v120, v0
	v_mov_b32_e32 v121, v0
	v_mov_b32_e32 v122, v0
	v_mov_b32_e32 v123, v0
	v_mov_b32_e32 v124, v0
	v_mov_b32_e32 v125, v0
	v_mov_b32_e32 v126, v0
	v_mov_b32_e32 v127, v0
	v_add_u32_e32 v168, 0x18000, v171
	v_add_u32_e32 v169, 0x1c000, v171
.LBB0_436:
	ds_read_b128 v[128:131], v180
	ds_read_b128 v[132:135], v180 offset:1024
	ds_read_b128 v[136:139], v180 offset:2048
	ds_read_b128 v[184:187], v180 offset:3072
	ds_read_b128 v[188:191], v181
	ds_read_b128 v[192:195], v181 offset:1024
	ds_read_b128 v[196:199], v181 offset:2048
	ds_read_b128 v[200:203], v181 offset:3072
	s_add_i32 s37, s45, 2
	s_add_u32 s4, s0, 0xfff80080
	s_addc_u32 s5, s1, -1
	s_cmp_eq_u32 s23, s45
	s_cselect_b32 s49, s14, s5
	s_cselect_b32 s48, s15, s4
	s_cselect_b32 s5, s16, s35
	s_cselect_b32 s4, s17, s33
	s_add_i32 m0, s47, 0xc000
	ds_read_b128 v[204:207], v182
	ds_read_b128 v[208:211], v182 offset:1024
	ds_read_b128 v[212:215], v182 offset:2048
	ds_read_b128 v[216:219], v182 offset:3072
	ds_read_b128 v[220:223], v182 offset:4096
	ds_read_b128 v[224:227], v182 offset:5120
	ds_read_b128 v[228:231], v182 offset:6144
	ds_read_b128 v[232:235], v182 offset:7168
	global_load_lds_dwordx4 v160, s[0:1]
	s_add_i32 m0, s47, 0xe000
	s_nop 0
	global_load_lds_dwordx4 v162, s[0:1]
	s_waitcnt vmcnt(8)
	s_waitcnt lgkmcnt(0)
	s_barrier
; #define PG8_STAGE(bufoff, gbase, voff) do { _Pragma("unroll") for (int _i = 0; _i < 2; ++_i) \
;         __builtin_amdgcn_global_load_lds((const unsigned*)((const char*)(gbase) + (voff)[_i]), (LAS unsigned*)(lds + (bufoff) + ldsw + _i * 8192), 16, 0, 0); } while (0)
; #define PG8_LDA(dst, b, h) do { _Pragma("unroll") for (int m = 0; m < 4; ++m) _Pragma("unroll") for (int k = 0; k < 2; ++k) dst[m][k] = *(const LAS bf16x8*)(lds + PG8_SA(b, h) + aoff + m * 2048 + k * 1024); } while (0)
; #define PG8_MMA(ai, bj, At, Bt) do { __builtin_amdgcn_s_setprio(1); _Pragma("unroll") for (int m = 0; m < 4; ++m) _Pragma("unroll") for (int n = 0; n < 2; ++n) _Pragma("unroll") for (int k = 0; k < 2; ++k) \
;         acc[ai][bj][m][n] = __builtin_amdgcn_mfma_f32_16x16x32_bf16(Bt[n][k], At[m][k], acc[ai][bj][m][n], 0, 0, 0); __builtin_amdgcn_s_setprio(0); } while (0)
; #define PG8_WAIT_V(n) asm volatile("s_waitcnt vmcnt(" #n ")" ::: "memory")
; #define PG8_WAIT_L(n) asm volatile("s_waitcnt lgkmcnt(" #n ")" ::: "memory")
; #define PG8_BAR __builtin_amdgcn_s_barrier()
; #define PG8_SCHED __builtin_amdgcn_sched_barrier(0)
; __device__ __forceinline__ void gemm_phase(LAS unsigned char* lds, const Params& p, const bf16_t* gA, const bf16_t* gBt, const int gM, const int gN, const int gK, const int epi, const int perm, bf16_t* const Hp, const int goff, const float coef) {
;     ...
;             PG8_WAIT_V(8); PG8_WAIT_L(0); PG8_BAR; PG8_MMA(0, 0, At, B0); PG8_MMA(0, 1, At, B1); PG8_BAR; PG8_SCHED;
;             PG8_LDA(At, 0, 1); PG8_STAGE(PG8_SB(0, 0), b2, voffB); PG8_STAGE(PG8_SB(0, 1), b2 + hstep, voffB); PG8_STAGE(PG8_SA(0, 0), a2, voffA);
;             PG8_WAIT_V(8); PG8_WAIT_L(0); PG8_BAR; PG8_MMA(1, 0, At, B0); PG8_MMA(1, 1, At, B1); PG8_BAR; PG8_SCHED;
	s_setprio 1
	s_waitcnt lgkmcnt(0)
	v_mfma_f32_16x16x32_bf16 v[124:127], v[128:131], v[204:207], v[124:127]
	v_mfma_f32_16x16x32_bf16 v[120:123], v[136:139], v[204:207], v[120:123]
	v_mfma_f32_16x16x32_bf16 v[108:111], v[128:131], v[212:215], v[108:111]
	v_mfma_f32_16x16x32_bf16 v[104:107], v[136:139], v[212:215], v[104:107]
	v_mfma_f32_16x16x32_bf16 v[92:95], v[128:131], v[220:223], v[92:95]
	v_mfma_f32_16x16x32_bf16 v[88:91], v[136:139], v[220:223], v[88:91]
	v_mfma_f32_16x16x32_bf16 v[76:79], v[128:131], v[228:231], v[76:79]
	v_mfma_f32_16x16x32_bf16 v[72:75], v[136:139], v[228:231], v[72:75]
	v_mfma_f32_16x16x32_bf16 v[124:127], v[132:135], v[208:211], v[124:127]
	v_mfma_f32_16x16x32_bf16 v[120:123], v[184:187], v[208:211], v[120:123]
	v_mfma_f32_16x16x32_bf16 v[108:111], v[132:135], v[216:219], v[108:111]
	v_mfma_f32_16x16x32_bf16 v[104:107], v[184:187], v[216:219], v[104:107]
	v_mfma_f32_16x16x32_bf16 v[92:95], v[132:135], v[224:227], v[92:95]
	v_mfma_f32_16x16x32_bf16 v[88:91], v[184:187], v[224:227], v[88:91]
	v_mfma_f32_16x16x32_bf16 v[76:79], v[132:135], v[232:235], v[76:79]
	v_mfma_f32_16x16x32_bf16 v[72:75], v[184:187], v[232:235], v[72:75]
	s_setprio 0
	s_setprio 1
	v_mfma_f32_16x16x32_bf16 v[116:119], v[188:191], v[204:207], v[116:119]
	v_mfma_f32_16x16x32_bf16 v[112:115], v[196:199], v[204:207], v[112:115]
	v_mfma_f32_16x16x32_bf16 v[100:103], v[188:191], v[212:215], v[100:103]
	v_mfma_f32_16x16x32_bf16 v[96:99], v[196:199], v[212:215], v[96:99]
	v_mfma_f32_16x16x32_bf16 v[84:87], v[188:191], v[220:223], v[84:87]
	v_mfma_f32_16x16x32_bf16 v[80:83], v[196:199], v[220:223], v[80:83]
	v_mfma_f32_16x16x32_bf16 v[68:71], v[188:191], v[228:231], v[68:71]
	v_mfma_f32_16x16x32_bf16 v[64:67], v[196:199], v[228:231], v[64:67]
	v_mfma_f32_16x16x32_bf16 v[116:119], v[192:195], v[208:211], v[116:119]
	v_mfma_f32_16x16x32_bf16 v[112:115], v[200:203], v[208:211], v[112:115]
	v_mfma_f32_16x16x32_bf16 v[100:103], v[192:195], v[216:219], v[100:103]
	v_mfma_f32_16x16x32_bf16 v[96:99], v[200:203], v[216:219], v[96:99]
	v_mfma_f32_16x16x32_bf16 v[84:87], v[192:195], v[224:227], v[84:87]
	v_mfma_f32_16x16x32_bf16 v[80:83], v[200:203], v[224:227], v[80:83]
	v_mfma_f32_16x16x32_bf16 v[68:71], v[192:195], v[232:235], v[68:71]
	v_mfma_f32_16x16x32_bf16 v[64:67], v[200:203], v[232:235], v[64:67]
	s_setprio 0
	s_barrier
	s_add_i32 s45, s19, s52
	s_mov_b32 m0, s45
	ds_read_b128 v[204:207], v182 offset:16384
	ds_read_b128 v[208:211], v182 offset:17408
	ds_read_b128 v[212:215], v182 offset:18432
	ds_read_b128 v[216:219], v182 offset:19456
	ds_read_b128 v[220:223], v182 offset:20480
	ds_read_b128 v[224:227], v182 offset:21504
	ds_read_b128 v[228:231], v182 offset:22528
	ds_read_b128 v[232:235], v182 offset:23552
	global_load_lds_dwordx4 v144, s[4:5]
	s_add_i32 m0, s45, 0x2000
	s_add_u32 s50, s4, 0x80000
	s_addc_u32 s51, s5, 0
	s_add_i32 s45, s21, s52
	global_load_lds_dwordx4 v148, s[4:5]
	s_mov_b32 m0, s45
	s_nop 0
	global_load_lds_dwordx4 v144, s[50:51]
	s_add_i32 m0, s45, 0x2000
	s_nop 0
	global_load_lds_dwordx4 v148, s[50:51]
	s_mov_b32 m0, s47
	s_nop 0
	global_load_lds_dwordx4 v142, s[48:49]
	s_mov_b32 m0, s53
	s_nop 0
	global_load_lds_dwordx4 v146, s[48:49]
	s_waitcnt vmcnt(8)
	s_waitcnt lgkmcnt(0)
	s_barrier
	s_setprio 1
	s_waitcnt lgkmcnt(0)
	v_mfma_f32_16x16x32_bf16 v[60:63], v[128:131], v[204:207], v[60:63]
	v_mfma_f32_16x16x32_bf16 v[56:59], v[136:139], v[204:207], v[56:59]
	v_mfma_f32_16x16x32_bf16 v[44:47], v[128:131], v[212:215], v[44:47]
	v_mfma_f32_16x16x32_bf16 v[40:43], v[136:139], v[212:215], v[40:43]
	v_mfma_f32_16x16x32_bf16 v[28:31], v[128:131], v[220:223], v[28:31]
	v_mfma_f32_16x16x32_bf16 v[24:27], v[136:139], v[220:223], v[24:27]
	v_mfma_f32_16x16x32_bf16 v[12:15], v[128:131], v[228:231], v[12:15]
	v_mfma_f32_16x16x32_bf16 v[8:11], v[136:139], v[228:231], v[8:11]
	v_mfma_f32_16x16x32_bf16 v[60:63], v[132:135], v[208:211], v[60:63]
	v_mfma_f32_16x16x32_bf16 v[56:59], v[184:187], v[208:211], v[56:59]
	v_mfma_f32_16x16x32_bf16 v[44:47], v[132:135], v[216:219], v[44:47]
	v_mfma_f32_16x16x32_bf16 v[40:43], v[184:187], v[216:219], v[40:43]
	v_mfma_f32_16x16x32_bf16 v[28:31], v[132:135], v[224:227], v[28:31]
	v_mfma_f32_16x16x32_bf16 v[24:27], v[184:187], v[224:227], v[24:27]
	v_mfma_f32_16x16x32_bf16 v[12:15], v[132:135], v[232:235], v[12:15]
	v_mfma_f32_16x16x32_bf16 v[8:11], v[184:187], v[232:235], v[8:11]
	s_setprio 0
	s_setprio 1
	v_mfma_f32_16x16x32_bf16 v[52:55], v[188:191], v[204:207], v[52:55]
	v_mfma_f32_16x16x32_bf16 v[48:51], v[196:199], v[204:207], v[48:51]
	v_mfma_f32_16x16x32_bf16 v[36:39], v[188:191], v[212:215], v[36:39]
	v_mfma_f32_16x16x32_bf16 v[32:35], v[196:199], v[212:215], v[32:35]
	v_mfma_f32_16x16x32_bf16 v[20:23], v[188:191], v[220:223], v[20:23]
	v_mfma_f32_16x16x32_bf16 v[16:19], v[196:199], v[220:223], v[16:19]
	v_mfma_f32_16x16x32_bf16 v[4:7], v[188:191], v[228:231], v[4:7]
	v_mfma_f32_16x16x32_bf16 v[0:3], v[196:199], v[228:231], v[0:3]
	v_mfma_f32_16x16x32_bf16 v[52:55], v[192:195], v[208:211], v[52:55]
	v_mfma_f32_16x16x32_bf16 v[48:51], v[200:203], v[208:211], v[48:51]
	v_mfma_f32_16x16x32_bf16 v[36:39], v[192:195], v[216:219], v[36:39]
	v_mfma_f32_16x16x32_bf16 v[32:35], v[200:203], v[216:219], v[32:35]
	v_mfma_f32_16x16x32_bf16 v[20:23], v[192:195], v[224:227], v[20:23]
	v_mfma_f32_16x16x32_bf16 v[16:19], v[200:203], v[224:227], v[16:19]
	v_mfma_f32_16x16x32_bf16 v[4:7], v[192:195], v[232:235], v[4:7]
	v_mfma_f32_16x16x32_bf16 v[0:3], v[200:203], v[232:235], v[0:3]
	s_setprio 0
	s_barrier
; #define PG8_STAGE(bufoff, gbase, voff) do { _Pragma("unroll") for (int _i = 0; _i < 2; ++_i) \
;         __builtin_amdgcn_global_load_lds((const unsigned*)((const char*)(gbase) + (voff)[_i]), (LAS unsigned*)(lds + (bufoff) + ldsw + _i * 8192), 16, 0, 0); } while (0)
; #define PG8_LDA(dst, b, h) do { _Pragma("unroll") for (int m = 0; m < 4; ++m) _Pragma("unroll") for (int k = 0; k < 2; ++k) dst[m][k] = *(const LAS bf16x8*)(lds + PG8_SA(b, h) + aoff + m * 2048 + k * 1024); } while (0)
; #define PG8_LDB(dst, b, h) do { _Pragma("unroll") for (int n = 0; n < 2; ++n) _Pragma("unroll") for (int k = 0; k < 2; ++k) dst[n][k] = *(const LAS bf16x8*)(lds + PG8_SB(b, h) + boff + n * 2048 + k * 1024); } while (0)
; #define PG8_MMA(ai, bj, At, Bt) do { __builtin_amdgcn_s_setprio(1); _Pragma("unroll") for (int m = 0; m < 4; ++m) _Pragma("unroll") for (int n = 0; n < 2; ++n) _Pragma("unroll") for (int k = 0; k < 2; ++k) \
;         acc[ai][bj][m][n] = __builtin_amdgcn_mfma_f32_16x16x32_bf16(Bt[n][k], At[m][k], acc[ai][bj][m][n], 0, 0, 0); __builtin_amdgcn_s_setprio(0); } while (0)
; #define PG8_WAIT_V(n) asm volatile("s_waitcnt vmcnt(" #n ")" ::: "memory")
; #define PG8_WAIT_L(n) asm volatile("s_waitcnt lgkmcnt(" #n ")" ::: "memory")
; #define PG8_BAR __builtin_amdgcn_s_barrier()
; #define PG8_SCHED __builtin_amdgcn_sched_barrier(0)
; __device__ __forceinline__ void gemm_phase(LAS unsigned char* lds, const Params& p, const bf16_t* gA, const bf16_t* gBt, const int gM, const int gN, const int gK, const int epi, const int perm, bf16_t* const Hp, const int goff, const float coef) {
;     ...
;             PG8_LDB(B0, 1, 0); PG8_LDB(B1, 1, 1); PG8_SCHED; PG8_LDA(At, 1, 0); PG8_STAGE(PG8_SA(0, 1), a2 + hstep, voffA);
;             PG8_WAIT_V(8); PG8_WAIT_L(0); PG8_BAR; PG8_MMA(0, 0, At, B0); PG8_MMA(0, 1, At, B1); PG8_BAR; PG8_SCHED;
;             PG8_LDA(At, 1, 1); PG8_STAGE(PG8_SB(1, 0), b3, voffB); PG8_STAGE(PG8_SB(1, 1), b3 + hstep, voffB); PG8_STAGE(PG8_SA(1, 0), a3, voffA);
;             PG8_WAIT_V(8); PG8_WAIT_L(0); PG8_BAR; PG8_MMA(1, 0, At, B0); PG8_MMA(1, 1, At, B1); PG8_BAR; PG8_SCHED;
;         }
	s_add_i32 s45, 0, 0x18000
	s_add_i32 s50, 0, 0x1c000
	ds_read_b128 v[128:131], v168
	ds_read_b128 v[132:135], v168 offset:1024
	ds_read_b128 v[136:139], v168 offset:2048
	ds_read_b128 v[184:187], v168 offset:3072
	ds_read_b128 v[188:191], v169
	ds_read_b128 v[192:195], v169 offset:1024
	ds_read_b128 v[196:199], v169 offset:2048
	ds_read_b128 v[200:203], v169 offset:3072
	s_add_u32 s48, s48, 0x80000
	s_addc_u32 s49, s49, 0
	s_mov_b32 m0, s54
	ds_read_b128 v[204:207], v182 offset:32768
	ds_read_b128 v[208:211], v182 offset:33792
	ds_read_b128 v[212:215], v182 offset:34816
	ds_read_b128 v[216:219], v182 offset:35840
	ds_read_b128 v[220:223], v182 offset:36864
	ds_read_b128 v[224:227], v182 offset:37888
	ds_read_b128 v[228:231], v182 offset:38912
	ds_read_b128 v[232:235], v182 offset:39936
	global_load_lds_dwordx4 v142, s[48:49]
	s_mov_b32 m0, s55
	s_nop 0
	global_load_lds_dwordx4 v146, s[48:49]
	s_waitcnt vmcnt(8)
	s_waitcnt lgkmcnt(0)
	s_barrier
	s_setprio 1
	s_waitcnt lgkmcnt(0)
	v_mfma_f32_16x16x32_bf16 v[124:127], v[128:131], v[204:207], v[124:127]
	v_mfma_f32_16x16x32_bf16 v[120:123], v[136:139], v[204:207], v[120:123]
	v_mfma_f32_16x16x32_bf16 v[108:111], v[128:131], v[212:215], v[108:111]
	v_mfma_f32_16x16x32_bf16 v[104:107], v[136:139], v[212:215], v[104:107]
	v_mfma_f32_16x16x32_bf16 v[92:95], v[128:131], v[220:223], v[92:95]
	v_mfma_f32_16x16x32_bf16 v[88:91], v[136:139], v[220:223], v[88:91]
	v_mfma_f32_16x16x32_bf16 v[76:79], v[128:131], v[228:231], v[76:79]
	v_mfma_f32_16x16x32_bf16 v[72:75], v[136:139], v[228:231], v[72:75]
	v_mfma_f32_16x16x32_bf16 v[124:127], v[132:135], v[208:211], v[124:127]
	v_mfma_f32_16x16x32_bf16 v[120:123], v[184:187], v[208:211], v[120:123]
	v_mfma_f32_16x16x32_bf16 v[108:111], v[132:135], v[216:219], v[108:111]
	v_mfma_f32_16x16x32_bf16 v[104:107], v[184:187], v[216:219], v[104:107]
	v_mfma_f32_16x16x32_bf16 v[92:95], v[132:135], v[224:227], v[92:95]
	v_mfma_f32_16x16x32_bf16 v[88:91], v[184:187], v[224:227], v[88:91]
	v_mfma_f32_16x16x32_bf16 v[76:79], v[132:135], v[232:235], v[76:79]
	v_mfma_f32_16x16x32_bf16 v[72:75], v[184:187], v[232:235], v[72:75]
	s_setprio 0
	s_setprio 1
	v_mfma_f32_16x16x32_bf16 v[116:119], v[188:191], v[204:207], v[116:119]
	v_mfma_f32_16x16x32_bf16 v[112:115], v[196:199], v[204:207], v[112:115]
	v_mfma_f32_16x16x32_bf16 v[100:103], v[188:191], v[212:215], v[100:103]
	v_mfma_f32_16x16x32_bf16 v[96:99], v[196:199], v[212:215], v[96:99]
	v_mfma_f32_16x16x32_bf16 v[84:87], v[188:191], v[220:223], v[84:87]
	v_mfma_f32_16x16x32_bf16 v[80:83], v[196:199], v[220:223], v[80:83]
	v_mfma_f32_16x16x32_bf16 v[68:71], v[188:191], v[228:231], v[68:71]
	v_mfma_f32_16x16x32_bf16 v[64:67], v[196:199], v[228:231], v[64:67]
	v_mfma_f32_16x16x32_bf16 v[116:119], v[192:195], v[208:211], v[116:119]
	v_mfma_f32_16x16x32_bf16 v[112:115], v[200:203], v[208:211], v[112:115]
	v_mfma_f32_16x16x32_bf16 v[100:103], v[192:195], v[216:219], v[100:103]
	v_mfma_f32_16x16x32_bf16 v[96:99], v[200:203], v[216:219], v[96:99]
	v_mfma_f32_16x16x32_bf16 v[84:87], v[192:195], v[224:227], v[84:87]
	v_mfma_f32_16x16x32_bf16 v[80:83], v[200:203], v[224:227], v[80:83]
	v_mfma_f32_16x16x32_bf16 v[68:71], v[192:195], v[232:235], v[68:71]
	v_mfma_f32_16x16x32_bf16 v[64:67], v[200:203], v[232:235], v[64:67]
	s_setprio 0
	s_barrier
	s_add_i32 s45, s45, s52
	s_mov_b32 m0, s45
	ds_read_b128 v[204:207], v182 offset:49152
	ds_read_b128 v[208:211], v182 offset:50176
	ds_read_b128 v[212:215], v182 offset:51200
	ds_read_b128 v[216:219], v182 offset:52224
	ds_read_b128 v[220:223], v182 offset:53248
	ds_read_b128 v[224:227], v182 offset:54272
	ds_read_b128 v[228:231], v182 offset:55296
	ds_read_b128 v[232:235], v182 offset:56320
	s_add_u32 s98, s4, 0x80
	s_addc_u32 s99, s5, 0
	global_load_lds_dwordx4 v144, s[98:99]
	s_add_i32 m0, s45, 0x2000
	s_add_u32 s4, s4, 0x80080
	s_addc_u32 s5, s5, 0
	s_add_i32 s45, s50, s52
	global_load_lds_dwordx4 v148, s[98:99]
	s_mov_b32 m0, s45
	s_nop 0
	global_load_lds_dwordx4 v144, s[4:5]
	s_add_i32 m0, s45, 0x2000
	s_nop 0
	global_load_lds_dwordx4 v148, s[4:5]
	s_mov_b32 m0, s57
	s_nop 0
	s_add_u32 s100, s48, 0xfff80080
	s_addc_u32 s101, s49, -1
	global_load_lds_dwordx4 v142, s[100:101]
	s_mov_b32 m0, s58
	s_nop 0
	global_load_lds_dwordx4 v146, s[100:101]
	s_waitcnt vmcnt(8)
	s_waitcnt lgkmcnt(0)
	s_barrier
	s_setprio 1
	s_waitcnt lgkmcnt(0)
	v_mfma_f32_16x16x32_bf16 v[60:63], v[128:131], v[204:207], v[60:63]
	v_mfma_f32_16x16x32_bf16 v[56:59], v[136:139], v[204:207], v[56:59]
	v_mfma_f32_16x16x32_bf16 v[44:47], v[128:131], v[212:215], v[44:47]
	v_mfma_f32_16x16x32_bf16 v[40:43], v[136:139], v[212:215], v[40:43]
	v_mfma_f32_16x16x32_bf16 v[28:31], v[128:131], v[220:223], v[28:31]
	v_mfma_f32_16x16x32_bf16 v[24:27], v[136:139], v[220:223], v[24:27]
	v_mfma_f32_16x16x32_bf16 v[12:15], v[128:131], v[228:231], v[12:15]
	v_mfma_f32_16x16x32_bf16 v[8:11], v[136:139], v[228:231], v[8:11]
	v_mfma_f32_16x16x32_bf16 v[60:63], v[132:135], v[208:211], v[60:63]
	v_mfma_f32_16x16x32_bf16 v[56:59], v[184:187], v[208:211], v[56:59]
	v_mfma_f32_16x16x32_bf16 v[44:47], v[132:135], v[216:219], v[44:47]
	v_mfma_f32_16x16x32_bf16 v[40:43], v[184:187], v[216:219], v[40:43]
	v_mfma_f32_16x16x32_bf16 v[28:31], v[132:135], v[224:227], v[28:31]
	v_mfma_f32_16x16x32_bf16 v[24:27], v[184:187], v[224:227], v[24:27]
	v_mfma_f32_16x16x32_bf16 v[12:15], v[132:135], v[232:235], v[12:15]
	v_mfma_f32_16x16x32_bf16 v[8:11], v[184:187], v[232:235], v[8:11]
	s_setprio 0
	s_setprio 1
	v_mfma_f32_16x16x32_bf16 v[52:55], v[188:191], v[204:207], v[52:55]
	v_mfma_f32_16x16x32_bf16 v[48:51], v[196:199], v[204:207], v[48:51]
	v_mfma_f32_16x16x32_bf16 v[36:39], v[188:191], v[212:215], v[36:39]
	v_mfma_f32_16x16x32_bf16 v[32:35], v[196:199], v[212:215], v[32:35]
	v_mfma_f32_16x16x32_bf16 v[20:23], v[188:191], v[220:223], v[20:23]
	v_mfma_f32_16x16x32_bf16 v[16:19], v[196:199], v[220:223], v[16:19]
	v_mfma_f32_16x16x32_bf16 v[4:7], v[188:191], v[228:231], v[4:7]
	v_mfma_f32_16x16x32_bf16 v[0:3], v[196:199], v[228:231], v[0:3]
	v_mfma_f32_16x16x32_bf16 v[52:55], v[192:195], v[208:211], v[52:55]
	v_mfma_f32_16x16x32_bf16 v[48:51], v[200:203], v[208:211], v[48:51]
	v_mfma_f32_16x16x32_bf16 v[36:39], v[192:195], v[216:219], v[36:39]
	v_mfma_f32_16x16x32_bf16 v[32:35], v[200:203], v[216:219], v[32:35]
	v_mfma_f32_16x16x32_bf16 v[20:23], v[192:195], v[224:227], v[20:23]
	v_mfma_f32_16x16x32_bf16 v[16:19], v[200:203], v[224:227], v[16:19]
	v_mfma_f32_16x16x32_bf16 v[4:7], v[192:195], v[232:235], v[4:7]
	v_mfma_f32_16x16x32_bf16 v[0:3], v[200:203], v[232:235], v[0:3]
	s_setprio 0
	s_barrier
	s_add_u32 s0, s0, 0x100
	s_addc_u32 s1, s1, 0
	s_add_u32 s33, s33, 0x100
	s_addc_u32 s35, s35, 0
	s_cmp_ge_u32 s37, s22
	s_mov_b32 s45, s37
	s_cbranch_scc0 .LBB0_436
	s_and_b64 vcc, exec, s[12:13]
	s_cbranch_vccnz .LBB0_440
	s_ashr_i32 s14, s46, 2
	s_cmp_gt_i32 s14, 4
	s_mov_b64 s[0:1], -1
	s_cbranch_scc1 .LBB0_441

; #define PG8_STAGE(bufoff, gbase, voff) do { _Pragma("unroll") for (int _i = 0; _i < 2; ++_i) \
;         __builtin_amdgcn_global_load_lds((const unsigned*)((const char*)(gbase) + (voff)[_i]), (LAS unsigned*)(lds + (bufoff) + ldsw + _i * 8192), 16, 0, 0); } while (0)
; #define PG8_LDA(dst, b, h) do { _Pragma("unroll") for (int m = 0; m < 4; ++m) _Pragma("unroll") for (int k = 0; k < 2; ++k) dst[m][k] = *(const LAS bf16x8*)(lds + PG8_SA(b, h) + aoff + m * 2048 + k * 1024); } while (0)
; #define PG8_LDB(dst, b, h) do { _Pragma("unroll") for (int n = 0; n < 2; ++n) _Pragma("unroll") for (int k = 0; k < 2; ++k) dst[n][k] = *(const LAS bf16x8*)(lds + PG8_SB(b, h) + boff + n * 2048 + k * 1024); } while (0)
; #define PG8_MMA(ai, bj, At, Bt) do { __builtin_amdgcn_s_setprio(1); _Pragma("unroll") for (int m = 0; m < 4; ++m) _Pragma("unroll") for (int n = 0; n < 2; ++n) _Pragma("unroll") for (int k = 0; k < 2; ++k) \
;         acc[ai][bj][m][n] = __builtin_amdgcn_mfma_f32_16x16x32_bf16(Bt[n][k], At[m][k], acc[ai][bj][m][n], 0, 0, 0); __builtin_amdgcn_s_setprio(0); } while (0)
; #define PG8_WAIT_V(n) asm volatile("s_waitcnt vmcnt(" #n ")" ::: "memory")
; #define PG8_BAR __builtin_amdgcn_s_barrier()
; __device__ __forceinline__ void gemm_phase(LAS unsigned char* lds, const Params& p, const bf16_t* gA, const bf16_t* gBt, const int gM, const int gN, const int gK, const int epi, const int perm, bf16_t* const Hp, const int goff, const float coef) {
;     ...
;         const bool has_next = S.next(ui + 1, nxt);
;         const char* nA = has_next ? (const char*)gA + (size_t)nxt.pm * tstep + (nxt.ks > 0 ? nxt.ks * ksl : 0) : cA; const char* nB = has_next ? (const char*)gBt + (size_t)nxt.pn * tstep + (nxt.ks > 0 ? nxt.ks * ksl : 0) : cB;
;         const int nt = cur.ks >= 0 ? ntf / 4 : ntf;
;         for (int t = 0; t < nt; t += 2) {
;             const bool last = (t == nt - 2);
;             const char* a1 = cA + (size_t)(t + 1) * kstep;
;             const char* a2 = last ? nA : cA + (size_t)(t + 2) * kstep; const char* b2 = last ? nB : cB + (size_t)(t + 2) * kstep;
;             const char* a3 = a2 + kstep; const char* b3 = b2 + kstep;
;             PG8_LDB(B0, 0, 0); PG8_LDB(B1, 0, 1); PG8_SCHED; PG8_LDA(At, 0, 0); PG8_STAGE(PG8_SA(1, 1), a1 + hstep, voffA);
;             PG8_WAIT_V(8); PG8_WAIT_L(0); PG8_BAR; PG8_MMA(0, 0, At, B0); PG8_MMA(0, 1, At, B1); PG8_BAR; PG8_SCHED;
.LBB0_1592:
	s_ashr_i32 s13, s12, 31
	s_lshl_b64 s[0:1], s[12:13], 20
	s_add_u32 s13, s3, s0
	s_mov_b32 s19, s5
	s_addc_u32 s15, s33, s1
	s_lshl_b64 s[0:1], s[18:19], 10
	s_cmp_gt_i32 s18, 0
	s_cselect_b32 s22, s0, 0
	s_cselect_b32 s23, s1, 0
	s_add_u32 s20, s13, s22
	s_addc_u32 s21, s15, s23
	s_and_b64 s[0:1], s[16:17], exec
	s_cselect_b32 s13, s21, s27
	s_cselect_b32 s19, s20, s26
	s_ashr_i32 s15, s14, 31
	s_lshl_b64 s[0:1], s[14:15], 20
	s_add_u32 s0, s34, s0
	s_addc_u32 s1, s35, s1
	s_add_u32 s22, s0, s22
	s_addc_u32 s23, s1, s23
	s_and_b64 s[0:1], s[16:17], exec
	s_cselect_b32 s15, s23, s29
	s_cselect_b32 s25, s22, s28
	s_cmp_gt_i32 s4, -1
	s_cselect_b64 s[0:1], -1, 0
	s_and_b64 s[52:53], s[0:1], exec
	s_cselect_b32 s52, 8, 32
	s_add_i32 s53, s52, -2
	s_add_u32 s26, s26, 0x80080
	s_addc_u32 s27, s27, 0
	s_add_u32 s54, s28, 0x100
	v_mov_b32_e32 v0, 0
	s_mov_b32 s30, 0
	s_addc_u32 s55, s29, 0
	v_mov_b32_e32 v1, v0
	v_mov_b32_e32 v2, v0
	v_mov_b32_e32 v3, v0
	v_mov_b32_e32 v4, v0
	v_mov_b32_e32 v5, v0
	v_mov_b32_e32 v6, v0
	v_mov_b32_e32 v7, v0
	v_mov_b32_e32 v8, v0
	v_mov_b32_e32 v9, v0
	v_mov_b32_e32 v10, v0
	v_mov_b32_e32 v11, v0
	v_mov_b32_e32 v12, v0
	v_mov_b32_e32 v13, v0
	v_mov_b32_e32 v14, v0
	v_mov_b32_e32 v15, v0
	v_mov_b32_e32 v16, v0
	v_mov_b32_e32 v17, v0
	v_mov_b32_e32 v18, v0
	v_mov_b32_e32 v19, v0
	v_mov_b32_e32 v20, v0
	v_mov_b32_e32 v21, v0
	v_mov_b32_e32 v22, v0
	v_mov_b32_e32 v23, v0
	v_mov_b32_e32 v24, v0
	v_mov_b32_e32 v25, v0
	v_mov_b32_e32 v26, v0
	v_mov_b32_e32 v27, v0
	v_mov_b32_e32 v28, v0
	v_mov_b32_e32 v29, v0
	v_mov_b32_e32 v30, v0
	v_mov_b32_e32 v31, v0
	v_mov_b32_e32 v56, v0
	v_mov_b32_e32 v57, v0
	v_mov_b32_e32 v58, v0
	v_mov_b32_e32 v59, v0
	v_mov_b32_e32 v60, v0
	v_mov_b32_e32 v61, v0
	v_mov_b32_e32 v62, v0
	v_mov_b32_e32 v63, v0
	v_mov_b32_e32 v72, v0
	v_mov_b32_e32 v73, v0
	v_mov_b32_e32 v74, v0
	v_mov_b32_e32 v75, v0
	v_mov_b32_e32 v76, v0
	v_mov_b32_e32 v77, v0
	v_mov_b32_e32 v78, v0
	v_mov_b32_e32 v79, v0
	v_mov_b32_e32 v80, v0
	v_mov_b32_e32 v81, v0
	v_mov_b32_e32 v82, v0
	v_mov_b32_e32 v83, v0
	v_mov_b32_e32 v84, v0
	v_mov_b32_e32 v85, v0
	v_mov_b32_e32 v86, v0
	v_mov_b32_e32 v87, v0
	v_mov_b32_e32 v88, v0
	v_mov_b32_e32 v89, v0
	v_mov_b32_e32 v90, v0
	v_mov_b32_e32 v91, v0
	v_mov_b32_e32 v92, v0
	v_mov_b32_e32 v93, v0
	v_mov_b32_e32 v94, v0
	v_mov_b32_e32 v95, v0
	v_mov_b32_e32 v32, v0
	v_mov_b32_e32 v33, v0
	v_mov_b32_e32 v34, v0
	v_mov_b32_e32 v35, v0
	v_mov_b32_e32 v36, v0
	v_mov_b32_e32 v37, v0
	v_mov_b32_e32 v38, v0
	v_mov_b32_e32 v39, v0
	v_mov_b32_e32 v40, v0
	v_mov_b32_e32 v41, v0
	v_mov_b32_e32 v42, v0
	v_mov_b32_e32 v43, v0
	v_mov_b32_e32 v44, v0
	v_mov_b32_e32 v45, v0
	v_mov_b32_e32 v46, v0
	v_mov_b32_e32 v47, v0
	v_mov_b32_e32 v48, v0
	v_mov_b32_e32 v49, v0
	v_mov_b32_e32 v50, v0
	v_mov_b32_e32 v51, v0
	v_mov_b32_e32 v52, v0
	v_mov_b32_e32 v53, v0
	v_mov_b32_e32 v54, v0
	v_mov_b32_e32 v55, v0
	v_mov_b32_e32 v64, v0
	v_mov_b32_e32 v65, v0
	v_mov_b32_e32 v66, v0
	v_mov_b32_e32 v67, v0
	v_mov_b32_e32 v68, v0
	v_mov_b32_e32 v69, v0
	v_mov_b32_e32 v70, v0
	v_mov_b32_e32 v71, v0
	v_mov_b32_e32 v96, v0
	v_mov_b32_e32 v97, v0
	v_mov_b32_e32 v98, v0
	v_mov_b32_e32 v99, v0
	v_mov_b32_e32 v100, v0
	v_mov_b32_e32 v101, v0
	v_mov_b32_e32 v102, v0
	v_mov_b32_e32 v103, v0
	v_mov_b32_e32 v104, v0
	v_mov_b32_e32 v105, v0
	v_mov_b32_e32 v106, v0
	v_mov_b32_e32 v107, v0
	v_mov_b32_e32 v108, v0
	v_mov_b32_e32 v109, v0
	v_mov_b32_e32 v110, v0
	v_mov_b32_e32 v111, v0
	v_mov_b32_e32 v112, v0
	v_mov_b32_e32 v113, v0
	v_mov_b32_e32 v114, v0
	v_mov_b32_e32 v115, v0
	v_mov_b32_e32 v116, v0
	v_mov_b32_e32 v117, v0
	v_mov_b32_e32 v118, v0
	v_mov_b32_e32 v119, v0
	v_mov_b32_e32 v120, v0
	v_mov_b32_e32 v121, v0
	v_mov_b32_e32 v122, v0
	v_mov_b32_e32 v123, v0
	v_mov_b32_e32 v124, v0
	v_mov_b32_e32 v125, v0
	v_mov_b32_e32 v126, v0
	v_mov_b32_e32 v127, v0
	v_add_u32_e32 v222, 0x18000, v165
	v_add_u32_e32 v223, 0x1c000, v165
.LBB0_1593:
	ds_read_b128 v[128:131], v174
	ds_read_b128 v[132:135], v174 offset:1024
	ds_read_b128 v[152:155], v174 offset:2048
	ds_read_b128 v[156:159], v174 offset:3072
	ds_read_b128 v[160:163], v175
	ds_read_b128 v[178:181], v175 offset:1024
	ds_read_b128 v[182:185], v175 offset:2048
	ds_read_b128 v[186:189], v175 offset:3072
	s_add_i32 s56, s30, 2
	s_add_u32 s28, s26, 0xfff80080
	s_addc_u32 s29, s27, -1
	s_cmp_eq_u32 s53, s30
	s_cselect_b32 s30, s19, s28
	s_cselect_b32 s31, s13, s29
	s_cselect_b32 s29, s15, s55
	s_cselect_b32 s28, s25, s54
	s_add_i32 m0, s37, 0xc000
	ds_read_b128 v[190:193], v176
	ds_read_b128 v[194:197], v176 offset:1024
	ds_read_b128 v[198:201], v176 offset:2048
	ds_read_b128 v[202:205], v176 offset:3072
	ds_read_b128 v[206:209], v176 offset:4096
	ds_read_b128 v[210:213], v176 offset:5120
	ds_read_b128 v[214:217], v176 offset:6144
	ds_read_b128 v[218:221], v176 offset:7168
	global_load_lds_dwordx4 v146, s[26:27]
	s_add_i32 m0, s37, 0xe000
	s_nop 0
	global_load_lds_dwordx4 v148, s[26:27]
	s_waitcnt vmcnt(8)
	s_waitcnt lgkmcnt(0)
	s_barrier
; #define PG8_STAGE(bufoff, gbase, voff) do { _Pragma("unroll") for (int _i = 0; _i < 2; ++_i) \
;         __builtin_amdgcn_global_load_lds((const unsigned*)((const char*)(gbase) + (voff)[_i]), (LAS unsigned*)(lds + (bufoff) + ldsw + _i * 8192), 16, 0, 0); } while (0)
; #define PG8_LDA(dst, b, h) do { _Pragma("unroll") for (int m = 0; m < 4; ++m) _Pragma("unroll") for (int k = 0; k < 2; ++k) dst[m][k] = *(const LAS bf16x8*)(lds + PG8_SA(b, h) + aoff + m * 2048 + k * 1024); } while (0)
; #define PG8_MMA(ai, bj, At, Bt) do { __builtin_amdgcn_s_setprio(1); _Pragma("unroll") for (int m = 0; m < 4; ++m) _Pragma("unroll") for (int n = 0; n < 2; ++n) _Pragma("unroll") for (int k = 0; k < 2; ++k) \
;         acc[ai][bj][m][n] = __builtin_amdgcn_mfma_f32_16x16x32_bf16(Bt[n][k], At[m][k], acc[ai][bj][m][n], 0, 0, 0); __builtin_amdgcn_s_setprio(0); } while (0)
; #define PG8_WAIT_V(n) asm volatile("s_waitcnt vmcnt(" #n ")" ::: "memory")
; #define PG8_WAIT_L(n) asm volatile("s_waitcnt lgkmcnt(" #n ")" ::: "memory")
; #define PG8_BAR __builtin_amdgcn_s_barrier()
; #define PG8_SCHED __builtin_amdgcn_sched_barrier(0)
; __device__ __forceinline__ void gemm_phase(LAS unsigned char* lds, const Params& p, const bf16_t* gA, const bf16_t* gBt, const int gM, const int gN, const int gK, const int epi, const int perm, bf16_t* const Hp, const int goff, const float coef) {
;     ...
;             PG8_WAIT_V(8); PG8_WAIT_L(0); PG8_BAR; PG8_MMA(0, 0, At, B0); PG8_MMA(0, 1, At, B1); PG8_BAR; PG8_SCHED;
;             PG8_LDA(At, 0, 1); PG8_STAGE(PG8_SB(0, 0), b2, voffB); PG8_STAGE(PG8_SB(0, 1), b2 + hstep, voffB); PG8_STAGE(PG8_SA(0, 0), a2, voffA);
;             PG8_WAIT_V(8); PG8_WAIT_L(0); PG8_BAR; PG8_MMA(1, 0, At, B0); PG8_MMA(1, 1, At, B1); PG8_BAR; PG8_SCHED;
	s_setprio 1
	s_waitcnt lgkmcnt(0)
	v_mfma_f32_16x16x32_bf16 v[124:127], v[128:131], v[190:193], v[124:127]
	v_mfma_f32_16x16x32_bf16 v[120:123], v[152:155], v[190:193], v[120:123]
	v_mfma_f32_16x16x32_bf16 v[116:119], v[128:131], v[198:201], v[116:119]
	v_mfma_f32_16x16x32_bf16 v[112:115], v[152:155], v[198:201], v[112:115]
	v_mfma_f32_16x16x32_bf16 v[108:111], v[128:131], v[206:209], v[108:111]
	v_mfma_f32_16x16x32_bf16 v[104:107], v[152:155], v[206:209], v[104:107]
	v_mfma_f32_16x16x32_bf16 v[100:103], v[128:131], v[214:217], v[100:103]
	v_mfma_f32_16x16x32_bf16 v[96:99], v[152:155], v[214:217], v[96:99]
	v_mfma_f32_16x16x32_bf16 v[124:127], v[132:135], v[194:197], v[124:127]
	v_mfma_f32_16x16x32_bf16 v[120:123], v[156:159], v[194:197], v[120:123]
	v_mfma_f32_16x16x32_bf16 v[116:119], v[132:135], v[202:205], v[116:119]
	v_mfma_f32_16x16x32_bf16 v[112:115], v[156:159], v[202:205], v[112:115]
	v_mfma_f32_16x16x32_bf16 v[108:111], v[132:135], v[210:213], v[108:111]
	v_mfma_f32_16x16x32_bf16 v[104:107], v[156:159], v[210:213], v[104:107]
	v_mfma_f32_16x16x32_bf16 v[100:103], v[132:135], v[218:221], v[100:103]
	v_mfma_f32_16x16x32_bf16 v[96:99], v[156:159], v[218:221], v[96:99]
	s_setprio 0
	s_setprio 1
	v_mfma_f32_16x16x32_bf16 v[68:71], v[160:163], v[190:193], v[68:71]
	v_mfma_f32_16x16x32_bf16 v[64:67], v[182:185], v[190:193], v[64:67]
	v_mfma_f32_16x16x32_bf16 v[52:55], v[160:163], v[198:201], v[52:55]
	v_mfma_f32_16x16x32_bf16 v[48:51], v[182:185], v[198:201], v[48:51]
	v_mfma_f32_16x16x32_bf16 v[44:47], v[160:163], v[206:209], v[44:47]
	v_mfma_f32_16x16x32_bf16 v[40:43], v[182:185], v[206:209], v[40:43]
	v_mfma_f32_16x16x32_bf16 v[36:39], v[160:163], v[214:217], v[36:39]
	v_mfma_f32_16x16x32_bf16 v[32:35], v[182:185], v[214:217], v[32:35]
	v_mfma_f32_16x16x32_bf16 v[68:71], v[178:181], v[194:197], v[68:71]
	v_mfma_f32_16x16x32_bf16 v[64:67], v[186:189], v[194:197], v[64:67]
	v_mfma_f32_16x16x32_bf16 v[52:55], v[178:181], v[202:205], v[52:55]
	v_mfma_f32_16x16x32_bf16 v[48:51], v[186:189], v[202:205], v[48:51]
	v_mfma_f32_16x16x32_bf16 v[44:47], v[178:181], v[210:213], v[44:47]
	v_mfma_f32_16x16x32_bf16 v[40:43], v[186:189], v[210:213], v[40:43]
	v_mfma_f32_16x16x32_bf16 v[36:39], v[178:181], v[218:221], v[36:39]
	v_mfma_f32_16x16x32_bf16 v[32:35], v[186:189], v[218:221], v[32:35]
	s_setprio 0
	s_barrier
	s_add_i32 s57, s48, s36
	s_mov_b32 m0, s57
	ds_read_b128 v[190:193], v176 offset:16384
	ds_read_b128 v[194:197], v176 offset:17408
	ds_read_b128 v[198:201], v176 offset:18432
	ds_read_b128 v[202:205], v176 offset:19456
	ds_read_b128 v[206:209], v176 offset:20480
	ds_read_b128 v[210:213], v176 offset:21504
	ds_read_b128 v[214:217], v176 offset:22528
	ds_read_b128 v[218:221], v176 offset:23552
	global_load_lds_dwordx4 v138, s[28:29]
	s_add_i32 m0, s57, 0x2000
	s_add_u32 s58, s28, 0x80000
	s_addc_u32 s59, s29, 0
	s_add_i32 s57, s49, s36
	global_load_lds_dwordx4 v144, s[28:29]
	s_mov_b32 m0, s57
	s_nop 0
	global_load_lds_dwordx4 v138, s[58:59]
	s_add_i32 m0, s57, 0x2000
	s_nop 0
	global_load_lds_dwordx4 v144, s[58:59]
	s_mov_b32 m0, s37
	s_nop 0
	global_load_lds_dwordx4 v136, s[30:31]
	s_mov_b32 m0, s38
	s_nop 0
	global_load_lds_dwordx4 v142, s[30:31]
	s_waitcnt vmcnt(8)
	s_waitcnt lgkmcnt(0)
	s_barrier
	s_setprio 1
	s_waitcnt lgkmcnt(0)
	v_mfma_f32_16x16x32_bf16 v[92:95], v[128:131], v[190:193], v[92:95]
	v_mfma_f32_16x16x32_bf16 v[88:91], v[152:155], v[190:193], v[88:91]
	v_mfma_f32_16x16x32_bf16 v[84:87], v[128:131], v[198:201], v[84:87]
	v_mfma_f32_16x16x32_bf16 v[80:83], v[152:155], v[198:201], v[80:83]
	v_mfma_f32_16x16x32_bf16 v[76:79], v[128:131], v[206:209], v[76:79]
	v_mfma_f32_16x16x32_bf16 v[72:75], v[152:155], v[206:209], v[72:75]
	v_mfma_f32_16x16x32_bf16 v[60:63], v[128:131], v[214:217], v[60:63]
	v_mfma_f32_16x16x32_bf16 v[56:59], v[152:155], v[214:217], v[56:59]
	v_mfma_f32_16x16x32_bf16 v[92:95], v[132:135], v[194:197], v[92:95]
	v_mfma_f32_16x16x32_bf16 v[88:91], v[156:159], v[194:197], v[88:91]
	v_mfma_f32_16x16x32_bf16 v[84:87], v[132:135], v[202:205], v[84:87]
	v_mfma_f32_16x16x32_bf16 v[80:83], v[156:159], v[202:205], v[80:83]
	v_mfma_f32_16x16x32_bf16 v[76:79], v[132:135], v[210:213], v[76:79]
	v_mfma_f32_16x16x32_bf16 v[72:75], v[156:159], v[210:213], v[72:75]
	v_mfma_f32_16x16x32_bf16 v[60:63], v[132:135], v[218:221], v[60:63]
	v_mfma_f32_16x16x32_bf16 v[56:59], v[156:159], v[218:221], v[56:59]
	s_setprio 0
	s_setprio 1
	v_mfma_f32_16x16x32_bf16 v[28:31], v[160:163], v[190:193], v[28:31]
	v_mfma_f32_16x16x32_bf16 v[24:27], v[182:185], v[190:193], v[24:27]
	v_mfma_f32_16x16x32_bf16 v[20:23], v[160:163], v[198:201], v[20:23]
	v_mfma_f32_16x16x32_bf16 v[16:19], v[182:185], v[198:201], v[16:19]
	v_mfma_f32_16x16x32_bf16 v[12:15], v[160:163], v[206:209], v[12:15]
	v_mfma_f32_16x16x32_bf16 v[8:11], v[182:185], v[206:209], v[8:11]
	v_mfma_f32_16x16x32_bf16 v[4:7], v[160:163], v[214:217], v[4:7]
	v_mfma_f32_16x16x32_bf16 v[0:3], v[182:185], v[214:217], v[0:3]
	v_mfma_f32_16x16x32_bf16 v[28:31], v[178:181], v[194:197], v[28:31]
	v_mfma_f32_16x16x32_bf16 v[24:27], v[186:189], v[194:197], v[24:27]
	v_mfma_f32_16x16x32_bf16 v[20:23], v[178:181], v[202:205], v[20:23]
	v_mfma_f32_16x16x32_bf16 v[16:19], v[186:189], v[202:205], v[16:19]
	v_mfma_f32_16x16x32_bf16 v[12:15], v[178:181], v[210:213], v[12:15]
	v_mfma_f32_16x16x32_bf16 v[8:11], v[186:189], v[210:213], v[8:11]
	v_mfma_f32_16x16x32_bf16 v[4:7], v[178:181], v[218:221], v[4:7]
	v_mfma_f32_16x16x32_bf16 v[0:3], v[186:189], v[218:221], v[0:3]
	s_setprio 0
	s_barrier
; #define PG8_STAGE(bufoff, gbase, voff) do { _Pragma("unroll") for (int _i = 0; _i < 2; ++_i) \
;         __builtin_amdgcn_global_load_lds((const unsigned*)((const char*)(gbase) + (voff)[_i]), (LAS unsigned*)(lds + (bufoff) + ldsw + _i * 8192), 16, 0, 0); } while (0)
; #define PG8_LDA(dst, b, h) do { _Pragma("unroll") for (int m = 0; m < 4; ++m) _Pragma("unroll") for (int k = 0; k < 2; ++k) dst[m][k] = *(const LAS bf16x8*)(lds + PG8_SA(b, h) + aoff + m * 2048 + k * 1024); } while (0)
; #define PG8_LDB(dst, b, h) do { _Pragma("unroll") for (int n = 0; n < 2; ++n) _Pragma("unroll") for (int k = 0; k < 2; ++k) dst[n][k] = *(const LAS bf16x8*)(lds + PG8_SB(b, h) + boff + n * 2048 + k * 1024); } while (0)
; #define PG8_MMA(ai, bj, At, Bt) do { __builtin_amdgcn_s_setprio(1); _Pragma("unroll") for (int m = 0; m < 4; ++m) _Pragma("unroll") for (int n = 0; n < 2; ++n) _Pragma("unroll") for (int k = 0; k < 2; ++k) \
;         acc[ai][bj][m][n] = __builtin_amdgcn_mfma_f32_16x16x32_bf16(Bt[n][k], At[m][k], acc[ai][bj][m][n], 0, 0, 0); __builtin_amdgcn_s_setprio(0); } while (0)
; #define PG8_WAIT_V(n) asm volatile("s_waitcnt vmcnt(" #n ")" ::: "memory")
; #define PG8_WAIT_L(n) asm volatile("s_waitcnt lgkmcnt(" #n ")" ::: "memory")
; #define PG8_BAR __builtin_amdgcn_s_barrier()
; #define PG8_SCHED __builtin_amdgcn_sched_barrier(0)
; __device__ __forceinline__ void gemm_phase(LAS unsigned char* lds, const Params& p, const bf16_t* gA, const bf16_t* gBt, const int gM, const int gN, const int gK, const int epi, const int perm, bf16_t* const Hp, const int goff, const float coef) {
;     ...
;             PG8_LDB(B0, 1, 0); PG8_LDB(B1, 1, 1); PG8_SCHED; PG8_LDA(At, 1, 0); PG8_STAGE(PG8_SA(0, 1), a2 + hstep, voffA);
;             PG8_WAIT_V(8); PG8_WAIT_L(0); PG8_BAR; PG8_MMA(0, 0, At, B0); PG8_MMA(0, 1, At, B1); PG8_BAR; PG8_SCHED;
;             PG8_LDA(At, 1, 1); PG8_STAGE(PG8_SB(1, 0), b3, voffB); PG8_STAGE(PG8_SB(1, 1), b3 + hstep, voffB); PG8_STAGE(PG8_SA(1, 0), a3, voffA);
;             PG8_WAIT_V(8); PG8_WAIT_L(0); PG8_BAR; PG8_MMA(1, 0, At, B0); PG8_MMA(1, 1, At, B1); PG8_BAR; PG8_SCHED;
;         }
	s_add_i32 s57, 0, 0x18000
	s_add_i32 s58, 0, 0x1c000
	ds_read_b128 v[128:131], v222
	ds_read_b128 v[132:135], v222 offset:1024
	ds_read_b128 v[152:155], v222 offset:2048
	ds_read_b128 v[156:159], v222 offset:3072
	ds_read_b128 v[160:163], v223
	ds_read_b128 v[178:181], v223 offset:1024
	ds_read_b128 v[182:185], v223 offset:2048
	ds_read_b128 v[186:189], v223 offset:3072
	s_add_u32 s30, s30, 0x80000
	s_addc_u32 s31, s31, 0
	s_mov_b32 m0, s39
	ds_read_b128 v[190:193], v176 offset:32768
	ds_read_b128 v[194:197], v176 offset:33792
	ds_read_b128 v[198:201], v176 offset:34816
	ds_read_b128 v[202:205], v176 offset:35840
	ds_read_b128 v[206:209], v176 offset:36864
	ds_read_b128 v[210:213], v176 offset:37888
	ds_read_b128 v[214:217], v176 offset:38912
	ds_read_b128 v[218:221], v176 offset:39936
	global_load_lds_dwordx4 v136, s[30:31]
	s_mov_b32 m0, s40
	s_nop 0
	global_load_lds_dwordx4 v142, s[30:31]
	s_waitcnt vmcnt(8)
	s_waitcnt lgkmcnt(0)
	s_barrier
	s_setprio 1
	s_waitcnt lgkmcnt(0)
	v_mfma_f32_16x16x32_bf16 v[124:127], v[128:131], v[190:193], v[124:127]
	v_mfma_f32_16x16x32_bf16 v[120:123], v[152:155], v[190:193], v[120:123]
	v_mfma_f32_16x16x32_bf16 v[116:119], v[128:131], v[198:201], v[116:119]
	v_mfma_f32_16x16x32_bf16 v[112:115], v[152:155], v[198:201], v[112:115]
	v_mfma_f32_16x16x32_bf16 v[108:111], v[128:131], v[206:209], v[108:111]
	v_mfma_f32_16x16x32_bf16 v[104:107], v[152:155], v[206:209], v[104:107]
	v_mfma_f32_16x16x32_bf16 v[100:103], v[128:131], v[214:217], v[100:103]
	v_mfma_f32_16x16x32_bf16 v[96:99], v[152:155], v[214:217], v[96:99]
	v_mfma_f32_16x16x32_bf16 v[124:127], v[132:135], v[194:197], v[124:127]
	v_mfma_f32_16x16x32_bf16 v[120:123], v[156:159], v[194:197], v[120:123]
	v_mfma_f32_16x16x32_bf16 v[116:119], v[132:135], v[202:205], v[116:119]
	v_mfma_f32_16x16x32_bf16 v[112:115], v[156:159], v[202:205], v[112:115]
	v_mfma_f32_16x16x32_bf16 v[108:111], v[132:135], v[210:213], v[108:111]
	v_mfma_f32_16x16x32_bf16 v[104:107], v[156:159], v[210:213], v[104:107]
	v_mfma_f32_16x16x32_bf16 v[100:103], v[132:135], v[218:221], v[100:103]
	v_mfma_f32_16x16x32_bf16 v[96:99], v[156:159], v[218:221], v[96:99]
	s_setprio 0
	s_setprio 1
	v_mfma_f32_16x16x32_bf16 v[68:71], v[160:163], v[190:193], v[68:71]
	v_mfma_f32_16x16x32_bf16 v[64:67], v[182:185], v[190:193], v[64:67]
	v_mfma_f32_16x16x32_bf16 v[52:55], v[160:163], v[198:201], v[52:55]
	v_mfma_f32_16x16x32_bf16 v[48:51], v[182:185], v[198:201], v[48:51]
	v_mfma_f32_16x16x32_bf16 v[44:47], v[160:163], v[206:209], v[44:47]
	v_mfma_f32_16x16x32_bf16 v[40:43], v[182:185], v[206:209], v[40:43]
	v_mfma_f32_16x16x32_bf16 v[36:39], v[160:163], v[214:217], v[36:39]
	v_mfma_f32_16x16x32_bf16 v[32:35], v[182:185], v[214:217], v[32:35]
	v_mfma_f32_16x16x32_bf16 v[68:71], v[178:181], v[194:197], v[68:71]
	v_mfma_f32_16x16x32_bf16 v[64:67], v[186:189], v[194:197], v[64:67]
	v_mfma_f32_16x16x32_bf16 v[52:55], v[178:181], v[202:205], v[52:55]
	v_mfma_f32_16x16x32_bf16 v[48:51], v[186:189], v[202:205], v[48:51]
	v_mfma_f32_16x16x32_bf16 v[44:47], v[178:181], v[210:213], v[44:47]
	v_mfma_f32_16x16x32_bf16 v[40:43], v[186:189], v[210:213], v[40:43]
	v_mfma_f32_16x16x32_bf16 v[36:39], v[178:181], v[218:221], v[36:39]
	v_mfma_f32_16x16x32_bf16 v[32:35], v[186:189], v[218:221], v[32:35]
	s_setprio 0
	s_barrier
	s_mov_b64 s[98:99], s[30:31]
	s_add_i32 s30, s57, s36
	s_mov_b32 m0, s30
	ds_read_b128 v[190:193], v176 offset:49152
	ds_read_b128 v[194:197], v176 offset:50176
	ds_read_b128 v[198:201], v176 offset:51200
	ds_read_b128 v[202:205], v176 offset:52224
	ds_read_b128 v[206:209], v176 offset:53248
	ds_read_b128 v[210:213], v176 offset:54272
	ds_read_b128 v[214:217], v176 offset:55296
	ds_read_b128 v[218:221], v176 offset:56320
	s_add_u32 s100, s28, 0x80
	s_addc_u32 s101, s29, 0
	global_load_lds_dwordx4 v138, s[100:101]
	s_add_i32 m0, s30, 0x2000
	s_add_u32 s28, s28, 0x80080
	s_addc_u32 s29, s29, 0
	s_add_i32 s30, s58, s36
	global_load_lds_dwordx4 v144, s[100:101]
	s_mov_b32 m0, s30
	s_nop 0
	global_load_lds_dwordx4 v138, s[28:29]
	s_add_i32 m0, s30, 0x2000
	s_nop 0
	global_load_lds_dwordx4 v144, s[28:29]
	s_mov_b32 m0, s44
	s_nop 0
	s_add_u32 s100, s98, 0xfff80080
	s_addc_u32 s101, s99, -1
	global_load_lds_dwordx4 v136, s[100:101]
	s_mov_b32 m0, s45
	s_nop 0
	global_load_lds_dwordx4 v142, s[100:101]
	s_waitcnt vmcnt(8)
	s_waitcnt lgkmcnt(0)
	s_barrier
	s_setprio 1
	s_waitcnt lgkmcnt(0)
	v_mfma_f32_16x16x32_bf16 v[92:95], v[128:131], v[190:193], v[92:95]
	v_mfma_f32_16x16x32_bf16 v[88:91], v[152:155], v[190:193], v[88:91]
	v_mfma_f32_16x16x32_bf16 v[84:87], v[128:131], v[198:201], v[84:87]
	v_mfma_f32_16x16x32_bf16 v[80:83], v[152:155], v[198:201], v[80:83]
	v_mfma_f32_16x16x32_bf16 v[76:79], v[128:131], v[206:209], v[76:79]
	v_mfma_f32_16x16x32_bf16 v[72:75], v[152:155], v[206:209], v[72:75]
	v_mfma_f32_16x16x32_bf16 v[60:63], v[128:131], v[214:217], v[60:63]
	v_mfma_f32_16x16x32_bf16 v[56:59], v[152:155], v[214:217], v[56:59]
	v_mfma_f32_16x16x32_bf16 v[92:95], v[132:135], v[194:197], v[92:95]
	v_mfma_f32_16x16x32_bf16 v[88:91], v[156:159], v[194:197], v[88:91]
	v_mfma_f32_16x16x32_bf16 v[84:87], v[132:135], v[202:205], v[84:87]
	v_mfma_f32_16x16x32_bf16 v[80:83], v[156:159], v[202:205], v[80:83]
	v_mfma_f32_16x16x32_bf16 v[76:79], v[132:135], v[210:213], v[76:79]
	v_mfma_f32_16x16x32_bf16 v[72:75], v[156:159], v[210:213], v[72:75]
	v_mfma_f32_16x16x32_bf16 v[60:63], v[132:135], v[218:221], v[60:63]
	v_mfma_f32_16x16x32_bf16 v[56:59], v[156:159], v[218:221], v[56:59]
	s_setprio 0
	s_setprio 1
	v_mfma_f32_16x16x32_bf16 v[28:31], v[160:163], v[190:193], v[28:31]
	v_mfma_f32_16x16x32_bf16 v[24:27], v[182:185], v[190:193], v[24:27]
	v_mfma_f32_16x16x32_bf16 v[20:23], v[160:163], v[198:201], v[20:23]
	v_mfma_f32_16x16x32_bf16 v[16:19], v[182:185], v[198:201], v[16:19]
	v_mfma_f32_16x16x32_bf16 v[12:15], v[160:163], v[206:209], v[12:15]
	v_mfma_f32_16x16x32_bf16 v[8:11], v[182:185], v[206:209], v[8:11]
	v_mfma_f32_16x16x32_bf16 v[4:7], v[160:163], v[214:217], v[4:7]
	v_mfma_f32_16x16x32_bf16 v[0:3], v[182:185], v[214:217], v[0:3]
	v_mfma_f32_16x16x32_bf16 v[28:31], v[178:181], v[194:197], v[28:31]
	v_mfma_f32_16x16x32_bf16 v[24:27], v[186:189], v[194:197], v[24:27]
	v_mfma_f32_16x16x32_bf16 v[20:23], v[178:181], v[202:205], v[20:23]
	v_mfma_f32_16x16x32_bf16 v[16:19], v[186:189], v[202:205], v[16:19]
	v_mfma_f32_16x16x32_bf16 v[12:15], v[178:181], v[210:213], v[12:15]
	v_mfma_f32_16x16x32_bf16 v[8:11], v[186:189], v[210:213], v[8:11]
	v_mfma_f32_16x16x32_bf16 v[4:7], v[178:181], v[218:221], v[4:7]
	v_mfma_f32_16x16x32_bf16 v[0:3], v[186:189], v[218:221], v[0:3]
	s_setprio 0
	s_barrier
	s_add_u32 s26, s26, 0x100
	s_addc_u32 s27, s27, 0
	s_add_u32 s54, s54, 0x100
	s_addc_u32 s55, s55, 0
	s_cmp_ge_u32 s56, s52
	s_mov_b32 s30, s56
	s_cbranch_scc0 .LBB0_1593
	s_and_b64 vcc, exec, s[10:11]
	s_cbranch_vccz .LBB0_1596
	s_barrier

; #define PG8_STAGE(bufoff, gbase, voff) do { _Pragma("unroll") for (int _i = 0; _i < 2; ++_i) \
;         __builtin_amdgcn_global_load_lds((const unsigned*)((const char*)(gbase) + (voff)[_i]), (LAS unsigned*)(lds + (bufoff) + ldsw + _i * 8192), 16, 0, 0); } while (0)
; #define PG8_LDA(dst, b, h) do { _Pragma("unroll") for (int m = 0; m < 4; ++m) _Pragma("unroll") for (int k = 0; k < 2; ++k) dst[m][k] = *(const LAS bf16x8*)(lds + PG8_SA(b, h) + aoff + m * 2048 + k * 1024); } while (0)
; #define PG8_LDB(dst, b, h) do { _Pragma("unroll") for (int n = 0; n < 2; ++n) _Pragma("unroll") for (int k = 0; k < 2; ++k) dst[n][k] = *(const LAS bf16x8*)(lds + PG8_SB(b, h) + boff + n * 2048 + k * 1024); } while (0)
; #define PG8_MMA(ai, bj, At, Bt) do { __builtin_amdgcn_s_setprio(1); _Pragma("unroll") for (int m = 0; m < 4; ++m) _Pragma("unroll") for (int n = 0; n < 2; ++n) _Pragma("unroll") for (int k = 0; k < 2; ++k) \
;         acc[ai][bj][m][n] = __builtin_amdgcn_mfma_f32_16x16x32_bf16(Bt[n][k], At[m][k], acc[ai][bj][m][n], 0, 0, 0); __builtin_amdgcn_s_setprio(0); } while (0)
; #define PG8_WAIT_V(n) asm volatile("s_waitcnt vmcnt(" #n ")" ::: "memory")
; #define PG8_BAR __builtin_amdgcn_s_barrier()
; __device__ __forceinline__ void gemm_phase(LAS unsigned char* lds, const Params& p, const bf16_t* gA, const bf16_t* gBt, const int gM, const int gN, const int gK, const int epi, const int perm, bf16_t* const Hp, const int goff, const float coef) {
;     ...
;         const bool has_next = S.next(ui + 1, nxt);
;         const char* nA = has_next ? (const char*)gA + (size_t)nxt.pm * tstep + (nxt.ks > 0 ? nxt.ks * ksl : 0) : cA; const char* nB = has_next ? (const char*)gBt + (size_t)nxt.pn * tstep + (nxt.ks > 0 ? nxt.ks * ksl : 0) : cB;
;         const int nt = cur.ks >= 0 ? ntf / 4 : ntf;
;         for (int t = 0; t < nt; t += 2) {
;             const bool last = (t == nt - 2);
;             const char* a1 = cA + (size_t)(t + 1) * kstep;
;             const char* a2 = last ? nA : cA + (size_t)(t + 2) * kstep; const char* b2 = last ? nB : cB + (size_t)(t + 2) * kstep;
;             const char* a3 = a2 + kstep; const char* b3 = b2 + kstep;
;             PG8_LDB(B0, 0, 0); PG8_LDB(B1, 0, 1); PG8_SCHED; PG8_LDA(At, 0, 0); PG8_STAGE(PG8_SA(1, 1), a1 + hstep, voffA);
;             PG8_WAIT_V(8); PG8_WAIT_L(0); PG8_BAR; PG8_MMA(0, 0, At, B0); PG8_MMA(0, 1, At, B1); PG8_BAR; PG8_SCHED;
.LBB0_1736:
	s_ashr_i32 s13, s12, 31
	s_lshl_b64 s[18:19], s[12:13], 20
	s_add_u32 s13, s3, s18
	s_addc_u32 s15, s33, s19
	s_lshl_b64 s[18:19], s[0:1], 10
	s_cmp_gt_i32 s0, 0
	s_cselect_b32 s50, s18, 0
	s_cselect_b32 s49, s19, 0
	s_add_u32 s18, s13, s50
	s_addc_u32 s19, s15, s49
	s_and_b64 s[20:21], s[16:17], exec
	s_cselect_b32 s13, s19, s27
	s_cselect_b32 s48, s18, s26
	s_ashr_i32 s15, s14, 31
	s_lshl_b64 s[20:21], s[14:15], 20
	s_add_u32 s15, s34, s20
	s_addc_u32 s21, s35, s21
	s_add_u32 s20, s15, s50
	s_addc_u32 s21, s21, s49
	s_and_b64 s[50:51], s[16:17], exec
	s_cselect_b32 s15, s21, s29
	s_cselect_b32 s49, s20, s28
	s_cmp_gt_i32 s31, -1
	s_cselect_b32 s50, 8, 32
	s_add_i32 s51, s50, -2
	s_add_u32 s26, s26, 0x80080
	s_addc_u32 s27, s27, 0
	s_add_u32 s52, s28, 0x100
	v_mov_b32_e32 v0, 0
	s_mov_b32 s30, 0
	s_addc_u32 s53, s29, 0
	v_mov_b32_e32 v1, v0
	v_mov_b32_e32 v2, v0
	v_mov_b32_e32 v3, v0
	v_mov_b32_e32 v4, v0
	v_mov_b32_e32 v5, v0
	v_mov_b32_e32 v6, v0
	v_mov_b32_e32 v7, v0
	v_mov_b32_e32 v16, v0
	v_mov_b32_e32 v17, v0
	v_mov_b32_e32 v18, v0
	v_mov_b32_e32 v19, v0
	v_mov_b32_e32 v20, v0
	v_mov_b32_e32 v21, v0
	v_mov_b32_e32 v22, v0
	v_mov_b32_e32 v23, v0
	v_mov_b32_e32 v32, v0
	v_mov_b32_e32 v33, v0
	v_mov_b32_e32 v34, v0
	v_mov_b32_e32 v35, v0
	v_mov_b32_e32 v36, v0
	v_mov_b32_e32 v37, v0
	v_mov_b32_e32 v38, v0
	v_mov_b32_e32 v39, v0
	v_mov_b32_e32 v48, v0
	v_mov_b32_e32 v49, v0
	v_mov_b32_e32 v50, v0
	v_mov_b32_e32 v51, v0
	v_mov_b32_e32 v52, v0
	v_mov_b32_e32 v53, v0
	v_mov_b32_e32 v54, v0
	v_mov_b32_e32 v55, v0
	v_mov_b32_e32 v8, v0
	v_mov_b32_e32 v9, v0
	v_mov_b32_e32 v10, v0
	v_mov_b32_e32 v11, v0
	v_mov_b32_e32 v12, v0
	v_mov_b32_e32 v13, v0
	v_mov_b32_e32 v14, v0
	v_mov_b32_e32 v15, v0
	v_mov_b32_e32 v24, v0
	v_mov_b32_e32 v25, v0
	v_mov_b32_e32 v26, v0
	v_mov_b32_e32 v27, v0
	v_mov_b32_e32 v28, v0
	v_mov_b32_e32 v29, v0
	v_mov_b32_e32 v30, v0
	v_mov_b32_e32 v31, v0
	v_mov_b32_e32 v40, v0
	v_mov_b32_e32 v41, v0
	v_mov_b32_e32 v42, v0
	v_mov_b32_e32 v43, v0
	v_mov_b32_e32 v44, v0
	v_mov_b32_e32 v45, v0
	v_mov_b32_e32 v46, v0
	v_mov_b32_e32 v47, v0
	v_mov_b32_e32 v56, v0
	v_mov_b32_e32 v57, v0
	v_mov_b32_e32 v58, v0
	v_mov_b32_e32 v59, v0
	v_mov_b32_e32 v60, v0
	v_mov_b32_e32 v61, v0
	v_mov_b32_e32 v62, v0
	v_mov_b32_e32 v63, v0
	v_mov_b32_e32 v64, v0
	v_mov_b32_e32 v65, v0
	v_mov_b32_e32 v66, v0
	v_mov_b32_e32 v67, v0
	v_mov_b32_e32 v68, v0
	v_mov_b32_e32 v69, v0
	v_mov_b32_e32 v70, v0
	v_mov_b32_e32 v71, v0
	v_mov_b32_e32 v80, v0
	v_mov_b32_e32 v81, v0
	v_mov_b32_e32 v82, v0
	v_mov_b32_e32 v83, v0
	v_mov_b32_e32 v84, v0
	v_mov_b32_e32 v85, v0
	v_mov_b32_e32 v86, v0
	v_mov_b32_e32 v87, v0
	v_mov_b32_e32 v96, v0
	v_mov_b32_e32 v97, v0
	v_mov_b32_e32 v98, v0
	v_mov_b32_e32 v99, v0
	v_mov_b32_e32 v100, v0
	v_mov_b32_e32 v101, v0
	v_mov_b32_e32 v102, v0
	v_mov_b32_e32 v103, v0
	v_mov_b32_e32 v112, v0
	v_mov_b32_e32 v113, v0
	v_mov_b32_e32 v114, v0
	v_mov_b32_e32 v115, v0
	v_mov_b32_e32 v116, v0
	v_mov_b32_e32 v117, v0
	v_mov_b32_e32 v118, v0
	v_mov_b32_e32 v119, v0
	v_mov_b32_e32 v72, v0
	v_mov_b32_e32 v73, v0
	v_mov_b32_e32 v74, v0
	v_mov_b32_e32 v75, v0
	v_mov_b32_e32 v76, v0
	v_mov_b32_e32 v77, v0
	v_mov_b32_e32 v78, v0
	v_mov_b32_e32 v79, v0
	v_mov_b32_e32 v88, v0
	v_mov_b32_e32 v89, v0
	v_mov_b32_e32 v90, v0
	v_mov_b32_e32 v91, v0
	v_mov_b32_e32 v92, v0
	v_mov_b32_e32 v93, v0
	v_mov_b32_e32 v94, v0
	v_mov_b32_e32 v95, v0
	v_mov_b32_e32 v104, v0
	v_mov_b32_e32 v105, v0
	v_mov_b32_e32 v106, v0
	v_mov_b32_e32 v107, v0
	v_mov_b32_e32 v108, v0
	v_mov_b32_e32 v109, v0
	v_mov_b32_e32 v110, v0
	v_mov_b32_e32 v111, v0
	v_mov_b32_e32 v120, v0
	v_mov_b32_e32 v121, v0
	v_mov_b32_e32 v122, v0
	v_mov_b32_e32 v123, v0
	v_mov_b32_e32 v124, v0
	v_mov_b32_e32 v125, v0
	v_mov_b32_e32 v126, v0
	v_mov_b32_e32 v127, v0
	v_add_u32_e32 v224, 0x18000, v147
	v_add_u32_e32 v225, 0x1c000, v147
.LBB0_1737:
	ds_read_b128 v[160:163], v156
	ds_read_b128 v[164:167], v156 offset:1024
	ds_read_b128 v[168:171], v156 offset:2048
	ds_read_b128 v[172:175], v156 offset:3072
	ds_read_b128 v[176:179], v157
	ds_read_b128 v[180:183], v157 offset:1024
	ds_read_b128 v[184:187], v157 offset:2048
	ds_read_b128 v[188:191], v157 offset:3072
	s_add_i32 s54, s30, 2
	s_add_u32 s28, s26, 0xfff80080
	s_addc_u32 s29, s27, -1
	s_cmp_eq_u32 s51, s30
	s_cselect_b32 s30, s48, s28
	s_cselect_b32 s31, s13, s29
	s_cselect_b32 s29, s15, s53
	s_cselect_b32 s28, s49, s52
	s_add_i32 m0, s23, 0xc000
	ds_read_b128 v[192:195], v158
	ds_read_b128 v[196:199], v158 offset:1024
	ds_read_b128 v[200:203], v158 offset:2048
	ds_read_b128 v[204:207], v158 offset:3072
	ds_read_b128 v[208:211], v158 offset:4096
	ds_read_b128 v[212:215], v158 offset:5120
	ds_read_b128 v[216:219], v158 offset:6144
	ds_read_b128 v[220:223], v158 offset:7168
	global_load_lds_dwordx4 v136, s[26:27]
	s_add_i32 m0, s23, 0xe000
	s_nop 0
	global_load_lds_dwordx4 v138, s[26:27]
	s_waitcnt vmcnt(8)
	s_waitcnt lgkmcnt(0)
	s_barrier
; #define PG8_STAGE(bufoff, gbase, voff) do { _Pragma("unroll") for (int _i = 0; _i < 2; ++_i) \
;         __builtin_amdgcn_global_load_lds((const unsigned*)((const char*)(gbase) + (voff)[_i]), (LAS unsigned*)(lds + (bufoff) + ldsw + _i * 8192), 16, 0, 0); } while (0)
; #define PG8_LDA(dst, b, h) do { _Pragma("unroll") for (int m = 0; m < 4; ++m) _Pragma("unroll") for (int k = 0; k < 2; ++k) dst[m][k] = *(const LAS bf16x8*)(lds + PG8_SA(b, h) + aoff + m * 2048 + k * 1024); } while (0)
; #define PG8_MMA(ai, bj, At, Bt) do { __builtin_amdgcn_s_setprio(1); _Pragma("unroll") for (int m = 0; m < 4; ++m) _Pragma("unroll") for (int n = 0; n < 2; ++n) _Pragma("unroll") for (int k = 0; k < 2; ++k) \
;         acc[ai][bj][m][n] = __builtin_amdgcn_mfma_f32_16x16x32_bf16(Bt[n][k], At[m][k], acc[ai][bj][m][n], 0, 0, 0); __builtin_amdgcn_s_setprio(0); } while (0)
; #define PG8_WAIT_V(n) asm volatile("s_waitcnt vmcnt(" #n ")" ::: "memory")
; #define PG8_WAIT_L(n) asm volatile("s_waitcnt lgkmcnt(" #n ")" ::: "memory")
; #define PG8_BAR __builtin_amdgcn_s_barrier()
; #define PG8_SCHED __builtin_amdgcn_sched_barrier(0)
; __device__ __forceinline__ void gemm_phase(LAS unsigned char* lds, const Params& p, const bf16_t* gA, const bf16_t* gBt, const int gM, const int gN, const int gK, const int epi, const int perm, bf16_t* const Hp, const int goff, const float coef) {
;     ...
;             PG8_WAIT_V(8); PG8_WAIT_L(0); PG8_BAR; PG8_MMA(0, 0, At, B0); PG8_MMA(0, 1, At, B1); PG8_BAR; PG8_SCHED;
;             PG8_LDA(At, 0, 1); PG8_STAGE(PG8_SB(0, 0), b2, voffB); PG8_STAGE(PG8_SB(0, 1), b2 + hstep, voffB); PG8_STAGE(PG8_SA(0, 0), a2, voffA);
;             PG8_WAIT_V(8); PG8_WAIT_L(0); PG8_BAR; PG8_MMA(1, 0, At, B0); PG8_MMA(1, 1, At, B1); PG8_BAR; PG8_SCHED;
	s_setprio 1
	s_waitcnt lgkmcnt(0)
	v_mfma_f32_16x16x32_bf16 v[124:127], v[160:163], v[192:195], v[124:127]
	v_mfma_f32_16x16x32_bf16 v[120:123], v[168:171], v[192:195], v[120:123]
	v_mfma_f32_16x16x32_bf16 v[108:111], v[160:163], v[200:203], v[108:111]
	v_mfma_f32_16x16x32_bf16 v[104:107], v[168:171], v[200:203], v[104:107]
	v_mfma_f32_16x16x32_bf16 v[92:95], v[160:163], v[208:211], v[92:95]
	v_mfma_f32_16x16x32_bf16 v[88:91], v[168:171], v[208:211], v[88:91]
	v_mfma_f32_16x16x32_bf16 v[76:79], v[160:163], v[216:219], v[76:79]
	v_mfma_f32_16x16x32_bf16 v[72:75], v[168:171], v[216:219], v[72:75]
	v_mfma_f32_16x16x32_bf16 v[124:127], v[164:167], v[196:199], v[124:127]
	v_mfma_f32_16x16x32_bf16 v[120:123], v[172:175], v[196:199], v[120:123]
	v_mfma_f32_16x16x32_bf16 v[108:111], v[164:167], v[204:207], v[108:111]
	v_mfma_f32_16x16x32_bf16 v[104:107], v[172:175], v[204:207], v[104:107]
	v_mfma_f32_16x16x32_bf16 v[92:95], v[164:167], v[212:215], v[92:95]
	v_mfma_f32_16x16x32_bf16 v[88:91], v[172:175], v[212:215], v[88:91]
	v_mfma_f32_16x16x32_bf16 v[76:79], v[164:167], v[220:223], v[76:79]
	v_mfma_f32_16x16x32_bf16 v[72:75], v[172:175], v[220:223], v[72:75]
	s_setprio 0
	s_setprio 1
	v_mfma_f32_16x16x32_bf16 v[116:119], v[176:179], v[192:195], v[116:119]
	v_mfma_f32_16x16x32_bf16 v[112:115], v[184:187], v[192:195], v[112:115]
	v_mfma_f32_16x16x32_bf16 v[100:103], v[176:179], v[200:203], v[100:103]
	v_mfma_f32_16x16x32_bf16 v[96:99], v[184:187], v[200:203], v[96:99]
	v_mfma_f32_16x16x32_bf16 v[84:87], v[176:179], v[208:211], v[84:87]
	v_mfma_f32_16x16x32_bf16 v[80:83], v[184:187], v[208:211], v[80:83]
	v_mfma_f32_16x16x32_bf16 v[68:71], v[176:179], v[216:219], v[68:71]
	v_mfma_f32_16x16x32_bf16 v[64:67], v[184:187], v[216:219], v[64:67]
	v_mfma_f32_16x16x32_bf16 v[116:119], v[180:183], v[196:199], v[116:119]
	v_mfma_f32_16x16x32_bf16 v[112:115], v[188:191], v[196:199], v[112:115]
	v_mfma_f32_16x16x32_bf16 v[100:103], v[180:183], v[204:207], v[100:103]
	v_mfma_f32_16x16x32_bf16 v[96:99], v[188:191], v[204:207], v[96:99]
	v_mfma_f32_16x16x32_bf16 v[84:87], v[180:183], v[212:215], v[84:87]
	v_mfma_f32_16x16x32_bf16 v[80:83], v[188:191], v[212:215], v[80:83]
	v_mfma_f32_16x16x32_bf16 v[68:71], v[180:183], v[220:223], v[68:71]
	v_mfma_f32_16x16x32_bf16 v[64:67], v[188:191], v[220:223], v[64:67]
	s_setprio 0
	s_barrier
	s_add_i32 s55, s44, s36
	s_mov_b32 m0, s55
	ds_read_b128 v[192:195], v158 offset:16384
	ds_read_b128 v[196:199], v158 offset:17408
	ds_read_b128 v[200:203], v158 offset:18432
	ds_read_b128 v[204:207], v158 offset:19456
	ds_read_b128 v[208:211], v158 offset:20480
	ds_read_b128 v[212:215], v158 offset:21504
	ds_read_b128 v[216:219], v158 offset:22528
	ds_read_b128 v[220:223], v158 offset:23552
	global_load_lds_dwordx4 v130, s[28:29]
	s_add_i32 m0, s55, 0x2000
	s_add_u32 s56, s28, 0x80000
	s_addc_u32 s57, s29, 0
	s_add_i32 s55, s45, s36
	global_load_lds_dwordx4 v134, s[28:29]
	s_mov_b32 m0, s55
	s_nop 0
	global_load_lds_dwordx4 v130, s[56:57]
	s_add_i32 m0, s55, 0x2000
	s_nop 0
	global_load_lds_dwordx4 v134, s[56:57]
	s_mov_b32 m0, s23
	s_nop 0
	global_load_lds_dwordx4 v128, s[30:31]
	s_mov_b32 m0, s25
	s_nop 0
	global_load_lds_dwordx4 v132, s[30:31]
	s_waitcnt vmcnt(8)
	s_waitcnt lgkmcnt(0)
	s_barrier
	s_setprio 1
	s_waitcnt lgkmcnt(0)
	v_mfma_f32_16x16x32_bf16 v[60:63], v[160:163], v[192:195], v[60:63]
	v_mfma_f32_16x16x32_bf16 v[56:59], v[168:171], v[192:195], v[56:59]
	v_mfma_f32_16x16x32_bf16 v[44:47], v[160:163], v[200:203], v[44:47]
	v_mfma_f32_16x16x32_bf16 v[40:43], v[168:171], v[200:203], v[40:43]
	v_mfma_f32_16x16x32_bf16 v[28:31], v[160:163], v[208:211], v[28:31]
	v_mfma_f32_16x16x32_bf16 v[24:27], v[168:171], v[208:211], v[24:27]
	v_mfma_f32_16x16x32_bf16 v[12:15], v[160:163], v[216:219], v[12:15]
	v_mfma_f32_16x16x32_bf16 v[8:11], v[168:171], v[216:219], v[8:11]
	v_mfma_f32_16x16x32_bf16 v[60:63], v[164:167], v[196:199], v[60:63]
	v_mfma_f32_16x16x32_bf16 v[56:59], v[172:175], v[196:199], v[56:59]
	v_mfma_f32_16x16x32_bf16 v[44:47], v[164:167], v[204:207], v[44:47]
	v_mfma_f32_16x16x32_bf16 v[40:43], v[172:175], v[204:207], v[40:43]
	v_mfma_f32_16x16x32_bf16 v[28:31], v[164:167], v[212:215], v[28:31]
	v_mfma_f32_16x16x32_bf16 v[24:27], v[172:175], v[212:215], v[24:27]
	v_mfma_f32_16x16x32_bf16 v[12:15], v[164:167], v[220:223], v[12:15]
	v_mfma_f32_16x16x32_bf16 v[8:11], v[172:175], v[220:223], v[8:11]
	s_setprio 0
	s_setprio 1
	v_mfma_f32_16x16x32_bf16 v[52:55], v[176:179], v[192:195], v[52:55]
	v_mfma_f32_16x16x32_bf16 v[48:51], v[184:187], v[192:195], v[48:51]
	v_mfma_f32_16x16x32_bf16 v[36:39], v[176:179], v[200:203], v[36:39]
	v_mfma_f32_16x16x32_bf16 v[32:35], v[184:187], v[200:203], v[32:35]
	v_mfma_f32_16x16x32_bf16 v[20:23], v[176:179], v[208:211], v[20:23]
	v_mfma_f32_16x16x32_bf16 v[16:19], v[184:187], v[208:211], v[16:19]
	v_mfma_f32_16x16x32_bf16 v[4:7], v[176:179], v[216:219], v[4:7]
	v_mfma_f32_16x16x32_bf16 v[0:3], v[184:187], v[216:219], v[0:3]
	v_mfma_f32_16x16x32_bf16 v[52:55], v[180:183], v[196:199], v[52:55]
	v_mfma_f32_16x16x32_bf16 v[48:51], v[188:191], v[196:199], v[48:51]
	v_mfma_f32_16x16x32_bf16 v[36:39], v[180:183], v[204:207], v[36:39]
	v_mfma_f32_16x16x32_bf16 v[32:35], v[188:191], v[204:207], v[32:35]
	v_mfma_f32_16x16x32_bf16 v[20:23], v[180:183], v[212:215], v[20:23]
	v_mfma_f32_16x16x32_bf16 v[16:19], v[188:191], v[212:215], v[16:19]
	v_mfma_f32_16x16x32_bf16 v[4:7], v[180:183], v[220:223], v[4:7]
	v_mfma_f32_16x16x32_bf16 v[0:3], v[188:191], v[220:223], v[0:3]
	s_setprio 0
	s_barrier
; #define PG8_STAGE(bufoff, gbase, voff) do { _Pragma("unroll") for (int _i = 0; _i < 2; ++_i) \
;         __builtin_amdgcn_global_load_lds((const unsigned*)((const char*)(gbase) + (voff)[_i]), (LAS unsigned*)(lds + (bufoff) + ldsw + _i * 8192), 16, 0, 0); } while (0)
; #define PG8_LDA(dst, b, h) do { _Pragma("unroll") for (int m = 0; m < 4; ++m) _Pragma("unroll") for (int k = 0; k < 2; ++k) dst[m][k] = *(const LAS bf16x8*)(lds + PG8_SA(b, h) + aoff + m * 2048 + k * 1024); } while (0)
; #define PG8_LDB(dst, b, h) do { _Pragma("unroll") for (int n = 0; n < 2; ++n) _Pragma("unroll") for (int k = 0; k < 2; ++k) dst[n][k] = *(const LAS bf16x8*)(lds + PG8_SB(b, h) + boff + n * 2048 + k * 1024); } while (0)
; #define PG8_MMA(ai, bj, At, Bt) do { __builtin_amdgcn_s_setprio(1); _Pragma("unroll") for (int m = 0; m < 4; ++m) _Pragma("unroll") for (int n = 0; n < 2; ++n) _Pragma("unroll") for (int k = 0; k < 2; ++k) \
;         acc[ai][bj][m][n] = __builtin_amdgcn_mfma_f32_16x16x32_bf16(Bt[n][k], At[m][k], acc[ai][bj][m][n], 0, 0, 0); __builtin_amdgcn_s_setprio(0); } while (0)
; #define PG8_WAIT_V(n) asm volatile("s_waitcnt vmcnt(" #n ")" ::: "memory")
; #define PG8_WAIT_L(n) asm volatile("s_waitcnt lgkmcnt(" #n ")" ::: "memory")
; #define PG8_BAR __builtin_amdgcn_s_barrier()
; #define PG8_SCHED __builtin_amdgcn_sched_barrier(0)
; __device__ __forceinline__ void gemm_phase(LAS unsigned char* lds, const Params& p, const bf16_t* gA, const bf16_t* gBt, const int gM, const int gN, const int gK, const int epi, const int perm, bf16_t* const Hp, const int goff, const float coef) {
;     ...
;             PG8_LDB(B0, 1, 0); PG8_LDB(B1, 1, 1); PG8_SCHED; PG8_LDA(At, 1, 0); PG8_STAGE(PG8_SA(0, 1), a2 + hstep, voffA);
;             PG8_WAIT_V(8); PG8_WAIT_L(0); PG8_BAR; PG8_MMA(0, 0, At, B0); PG8_MMA(0, 1, At, B1); PG8_BAR; PG8_SCHED;
;             PG8_LDA(At, 1, 1); PG8_STAGE(PG8_SB(1, 0), b3, voffB); PG8_STAGE(PG8_SB(1, 1), b3 + hstep, voffB); PG8_STAGE(PG8_SA(1, 0), a3, voffA);
;             PG8_WAIT_V(8); PG8_WAIT_L(0); PG8_BAR; PG8_MMA(1, 0, At, B0); PG8_MMA(1, 1, At, B1); PG8_BAR; PG8_SCHED;
;         }
	s_add_i32 s55, 0, 0x18000
	s_add_i32 s56, 0, 0x1c000
	ds_read_b128 v[160:163], v224
	ds_read_b128 v[164:167], v224 offset:1024
	ds_read_b128 v[168:171], v224 offset:2048
	ds_read_b128 v[172:175], v224 offset:3072
	ds_read_b128 v[176:179], v225
	ds_read_b128 v[180:183], v225 offset:1024
	ds_read_b128 v[184:187], v225 offset:2048
	ds_read_b128 v[188:191], v225 offset:3072
	s_add_u32 s30, s30, 0x80000
	s_addc_u32 s31, s31, 0
	s_mov_b32 m0, s37
	ds_read_b128 v[192:195], v158 offset:32768
	ds_read_b128 v[196:199], v158 offset:33792
	ds_read_b128 v[200:203], v158 offset:34816
	ds_read_b128 v[204:207], v158 offset:35840
	ds_read_b128 v[208:211], v158 offset:36864
	ds_read_b128 v[212:215], v158 offset:37888
	ds_read_b128 v[216:219], v158 offset:38912
	ds_read_b128 v[220:223], v158 offset:39936
	global_load_lds_dwordx4 v128, s[30:31]
	s_mov_b32 m0, s38
	s_nop 0
	global_load_lds_dwordx4 v132, s[30:31]
	s_waitcnt vmcnt(8)
	s_waitcnt lgkmcnt(0)
	s_barrier
	s_setprio 1
	s_waitcnt lgkmcnt(0)
	v_mfma_f32_16x16x32_bf16 v[124:127], v[160:163], v[192:195], v[124:127]
	v_mfma_f32_16x16x32_bf16 v[120:123], v[168:171], v[192:195], v[120:123]
	v_mfma_f32_16x16x32_bf16 v[108:111], v[160:163], v[200:203], v[108:111]
	v_mfma_f32_16x16x32_bf16 v[104:107], v[168:171], v[200:203], v[104:107]
	v_mfma_f32_16x16x32_bf16 v[92:95], v[160:163], v[208:211], v[92:95]
	v_mfma_f32_16x16x32_bf16 v[88:91], v[168:171], v[208:211], v[88:91]
	v_mfma_f32_16x16x32_bf16 v[76:79], v[160:163], v[216:219], v[76:79]
	v_mfma_f32_16x16x32_bf16 v[72:75], v[168:171], v[216:219], v[72:75]
	v_mfma_f32_16x16x32_bf16 v[124:127], v[164:167], v[196:199], v[124:127]
	v_mfma_f32_16x16x32_bf16 v[120:123], v[172:175], v[196:199], v[120:123]
	v_mfma_f32_16x16x32_bf16 v[108:111], v[164:167], v[204:207], v[108:111]
	v_mfma_f32_16x16x32_bf16 v[104:107], v[172:175], v[204:207], v[104:107]
	v_mfma_f32_16x16x32_bf16 v[92:95], v[164:167], v[212:215], v[92:95]
	v_mfma_f32_16x16x32_bf16 v[88:91], v[172:175], v[212:215], v[88:91]
	v_mfma_f32_16x16x32_bf16 v[76:79], v[164:167], v[220:223], v[76:79]
	v_mfma_f32_16x16x32_bf16 v[72:75], v[172:175], v[220:223], v[72:75]
	s_setprio 0
	s_setprio 1
	v_mfma_f32_16x16x32_bf16 v[116:119], v[176:179], v[192:195], v[116:119]
	v_mfma_f32_16x16x32_bf16 v[112:115], v[184:187], v[192:195], v[112:115]
	v_mfma_f32_16x16x32_bf16 v[100:103], v[176:179], v[200:203], v[100:103]
	v_mfma_f32_16x16x32_bf16 v[96:99], v[184:187], v[200:203], v[96:99]
	v_mfma_f32_16x16x32_bf16 v[84:87], v[176:179], v[208:211], v[84:87]
	v_mfma_f32_16x16x32_bf16 v[80:83], v[184:187], v[208:211], v[80:83]
	v_mfma_f32_16x16x32_bf16 v[68:71], v[176:179], v[216:219], v[68:71]
	v_mfma_f32_16x16x32_bf16 v[64:67], v[184:187], v[216:219], v[64:67]
	v_mfma_f32_16x16x32_bf16 v[116:119], v[180:183], v[196:199], v[116:119]
	v_mfma_f32_16x16x32_bf16 v[112:115], v[188:191], v[196:199], v[112:115]
	v_mfma_f32_16x16x32_bf16 v[100:103], v[180:183], v[204:207], v[100:103]
	v_mfma_f32_16x16x32_bf16 v[96:99], v[188:191], v[204:207], v[96:99]
	v_mfma_f32_16x16x32_bf16 v[84:87], v[180:183], v[212:215], v[84:87]
	v_mfma_f32_16x16x32_bf16 v[80:83], v[188:191], v[212:215], v[80:83]
	v_mfma_f32_16x16x32_bf16 v[68:71], v[180:183], v[220:223], v[68:71]
	v_mfma_f32_16x16x32_bf16 v[64:67], v[188:191], v[220:223], v[64:67]
	s_setprio 0
	s_barrier
	s_mov_b64 s[98:99], s[30:31]
	s_add_i32 s30, s55, s36
	s_mov_b32 m0, s30
	ds_read_b128 v[192:195], v158 offset:49152
	ds_read_b128 v[196:199], v158 offset:50176
	ds_read_b128 v[200:203], v158 offset:51200
	ds_read_b128 v[204:207], v158 offset:52224
	ds_read_b128 v[208:211], v158 offset:53248
	ds_read_b128 v[212:215], v158 offset:54272
	ds_read_b128 v[216:219], v158 offset:55296
	ds_read_b128 v[220:223], v158 offset:56320
	s_add_u32 s100, s28, 0x80
	s_addc_u32 s101, s29, 0
	global_load_lds_dwordx4 v130, s[100:101]
	s_add_i32 m0, s30, 0x2000
	s_add_u32 s28, s28, 0x80080
	s_addc_u32 s29, s29, 0
	s_add_i32 s30, s56, s36
	global_load_lds_dwordx4 v134, s[100:101]
	s_mov_b32 m0, s30
	s_nop 0
	global_load_lds_dwordx4 v130, s[28:29]
	s_add_i32 m0, s30, 0x2000
	s_nop 0
	global_load_lds_dwordx4 v134, s[28:29]
	s_mov_b32 m0, s40
	s_nop 0
	s_add_u32 s100, s98, 0xfff80080
	s_addc_u32 s101, s99, -1
	global_load_lds_dwordx4 v128, s[100:101]
	s_mov_b32 m0, s41
	s_nop 0
	global_load_lds_dwordx4 v132, s[100:101]
	s_waitcnt vmcnt(8)
	s_waitcnt lgkmcnt(0)
	s_barrier
	s_setprio 1
	s_waitcnt lgkmcnt(0)
	v_mfma_f32_16x16x32_bf16 v[60:63], v[160:163], v[192:195], v[60:63]
	v_mfma_f32_16x16x32_bf16 v[56:59], v[168:171], v[192:195], v[56:59]
	v_mfma_f32_16x16x32_bf16 v[44:47], v[160:163], v[200:203], v[44:47]
	v_mfma_f32_16x16x32_bf16 v[40:43], v[168:171], v[200:203], v[40:43]
	v_mfma_f32_16x16x32_bf16 v[28:31], v[160:163], v[208:211], v[28:31]
	v_mfma_f32_16x16x32_bf16 v[24:27], v[168:171], v[208:211], v[24:27]
	v_mfma_f32_16x16x32_bf16 v[12:15], v[160:163], v[216:219], v[12:15]
	v_mfma_f32_16x16x32_bf16 v[8:11], v[168:171], v[216:219], v[8:11]
	v_mfma_f32_16x16x32_bf16 v[60:63], v[164:167], v[196:199], v[60:63]
	v_mfma_f32_16x16x32_bf16 v[56:59], v[172:175], v[196:199], v[56:59]
	v_mfma_f32_16x16x32_bf16 v[44:47], v[164:167], v[204:207], v[44:47]
	v_mfma_f32_16x16x32_bf16 v[40:43], v[172:175], v[204:207], v[40:43]
	v_mfma_f32_16x16x32_bf16 v[28:31], v[164:167], v[212:215], v[28:31]
	v_mfma_f32_16x16x32_bf16 v[24:27], v[172:175], v[212:215], v[24:27]
	v_mfma_f32_16x16x32_bf16 v[12:15], v[164:167], v[220:223], v[12:15]
	v_mfma_f32_16x16x32_bf16 v[8:11], v[172:175], v[220:223], v[8:11]
	s_setprio 0
	s_setprio 1
	v_mfma_f32_16x16x32_bf16 v[52:55], v[176:179], v[192:195], v[52:55]
	v_mfma_f32_16x16x32_bf16 v[48:51], v[184:187], v[192:195], v[48:51]
	v_mfma_f32_16x16x32_bf16 v[36:39], v[176:179], v[200:203], v[36:39]
	v_mfma_f32_16x16x32_bf16 v[32:35], v[184:187], v[200:203], v[32:35]
	v_mfma_f32_16x16x32_bf16 v[20:23], v[176:179], v[208:211], v[20:23]
	v_mfma_f32_16x16x32_bf16 v[16:19], v[184:187], v[208:211], v[16:19]
	v_mfma_f32_16x16x32_bf16 v[4:7], v[176:179], v[216:219], v[4:7]
	v_mfma_f32_16x16x32_bf16 v[0:3], v[184:187], v[216:219], v[0:3]
	v_mfma_f32_16x16x32_bf16 v[52:55], v[180:183], v[196:199], v[52:55]
	v_mfma_f32_16x16x32_bf16 v[48:51], v[188:191], v[196:199], v[48:51]
	v_mfma_f32_16x16x32_bf16 v[36:39], v[180:183], v[204:207], v[36:39]
	v_mfma_f32_16x16x32_bf16 v[32:35], v[188:191], v[204:207], v[32:35]
	v_mfma_f32_16x16x32_bf16 v[20:23], v[180:183], v[212:215], v[20:23]
	v_mfma_f32_16x16x32_bf16 v[16:19], v[188:191], v[212:215], v[16:19]
	v_mfma_f32_16x16x32_bf16 v[4:7], v[180:183], v[220:223], v[4:7]
	v_mfma_f32_16x16x32_bf16 v[0:3], v[188:191], v[220:223], v[0:3]
	s_setprio 0
	s_barrier
	s_add_u32 s26, s26, 0x100
	s_addc_u32 s27, s27, 0
	s_add_u32 s52, s52, 0x100
	s_addc_u32 s53, s53, 0
	s_cmp_ge_u32 s54, s50
	s_mov_b32 s30, s54
	s_cbranch_scc0 .LBB0_1737
	s_and_b64 vcc, exec, s[10:11]
	s_cbranch_vccz .LBB0_1740
	s_barrier

; #define PG8_STAGE(bufoff, gbase, voff) do { _Pragma("unroll") for (int _i = 0; _i < 2; ++_i) \
;         __builtin_amdgcn_global_load_lds((const unsigned*)((const char*)(gbase) + (voff)[_i]), (LAS unsigned*)(lds + (bufoff) + ldsw + _i * 8192), 16, 0, 0); } while (0)
; #define PG8_LDA(dst, b, h) do { _Pragma("unroll") for (int m = 0; m < 4; ++m) _Pragma("unroll") for (int k = 0; k < 2; ++k) dst[m][k] = *(const LAS bf16x8*)(lds + PG8_SA(b, h) + aoff + m * 2048 + k * 1024); } while (0)
; #define PG8_LDB(dst, b, h) do { _Pragma("unroll") for (int n = 0; n < 2; ++n) _Pragma("unroll") for (int k = 0; k < 2; ++k) dst[n][k] = *(const LAS bf16x8*)(lds + PG8_SB(b, h) + boff + n * 2048 + k * 1024); } while (0)
; #define PG8_MMA(ai, bj, At, Bt) do { __builtin_amdgcn_s_setprio(1); _Pragma("unroll") for (int m = 0; m < 4; ++m) _Pragma("unroll") for (int n = 0; n < 2; ++n) _Pragma("unroll") for (int k = 0; k < 2; ++k) \
;         acc[ai][bj][m][n] = __builtin_amdgcn_mfma_f32_16x16x32_bf16(Bt[n][k], At[m][k], acc[ai][bj][m][n], 0, 0, 0); __builtin_amdgcn_s_setprio(0); } while (0)
; #define PG8_WAIT_V(n) asm volatile("s_waitcnt vmcnt(" #n ")" ::: "memory")
; #define PG8_WAIT_L(n) asm volatile("s_waitcnt lgkmcnt(" #n ")" ::: "memory")
; #define PG8_BAR __builtin_amdgcn_s_barrier()
; #define PG8_SCHED __builtin_amdgcn_sched_barrier(0)
; __device__ __forceinline__ void gemm_phase(LAS unsigned char* lds, const Params& p, const bf16_t* gA, const bf16_t* gBt, const int gM, const int gN, const int gK, const int epi, const int perm, bf16_t* const Hp, const int goff, const float coef) {
;     ...
;         const int nt = cur.ks >= 0 ? ntf / 4 : ntf;
;         for (int t = 0; t < nt; t += 2) {
;             const bool last = (t == nt - 2);
;             const char* a1 = cA + (size_t)(t + 1) * kstep;
;             const char* a2 = last ? nA : cA + (size_t)(t + 2) * kstep; const char* b2 = last ? nB : cB + (size_t)(t + 2) * kstep;
;             const char* a3 = a2 + kstep; const char* b3 = b2 + kstep;
;             PG8_LDB(B0, 0, 0); PG8_LDB(B1, 0, 1); PG8_SCHED; PG8_LDA(At, 0, 0); PG8_STAGE(PG8_SA(1, 1), a1 + hstep, voffA);
;             PG8_WAIT_V(8); PG8_WAIT_L(0); PG8_BAR; PG8_MMA(0, 0, At, B0); PG8_MMA(0, 1, At, B1); PG8_BAR; PG8_SCHED;
.LBB0_1826:
	s_cmp_gt_i32 s6, -1
	s_cselect_b64 s[4:5], -1, 0
	s_and_b64 s[22:23], s[4:5], exec
	s_cselect_b32 s50, 22, 0x58
	s_add_i32 s51, s50, -2
	s_add_u32 s18, s18, 0x160080
	s_addc_u32 s19, s19, 0
	s_add_u32 s52, s20, 0x100
	v_mov_b32_e32 v0, 0
	s_addc_u32 s53, s21, 0
	s_mov_b32 s20, 0
	v_mov_b32_e32 v1, v0
	v_mov_b32_e32 v2, v0
	v_mov_b32_e32 v3, v0
	v_mov_b32_e32 v4, v0
	v_mov_b32_e32 v5, v0
	v_mov_b32_e32 v6, v0
	v_mov_b32_e32 v7, v0
	v_mov_b32_e32 v8, v0
	v_mov_b32_e32 v9, v0
	v_mov_b32_e32 v10, v0
	v_mov_b32_e32 v11, v0
	v_mov_b32_e32 v12, v0
	v_mov_b32_e32 v13, v0
	v_mov_b32_e32 v14, v0
	v_mov_b32_e32 v15, v0
	v_mov_b32_e32 v16, v0
	v_mov_b32_e32 v17, v0
	v_mov_b32_e32 v18, v0
	v_mov_b32_e32 v19, v0
	v_mov_b32_e32 v20, v0
	v_mov_b32_e32 v21, v0
	v_mov_b32_e32 v22, v0
	v_mov_b32_e32 v23, v0
	v_mov_b32_e32 v24, v0
	v_mov_b32_e32 v25, v0
	v_mov_b32_e32 v26, v0
	v_mov_b32_e32 v27, v0
	v_mov_b32_e32 v28, v0
	v_mov_b32_e32 v29, v0
	v_mov_b32_e32 v30, v0
	v_mov_b32_e32 v31, v0
	v_mov_b32_e32 v56, v0
	v_mov_b32_e32 v57, v0
	v_mov_b32_e32 v58, v0
	v_mov_b32_e32 v59, v0
	v_mov_b32_e32 v64, v0
	v_mov_b32_e32 v65, v0
	v_mov_b32_e32 v66, v0
	v_mov_b32_e32 v67, v0
	v_mov_b32_e32 v72, v0
	v_mov_b32_e32 v73, v0
	v_mov_b32_e32 v74, v0
	v_mov_b32_e32 v75, v0
	v_mov_b32_e32 v76, v0
	v_mov_b32_e32 v77, v0
	v_mov_b32_e32 v78, v0
	v_mov_b32_e32 v79, v0
	v_mov_b32_e32 v80, v0
	v_mov_b32_e32 v81, v0
	v_mov_b32_e32 v82, v0
	v_mov_b32_e32 v83, v0
	v_mov_b32_e32 v84, v0
	v_mov_b32_e32 v85, v0
	v_mov_b32_e32 v86, v0
	v_mov_b32_e32 v87, v0
	v_mov_b32_e32 v88, v0
	v_mov_b32_e32 v89, v0
	v_mov_b32_e32 v90, v0
	v_mov_b32_e32 v91, v0
	v_mov_b32_e32 v92, v0
	v_mov_b32_e32 v93, v0
	v_mov_b32_e32 v94, v0
	v_mov_b32_e32 v95, v0
	v_mov_b32_e32 v32, v0
	v_mov_b32_e32 v33, v0
	v_mov_b32_e32 v34, v0
	v_mov_b32_e32 v35, v0
	v_mov_b32_e32 v36, v0
	v_mov_b32_e32 v37, v0
	v_mov_b32_e32 v38, v0
	v_mov_b32_e32 v39, v0
	v_mov_b32_e32 v40, v0
	v_mov_b32_e32 v41, v0
	v_mov_b32_e32 v42, v0
	v_mov_b32_e32 v43, v0
	v_mov_b32_e32 v44, v0
	v_mov_b32_e32 v45, v0
	v_mov_b32_e32 v46, v0
	v_mov_b32_e32 v47, v0
	v_mov_b32_e32 v48, v0
	v_mov_b32_e32 v49, v0
	v_mov_b32_e32 v50, v0
	v_mov_b32_e32 v51, v0
	v_mov_b32_e32 v52, v0
	v_mov_b32_e32 v53, v0
	v_mov_b32_e32 v54, v0
	v_mov_b32_e32 v55, v0
	v_mov_b32_e32 v60, v0
	v_mov_b32_e32 v61, v0
	v_mov_b32_e32 v62, v0
	v_mov_b32_e32 v63, v0
	v_mov_b32_e32 v68, v0
	v_mov_b32_e32 v69, v0
	v_mov_b32_e32 v70, v0
	v_mov_b32_e32 v71, v0
	v_mov_b32_e32 v96, v0
	v_mov_b32_e32 v97, v0
	v_mov_b32_e32 v98, v0
	v_mov_b32_e32 v99, v0
	v_mov_b32_e32 v100, v0
	v_mov_b32_e32 v101, v0
	v_mov_b32_e32 v102, v0
	v_mov_b32_e32 v103, v0
	v_mov_b32_e32 v104, v0
	v_mov_b32_e32 v105, v0
	v_mov_b32_e32 v106, v0
	v_mov_b32_e32 v107, v0
	v_mov_b32_e32 v108, v0
	v_mov_b32_e32 v109, v0
	v_mov_b32_e32 v110, v0
	v_mov_b32_e32 v111, v0
	v_mov_b32_e32 v112, v0
	v_mov_b32_e32 v113, v0
	v_mov_b32_e32 v114, v0
	v_mov_b32_e32 v115, v0
	v_mov_b32_e32 v116, v0
	v_mov_b32_e32 v117, v0
	v_mov_b32_e32 v118, v0
	v_mov_b32_e32 v119, v0
	v_mov_b32_e32 v120, v0
	v_mov_b32_e32 v121, v0
	v_mov_b32_e32 v122, v0
	v_mov_b32_e32 v123, v0
	v_mov_b32_e32 v124, v0
	v_mov_b32_e32 v125, v0
	v_mov_b32_e32 v126, v0
	v_mov_b32_e32 v127, v0
	v_add_u32_e32 v222, 0x18000, v157
	v_add_u32_e32 v223, 0x1c000, v157
.LBB0_1827:
	ds_read_b128 v[144:147], v166
	ds_read_b128 v[148:151], v166 offset:1024
	ds_read_b128 v[152:155], v166 offset:2048
	ds_read_b128 v[170:173], v166 offset:3072
	ds_read_b128 v[174:177], v167
	ds_read_b128 v[178:181], v167 offset:1024
	ds_read_b128 v[182:185], v167 offset:2048
	ds_read_b128 v[186:189], v167 offset:3072
	s_add_i32 s54, s20, 2
	s_add_u32 s21, s18, 0xffea0080
	s_addc_u32 s22, s19, -1
	s_cmp_eq_u32 s51, s20
	s_cselect_b32 s20, s16, s52
	s_cselect_b32 s23, s15, s22
	s_cselect_b32 s22, s14, s21
	s_cselect_b32 s21, s17, s53
	s_add_i32 m0, s28, 0xc000
	ds_read_b128 v[190:193], v168
	ds_read_b128 v[194:197], v168 offset:1024
	ds_read_b128 v[198:201], v168 offset:2048
	ds_read_b128 v[202:205], v168 offset:3072
	ds_read_b128 v[206:209], v168 offset:4096
	ds_read_b128 v[210:213], v168 offset:5120
	ds_read_b128 v[214:217], v168 offset:6144
	ds_read_b128 v[218:221], v168 offset:7168
	global_load_lds_dwordx4 v136, s[18:19]
	s_add_i32 m0, s28, 0xe000
	s_nop 0
	global_load_lds_dwordx4 v138, s[18:19]
	s_waitcnt vmcnt(8)
	s_waitcnt lgkmcnt(0)
	s_barrier
	s_setprio 1
	s_waitcnt lgkmcnt(0)
	v_mfma_f32_16x16x32_bf16 v[124:127], v[144:147], v[190:193], v[124:127]
	v_mfma_f32_16x16x32_bf16 v[120:123], v[152:155], v[190:193], v[120:123]
	v_mfma_f32_16x16x32_bf16 v[116:119], v[144:147], v[198:201], v[116:119]
	v_mfma_f32_16x16x32_bf16 v[112:115], v[152:155], v[198:201], v[112:115]
	v_mfma_f32_16x16x32_bf16 v[108:111], v[144:147], v[206:209], v[108:111]
	v_mfma_f32_16x16x32_bf16 v[104:107], v[152:155], v[206:209], v[104:107]
	v_mfma_f32_16x16x32_bf16 v[100:103], v[144:147], v[214:217], v[100:103]
	v_mfma_f32_16x16x32_bf16 v[96:99], v[152:155], v[214:217], v[96:99]
	v_mfma_f32_16x16x32_bf16 v[124:127], v[148:151], v[194:197], v[124:127]
	v_mfma_f32_16x16x32_bf16 v[120:123], v[170:173], v[194:197], v[120:123]
	v_mfma_f32_16x16x32_bf16 v[116:119], v[148:151], v[202:205], v[116:119]
	v_mfma_f32_16x16x32_bf16 v[112:115], v[170:173], v[202:205], v[112:115]
	v_mfma_f32_16x16x32_bf16 v[108:111], v[148:151], v[210:213], v[108:111]
	v_mfma_f32_16x16x32_bf16 v[104:107], v[170:173], v[210:213], v[104:107]
	v_mfma_f32_16x16x32_bf16 v[100:103], v[148:151], v[218:221], v[100:103]
	v_mfma_f32_16x16x32_bf16 v[96:99], v[170:173], v[218:221], v[96:99]
	s_setprio 0
	s_setprio 1
	v_mfma_f32_16x16x32_bf16 v[68:71], v[174:177], v[190:193], v[68:71]
	v_mfma_f32_16x16x32_bf16 v[60:63], v[182:185], v[190:193], v[60:63]
	v_mfma_f32_16x16x32_bf16 v[52:55], v[174:177], v[198:201], v[52:55]
	v_mfma_f32_16x16x32_bf16 v[48:51], v[182:185], v[198:201], v[48:51]
	v_mfma_f32_16x16x32_bf16 v[44:47], v[174:177], v[206:209], v[44:47]
	v_mfma_f32_16x16x32_bf16 v[40:43], v[182:185], v[206:209], v[40:43]
	v_mfma_f32_16x16x32_bf16 v[36:39], v[174:177], v[214:217], v[36:39]
	v_mfma_f32_16x16x32_bf16 v[32:35], v[182:185], v[214:217], v[32:35]
	v_mfma_f32_16x16x32_bf16 v[68:71], v[178:181], v[194:197], v[68:71]
	v_mfma_f32_16x16x32_bf16 v[60:63], v[186:189], v[194:197], v[60:63]
	v_mfma_f32_16x16x32_bf16 v[52:55], v[178:181], v[202:205], v[52:55]
	v_mfma_f32_16x16x32_bf16 v[48:51], v[186:189], v[202:205], v[48:51]
	v_mfma_f32_16x16x32_bf16 v[44:47], v[178:181], v[210:213], v[44:47]
	v_mfma_f32_16x16x32_bf16 v[40:43], v[186:189], v[210:213], v[40:43]
	v_mfma_f32_16x16x32_bf16 v[36:39], v[178:181], v[218:221], v[36:39]
	v_mfma_f32_16x16x32_bf16 v[32:35], v[186:189], v[218:221], v[32:35]
	s_setprio 0
	s_barrier
; #define PG8_STAGE(bufoff, gbase, voff) do { _Pragma("unroll") for (int _i = 0; _i < 2; ++_i) \
;         __builtin_amdgcn_global_load_lds((const unsigned*)((const char*)(gbase) + (voff)[_i]), (LAS unsigned*)(lds + (bufoff) + ldsw + _i * 8192), 16, 0, 0); } while (0)
; #define PG8_LDA(dst, b, h) do { _Pragma("unroll") for (int m = 0; m < 4; ++m) _Pragma("unroll") for (int k = 0; k < 2; ++k) dst[m][k] = *(const LAS bf16x8*)(lds + PG8_SA(b, h) + aoff + m * 2048 + k * 1024); } while (0)
; #define PG8_LDB(dst, b, h) do { _Pragma("unroll") for (int n = 0; n < 2; ++n) _Pragma("unroll") for (int k = 0; k < 2; ++k) dst[n][k] = *(const LAS bf16x8*)(lds + PG8_SB(b, h) + boff + n * 2048 + k * 1024); } while (0)
; #define PG8_MMA(ai, bj, At, Bt) do { __builtin_amdgcn_s_setprio(1); _Pragma("unroll") for (int m = 0; m < 4; ++m) _Pragma("unroll") for (int n = 0; n < 2; ++n) _Pragma("unroll") for (int k = 0; k < 2; ++k) \
;         acc[ai][bj][m][n] = __builtin_amdgcn_mfma_f32_16x16x32_bf16(Bt[n][k], At[m][k], acc[ai][bj][m][n], 0, 0, 0); __builtin_amdgcn_s_setprio(0); } while (0)
; #define PG8_WAIT_V(n) asm volatile("s_waitcnt vmcnt(" #n ")" ::: "memory")
; #define PG8_WAIT_L(n) asm volatile("s_waitcnt lgkmcnt(" #n ")" ::: "memory")
; #define PG8_BAR __builtin_amdgcn_s_barrier()
; #define PG8_SCHED __builtin_amdgcn_sched_barrier(0)
; __device__ __forceinline__ void gemm_phase(LAS unsigned char* lds, const Params& p, const bf16_t* gA, const bf16_t* gBt, const int gM, const int gN, const int gK, const int epi, const int perm, bf16_t* const Hp, const int goff, const float coef) {
;     ...
;             PG8_LDA(At, 0, 1); PG8_STAGE(PG8_SB(0, 0), b2, voffB); PG8_STAGE(PG8_SB(0, 1), b2 + hstep, voffB); PG8_STAGE(PG8_SA(0, 0), a2, voffA);
;             PG8_WAIT_V(8); PG8_WAIT_L(0); PG8_BAR; PG8_MMA(1, 0, At, B0); PG8_MMA(1, 1, At, B1); PG8_BAR; PG8_SCHED;
;             PG8_LDB(B0, 1, 0); PG8_LDB(B1, 1, 1); PG8_SCHED; PG8_LDA(At, 1, 0); PG8_STAGE(PG8_SA(0, 1), a2 + hstep, voffA);
;             PG8_WAIT_V(8); PG8_WAIT_L(0); PG8_BAR; PG8_MMA(0, 0, At, B0); PG8_MMA(0, 1, At, B1); PG8_BAR; PG8_SCHED;
	s_add_i32 s55, s42, s27
	s_mov_b32 m0, s55
	ds_read_b128 v[190:193], v168 offset:16384
	ds_read_b128 v[194:197], v168 offset:17408
	ds_read_b128 v[198:201], v168 offset:18432
	ds_read_b128 v[202:205], v168 offset:19456
	ds_read_b128 v[206:209], v168 offset:20480
	ds_read_b128 v[210:213], v168 offset:21504
	ds_read_b128 v[214:217], v168 offset:22528
	ds_read_b128 v[218:221], v168 offset:23552
	global_load_lds_dwordx4 v130, s[20:21]
	s_add_i32 m0, s55, 0x2000
	s_add_u32 s56, s20, 0x160000
	s_addc_u32 s57, s21, 0
	s_add_i32 s55, s43, s27
	global_load_lds_dwordx4 v134, s[20:21]
	s_mov_b32 m0, s55
	s_nop 0
	global_load_lds_dwordx4 v130, s[56:57]
	s_add_i32 m0, s55, 0x2000
	s_nop 0
	global_load_lds_dwordx4 v134, s[56:57]
	s_mov_b32 m0, s28
	s_nop 0
	global_load_lds_dwordx4 v128, s[22:23]
	s_mov_b32 m0, s29
	s_nop 0
	global_load_lds_dwordx4 v132, s[22:23]
	s_waitcnt vmcnt(8)
	s_waitcnt lgkmcnt(0)
	s_barrier
	s_setprio 1
	s_waitcnt lgkmcnt(0)
	v_mfma_f32_16x16x32_bf16 v[92:95], v[144:147], v[190:193], v[92:95]
	v_mfma_f32_16x16x32_bf16 v[88:91], v[152:155], v[190:193], v[88:91]
	v_mfma_f32_16x16x32_bf16 v[84:87], v[144:147], v[198:201], v[84:87]
	v_mfma_f32_16x16x32_bf16 v[80:83], v[152:155], v[198:201], v[80:83]
	v_mfma_f32_16x16x32_bf16 v[76:79], v[144:147], v[206:209], v[76:79]
	v_mfma_f32_16x16x32_bf16 v[72:75], v[152:155], v[206:209], v[72:75]
	v_mfma_f32_16x16x32_bf16 v[64:67], v[144:147], v[214:217], v[64:67]
	v_mfma_f32_16x16x32_bf16 v[56:59], v[152:155], v[214:217], v[56:59]
	v_mfma_f32_16x16x32_bf16 v[92:95], v[148:151], v[194:197], v[92:95]
	v_mfma_f32_16x16x32_bf16 v[88:91], v[170:173], v[194:197], v[88:91]
	v_mfma_f32_16x16x32_bf16 v[84:87], v[148:151], v[202:205], v[84:87]
	v_mfma_f32_16x16x32_bf16 v[80:83], v[170:173], v[202:205], v[80:83]
	v_mfma_f32_16x16x32_bf16 v[76:79], v[148:151], v[210:213], v[76:79]
	v_mfma_f32_16x16x32_bf16 v[72:75], v[170:173], v[210:213], v[72:75]
	v_mfma_f32_16x16x32_bf16 v[64:67], v[148:151], v[218:221], v[64:67]
	v_mfma_f32_16x16x32_bf16 v[56:59], v[170:173], v[218:221], v[56:59]
	s_setprio 0
	s_setprio 1
	v_mfma_f32_16x16x32_bf16 v[28:31], v[174:177], v[190:193], v[28:31]
	v_mfma_f32_16x16x32_bf16 v[24:27], v[182:185], v[190:193], v[24:27]
	v_mfma_f32_16x16x32_bf16 v[20:23], v[174:177], v[198:201], v[20:23]
	v_mfma_f32_16x16x32_bf16 v[16:19], v[182:185], v[198:201], v[16:19]
	v_mfma_f32_16x16x32_bf16 v[12:15], v[174:177], v[206:209], v[12:15]
	v_mfma_f32_16x16x32_bf16 v[8:11], v[182:185], v[206:209], v[8:11]
	v_mfma_f32_16x16x32_bf16 v[4:7], v[174:177], v[214:217], v[4:7]
	v_mfma_f32_16x16x32_bf16 v[0:3], v[182:185], v[214:217], v[0:3]
	v_mfma_f32_16x16x32_bf16 v[28:31], v[178:181], v[194:197], v[28:31]
	v_mfma_f32_16x16x32_bf16 v[24:27], v[186:189], v[194:197], v[24:27]
	v_mfma_f32_16x16x32_bf16 v[20:23], v[178:181], v[202:205], v[20:23]
	v_mfma_f32_16x16x32_bf16 v[16:19], v[186:189], v[202:205], v[16:19]
	v_mfma_f32_16x16x32_bf16 v[12:15], v[178:181], v[210:213], v[12:15]
	v_mfma_f32_16x16x32_bf16 v[8:11], v[186:189], v[210:213], v[8:11]
	v_mfma_f32_16x16x32_bf16 v[4:7], v[178:181], v[218:221], v[4:7]
	v_mfma_f32_16x16x32_bf16 v[0:3], v[186:189], v[218:221], v[0:3]
	s_setprio 0
	s_barrier
	s_add_i32 s55, 0, 0x18000
	s_add_i32 s56, 0, 0x1c000
	ds_read_b128 v[144:147], v222
	ds_read_b128 v[148:151], v222 offset:1024
	ds_read_b128 v[152:155], v222 offset:2048
	ds_read_b128 v[170:173], v222 offset:3072
	ds_read_b128 v[174:177], v223
	ds_read_b128 v[178:181], v223 offset:1024
	ds_read_b128 v[182:185], v223 offset:2048
	ds_read_b128 v[186:189], v223 offset:3072
	s_add_u32 s22, s22, 0x160000
	s_addc_u32 s23, s23, 0
	s_mov_b32 m0, s30
	ds_read_b128 v[190:193], v168 offset:32768
	ds_read_b128 v[194:197], v168 offset:33792
	ds_read_b128 v[198:201], v168 offset:34816
	ds_read_b128 v[202:205], v168 offset:35840
	ds_read_b128 v[206:209], v168 offset:36864
	ds_read_b128 v[210:213], v168 offset:37888
	ds_read_b128 v[214:217], v168 offset:38912
	ds_read_b128 v[218:221], v168 offset:39936
	global_load_lds_dwordx4 v128, s[22:23]
	s_mov_b32 m0, s31
	s_nop 0
	global_load_lds_dwordx4 v132, s[22:23]
	s_waitcnt vmcnt(8)
	s_waitcnt lgkmcnt(0)
	s_barrier
; #define PG8_STAGE(bufoff, gbase, voff) do { _Pragma("unroll") for (int _i = 0; _i < 2; ++_i) \
;         __builtin_amdgcn_global_load_lds((const unsigned*)((const char*)(gbase) + (voff)[_i]), (LAS unsigned*)(lds + (bufoff) + ldsw + _i * 8192), 16, 0, 0); } while (0)
; #define PG8_LDA(dst, b, h) do { _Pragma("unroll") for (int m = 0; m < 4; ++m) _Pragma("unroll") for (int k = 0; k < 2; ++k) dst[m][k] = *(const LAS bf16x8*)(lds + PG8_SA(b, h) + aoff + m * 2048 + k * 1024); } while (0)
; #define PG8_MMA(ai, bj, At, Bt) do { __builtin_amdgcn_s_setprio(1); _Pragma("unroll") for (int m = 0; m < 4; ++m) _Pragma("unroll") for (int n = 0; n < 2; ++n) _Pragma("unroll") for (int k = 0; k < 2; ++k) \
;         acc[ai][bj][m][n] = __builtin_amdgcn_mfma_f32_16x16x32_bf16(Bt[n][k], At[m][k], acc[ai][bj][m][n], 0, 0, 0); __builtin_amdgcn_s_setprio(0); } while (0)
; #define PG8_WAIT_V(n) asm volatile("s_waitcnt vmcnt(" #n ")" ::: "memory")
; #define PG8_WAIT_L(n) asm volatile("s_waitcnt lgkmcnt(" #n ")" ::: "memory")
; #define PG8_BAR __builtin_amdgcn_s_barrier()
; #define PG8_SCHED __builtin_amdgcn_sched_barrier(0)
; __device__ __forceinline__ void gemm_phase(LAS unsigned char* lds, const Params& p, const bf16_t* gA, const bf16_t* gBt, const int gM, const int gN, const int gK, const int epi, const int perm, bf16_t* const Hp, const int goff, const float coef) {
;     ...
;             PG8_WAIT_V(8); PG8_WAIT_L(0); PG8_BAR; PG8_MMA(0, 0, At, B0); PG8_MMA(0, 1, At, B1); PG8_BAR; PG8_SCHED;
;             PG8_LDA(At, 1, 1); PG8_STAGE(PG8_SB(1, 0), b3, voffB); PG8_STAGE(PG8_SB(1, 1), b3 + hstep, voffB); PG8_STAGE(PG8_SA(1, 0), a3, voffA);
;             PG8_WAIT_V(8); PG8_WAIT_L(0); PG8_BAR; PG8_MMA(1, 0, At, B0); PG8_MMA(1, 1, At, B1); PG8_BAR; PG8_SCHED;
;         }
	s_setprio 1
	s_waitcnt lgkmcnt(0)
	v_mfma_f32_16x16x32_bf16 v[124:127], v[144:147], v[190:193], v[124:127]
	v_mfma_f32_16x16x32_bf16 v[120:123], v[152:155], v[190:193], v[120:123]
	v_mfma_f32_16x16x32_bf16 v[116:119], v[144:147], v[198:201], v[116:119]
	v_mfma_f32_16x16x32_bf16 v[112:115], v[152:155], v[198:201], v[112:115]
	v_mfma_f32_16x16x32_bf16 v[108:111], v[144:147], v[206:209], v[108:111]
	v_mfma_f32_16x16x32_bf16 v[104:107], v[152:155], v[206:209], v[104:107]
	v_mfma_f32_16x16x32_bf16 v[100:103], v[144:147], v[214:217], v[100:103]
	v_mfma_f32_16x16x32_bf16 v[96:99], v[152:155], v[214:217], v[96:99]
	v_mfma_f32_16x16x32_bf16 v[124:127], v[148:151], v[194:197], v[124:127]
	v_mfma_f32_16x16x32_bf16 v[120:123], v[170:173], v[194:197], v[120:123]
	v_mfma_f32_16x16x32_bf16 v[116:119], v[148:151], v[202:205], v[116:119]
	v_mfma_f32_16x16x32_bf16 v[112:115], v[170:173], v[202:205], v[112:115]
	v_mfma_f32_16x16x32_bf16 v[108:111], v[148:151], v[210:213], v[108:111]
	v_mfma_f32_16x16x32_bf16 v[104:107], v[170:173], v[210:213], v[104:107]
	v_mfma_f32_16x16x32_bf16 v[100:103], v[148:151], v[218:221], v[100:103]
	v_mfma_f32_16x16x32_bf16 v[96:99], v[170:173], v[218:221], v[96:99]
	s_setprio 0
	s_setprio 1
	v_mfma_f32_16x16x32_bf16 v[68:71], v[174:177], v[190:193], v[68:71]
	v_mfma_f32_16x16x32_bf16 v[60:63], v[182:185], v[190:193], v[60:63]
	v_mfma_f32_16x16x32_bf16 v[52:55], v[174:177], v[198:201], v[52:55]
	v_mfma_f32_16x16x32_bf16 v[48:51], v[182:185], v[198:201], v[48:51]
	v_mfma_f32_16x16x32_bf16 v[44:47], v[174:177], v[206:209], v[44:47]
	v_mfma_f32_16x16x32_bf16 v[40:43], v[182:185], v[206:209], v[40:43]
	v_mfma_f32_16x16x32_bf16 v[36:39], v[174:177], v[214:217], v[36:39]
	v_mfma_f32_16x16x32_bf16 v[32:35], v[182:185], v[214:217], v[32:35]
	v_mfma_f32_16x16x32_bf16 v[68:71], v[178:181], v[194:197], v[68:71]
	v_mfma_f32_16x16x32_bf16 v[60:63], v[186:189], v[194:197], v[60:63]
	v_mfma_f32_16x16x32_bf16 v[52:55], v[178:181], v[202:205], v[52:55]
	v_mfma_f32_16x16x32_bf16 v[48:51], v[186:189], v[202:205], v[48:51]
	v_mfma_f32_16x16x32_bf16 v[44:47], v[178:181], v[210:213], v[44:47]
	v_mfma_f32_16x16x32_bf16 v[40:43], v[186:189], v[210:213], v[40:43]
	v_mfma_f32_16x16x32_bf16 v[36:39], v[178:181], v[218:221], v[36:39]
	v_mfma_f32_16x16x32_bf16 v[32:35], v[186:189], v[218:221], v[32:35]
	s_setprio 0
	s_barrier
	s_mov_b64 s[98:99], s[22:23]
	s_add_i32 s22, s55, s27
	s_mov_b32 m0, s22
	ds_read_b128 v[190:193], v168 offset:49152
	ds_read_b128 v[194:197], v168 offset:50176
	ds_read_b128 v[198:201], v168 offset:51200
	ds_read_b128 v[202:205], v168 offset:52224
	ds_read_b128 v[206:209], v168 offset:53248
	ds_read_b128 v[210:213], v168 offset:54272
	ds_read_b128 v[214:217], v168 offset:55296
	ds_read_b128 v[218:221], v168 offset:56320
	s_add_u32 s100, s20, 0x80
	s_addc_u32 s101, s21, 0
	global_load_lds_dwordx4 v130, s[100:101]
	s_add_i32 m0, s22, 0x2000
	s_add_u32 s20, s20, 0x160080
	s_addc_u32 s21, s21, 0
	s_add_i32 s22, s56, s27
	global_load_lds_dwordx4 v134, s[100:101]
	s_mov_b32 m0, s22
	s_nop 0
	global_load_lds_dwordx4 v130, s[20:21]
	s_add_i32 m0, s22, 0x2000
	s_nop 0
	global_load_lds_dwordx4 v134, s[20:21]
	s_mov_b32 m0, s36
	s_nop 0
	s_add_u32 s100, s98, 0xffea0080
	s_addc_u32 s101, s99, -1
	global_load_lds_dwordx4 v128, s[100:101]
	s_mov_b32 m0, s37
	s_nop 0
	global_load_lds_dwordx4 v132, s[100:101]
	s_waitcnt vmcnt(8)
	s_waitcnt lgkmcnt(0)
	s_barrier
	s_setprio 1
	s_waitcnt lgkmcnt(0)
	v_mfma_f32_16x16x32_bf16 v[92:95], v[144:147], v[190:193], v[92:95]
	v_mfma_f32_16x16x32_bf16 v[88:91], v[152:155], v[190:193], v[88:91]
	v_mfma_f32_16x16x32_bf16 v[84:87], v[144:147], v[198:201], v[84:87]
	v_mfma_f32_16x16x32_bf16 v[80:83], v[152:155], v[198:201], v[80:83]
	v_mfma_f32_16x16x32_bf16 v[76:79], v[144:147], v[206:209], v[76:79]
	v_mfma_f32_16x16x32_bf16 v[72:75], v[152:155], v[206:209], v[72:75]
	v_mfma_f32_16x16x32_bf16 v[64:67], v[144:147], v[214:217], v[64:67]
	v_mfma_f32_16x16x32_bf16 v[56:59], v[152:155], v[214:217], v[56:59]
	v_mfma_f32_16x16x32_bf16 v[92:95], v[148:151], v[194:197], v[92:95]
	v_mfma_f32_16x16x32_bf16 v[88:91], v[170:173], v[194:197], v[88:91]
	v_mfma_f32_16x16x32_bf16 v[84:87], v[148:151], v[202:205], v[84:87]
	v_mfma_f32_16x16x32_bf16 v[80:83], v[170:173], v[202:205], v[80:83]
	v_mfma_f32_16x16x32_bf16 v[76:79], v[148:151], v[210:213], v[76:79]
	v_mfma_f32_16x16x32_bf16 v[72:75], v[170:173], v[210:213], v[72:75]
	v_mfma_f32_16x16x32_bf16 v[64:67], v[148:151], v[218:221], v[64:67]
	v_mfma_f32_16x16x32_bf16 v[56:59], v[170:173], v[218:221], v[56:59]
	s_setprio 0
	s_setprio 1
	v_mfma_f32_16x16x32_bf16 v[28:31], v[174:177], v[190:193], v[28:31]
	v_mfma_f32_16x16x32_bf16 v[24:27], v[182:185], v[190:193], v[24:27]
	v_mfma_f32_16x16x32_bf16 v[20:23], v[174:177], v[198:201], v[20:23]
	v_mfma_f32_16x16x32_bf16 v[16:19], v[182:185], v[198:201], v[16:19]
	v_mfma_f32_16x16x32_bf16 v[12:15], v[174:177], v[206:209], v[12:15]
	v_mfma_f32_16x16x32_bf16 v[8:11], v[182:185], v[206:209], v[8:11]
	v_mfma_f32_16x16x32_bf16 v[4:7], v[174:177], v[214:217], v[4:7]
	v_mfma_f32_16x16x32_bf16 v[0:3], v[182:185], v[214:217], v[0:3]
	v_mfma_f32_16x16x32_bf16 v[28:31], v[178:181], v[194:197], v[28:31]
	v_mfma_f32_16x16x32_bf16 v[24:27], v[186:189], v[194:197], v[24:27]
	v_mfma_f32_16x16x32_bf16 v[20:23], v[178:181], v[202:205], v[20:23]
	v_mfma_f32_16x16x32_bf16 v[16:19], v[186:189], v[202:205], v[16:19]
	v_mfma_f32_16x16x32_bf16 v[12:15], v[178:181], v[210:213], v[12:15]
	v_mfma_f32_16x16x32_bf16 v[8:11], v[186:189], v[210:213], v[8:11]
	v_mfma_f32_16x16x32_bf16 v[4:7], v[178:181], v[218:221], v[4:7]
	v_mfma_f32_16x16x32_bf16 v[0:3], v[186:189], v[218:221], v[0:3]
	s_setprio 0
	s_barrier
	s_add_u32 s18, s18, 0x100
	s_addc_u32 s19, s19, 0
	s_add_u32 s52, s52, 0x100
	s_addc_u32 s53, s53, 0
	s_cmp_ge_u32 s54, s50
	s_mov_b64 s[98:99], s[20:21]
	s_mov_b32 s20, s54
	s_cbranch_scc0 .LBB0_1827
	s_and_b64 vcc, exec, s[12:13]
	s_cbranch_vccz .LBB0_1830
	s_barrier

; __global__ void __launch_bounds__(512, 2) hymba_megakernel(Params p) {
	.amdhsa_kernel _Z16hymba_megakernel6Params
		.amdhsa_group_segment_fixed_size 0
		.amdhsa_private_segment_fixed_size 0
		.amdhsa_kernarg_size 472
		.amdhsa_user_sgpr_count 2
		.amdhsa_user_sgpr_dispatch_ptr 0
		.amdhsa_user_sgpr_queue_ptr 0
		.amdhsa_user_sgpr_kernarg_segment_ptr 1
		.amdhsa_user_sgpr_dispatch_id 0
		.amdhsa_user_sgpr_kernarg_preload_length 0
		.amdhsa_user_sgpr_kernarg_preload_offset 0
		.amdhsa_user_sgpr_private_segment_size 0
		.amdhsa_uses_dynamic_stack 0
		.amdhsa_enable_private_segment 0
		.amdhsa_system_sgpr_workgroup_id_x 1
		.amdhsa_system_sgpr_workgroup_id_y 0
		.amdhsa_system_sgpr_workgroup_id_z 0
		.amdhsa_system_sgpr_workgroup_info 0
		.amdhsa_system_vgpr_workitem_id 2
		.amdhsa_next_free_vgpr 256
		.amdhsa_next_free_sgpr 102
		.amdhsa_accum_offset 256
		.amdhsa_reserve_vcc 1
		.amdhsa_float_round_mode_32 0
		.amdhsa_float_round_mode_16_64 0
		.amdhsa_float_denorm_mode_32 3
		.amdhsa_float_denorm_mode_16_64 3
		.amdhsa_dx10_clamp 1
		.amdhsa_ieee_mode 1
		.amdhsa_fp16_overflow 0
		.amdhsa_tg_split 0
		.amdhsa_exception_fp_ieee_invalid_op 0
		.amdhsa_exception_fp_denorm_src 0
		.amdhsa_exception_fp_ieee_div_zero 0
		.amdhsa_exception_fp_ieee_overflow 0
		.amdhsa_exception_fp_ieee_underflow 0
		.amdhsa_exception_fp_ieee_inexact 0
		.amdhsa_exception_int_div_zero 0
	.end_amdhsa_kernel

; __global__ void __launch_bounds__(512, 2) hymba_megakernel(Params p) {
amdhsa.kernels:
  - .agpr_count:     0
    .args:
      - .offset:         0
        .size:           216
        .value_kind:     by_value
      - .offset:         216
        .size:           4
        .value_kind:     hidden_block_count_x
      - .offset:         220
        .size:           4
        .value_kind:     hidden_block_count_y
      - .offset:         224
        .size:           4
        .value_kind:     hidden_block_count_z
      - .offset:         228
        .size:           2
        .value_kind:     hidden_group_size_x
      - .offset:         230
        .size:           2
        .value_kind:     hidden_group_size_y
      - .offset:         232
        .size:           2
        .value_kind:     hidden_group_size_z
      - .offset:         234
        .size:           2
        .value_kind:     hidden_remainder_x
      - .offset:         236
        .size:           2
        .value_kind:     hidden_remainder_y
      - .offset:         238
        .size:           2
        .value_kind:     hidden_remainder_z
      - .offset:         256
        .size:           8
        .value_kind:     hidden_global_offset_x
      - .offset:         264
        .size:           8
        .value_kind:     hidden_global_offset_y
      - .offset:         272
        .size:           8
        .value_kind:     hidden_global_offset_z
      - .offset:         280
        .size:           2
        .value_kind:     hidden_grid_dims
      - .offset:         304
        .size:           8
        .value_kind:     hidden_multigrid_sync_arg
      - .offset:         336
        .size:           4
        .value_kind:     hidden_dynamic_lds_size
    .group_segment_fixed_size: 0
    .kernarg_segment_align: 8
    .kernarg_segment_size: 472
    .language:       OpenCL C
    .language_version:
      - 2
      - 0
    .max_flat_workgroup_size: 512
    .name:           _Z16hymba_megakernel6Params
    .private_segment_fixed_size: 0
    .sgpr_count:     108
    .sgpr_spill_count: 161
    .symbol:         _Z16hymba_megakernel6Params.kd
    .uniform_work_group_size: 1
    .uses_dynamic_stack: false
    .vgpr_count:     256
    .vgpr_spill_count: 0
    .wavefront_size: 64
